# rowstat partials in a locality-friendly layout [row-tile][plane][256 rows] (a unit's partials land in one 128 KB block instead of 128 planes 128 KB apart)
# speedup vs baseline: 1.0026x; 1.0026x over previous
; #define PG8_STAGE(bufoff, gbase, voff) do { _Pragma("unroll") for (int _i = 0; _i < 2; ++_i) \
;         __builtin_amdgcn_global_load_lds((const unsigned*)((const char*)(gbase) + (voff)[_i]), (LAS unsigned*)(lds + (bufoff) + ldsw + _i * 8192), 16, 0, 0); } while (0)
; #define PG8_LDA(dst, b, h) do { _Pragma("unroll") for (int m = 0; m < 4; ++m) _Pragma("unroll") for (int k = 0; k < 2; ++k) dst[m][k] = *(const LAS bf16x8*)(lds + PG8_SA(b, h) + aoff + m * 2048 + k * 1024); } while (0)
; #define PG8_LDB(dst, b, h) do { _Pragma("unroll") for (int n = 0; n < 2; ++n) _Pragma("unroll") for (int k = 0; k < 2; ++k) dst[n][k] = *(const LAS bf16x8*)(lds + PG8_SB(b, h) + boff + n * 2048 + k * 1024); } while (0)
; #define PG8_MMA(ai, bj, At, Bt) do { __builtin_amdgcn_s_setprio(1); _Pragma("unroll") for (int m = 0; m < 4; ++m) _Pragma("unroll") for (int n = 0; n < 2; ++n) _Pragma("unroll") for (int k = 0; k < 2; ++k) \
;         acc[ai][bj][m][n] = __builtin_amdgcn_mfma_f32_16x16x32_bf16(Bt[n][k], At[m][k], acc[ai][bj][m][n], 0, 0, 0); __builtin_amdgcn_s_setprio(0); } while (0)
; #define PG8_WAIT_V(n) asm volatile("s_waitcnt vmcnt(" #n ")" ::: "memory")
; #define PG8_BAR __builtin_amdgcn_s_barrier()
; template <class Epi, class Sched>
; __device__ __forceinline__ void gemm_phase(LAS unsigned char* lds, const Gemm g, const Sched& S, const Epi& E) {
;     ...
;         for (int t = 0; t < nt; t += 2) {
;             const bool last = (t == nt - 2);
;             const char* a1 = cA + (size_t)(t + 1) * kstep;
;             const char* a2 = last ? nA : cA + (size_t)(t + 2) * kstep; const char* b2 = last ? nB : cB + (size_t)(t + 2) * kstep;
;             const char* a3 = a2 + kstep; const char* b3 = b2 + kstep;
;             if (last && has_next) S.a_ready(nxt);
;             PG8_LDB(B0, 0, 0); PG8_SCHED; PG8_LDA(At, 0, 0); PG8_STAGE(PG8_SA(1, 1), a1 + hstepA, voffA);
;             PG8_WAIT_L(8); PG8_BAR; PG8_WAIT_L(0); PG8_MMA(0, 0, At, B0); PG8_BAR; PG8_SCHED;
;             PG8_LDB(B1, 0, 1); PG8_STAGE(PG8_SB(0, 0), b2, voffB);
;             PG8_BAR; PG8_WAIT_L(0); PG8_MMA(0, 1, At, B1); PG8_BAR;
;             PG8_LDA(At, 0, 1); PG8_STAGE(PG8_SA(0, 0), a2, voffA);
;             PG8_BAR; PG8_WAIT_L(0); PG8_MMA(1, 0, At, B0); PG8_BAR; PG8_SCHED;
;             PG8_STAGE(PG8_SB(0, 1), b2 + hstepB, voffB);
;             PG8_WAIT_V(6); PG8_BAR; PG8_MMA(1, 1, At, B1); PG8_BAR;
.LBB0_966:
	s_setprio 0
	s_add_u32 s20, s6, 0xfff80080
	s_addc_u32 s21, s7, -1
	s_add_i32 s52, 0, 0x10000
	v_add_u32_e32 v144, s52, v1
	ds_read_b128 v[132:135], v144
	ds_read_b128 v[136:139], v144 offset:1024
	ds_read_b128 v[140:143], v144 offset:2048
	ds_read_b128 v[144:147], v144 offset:3072
	s_cmp_eq_u32 s51, 28
	s_cselect_b32 s25, s15, s21
	s_cselect_b32 s24, s47, s20
	s_cselect_b32 s21, s1, s50
	s_cselect_b32 s20, s48, s49
	ds_read_b128 v[148:151], v224
	ds_read_b128 v[152:155], v224 offset:1024
	ds_read_b128 v[156:159], v224 offset:2048
	ds_read_b128 v[160:163], v224 offset:3072
	ds_read_b128 v[164:167], v224 offset:4096
	ds_read_b128 v[168:171], v224 offset:5120
	ds_read_b128 v[172:175], v224 offset:6144
	ds_read_b128 v[176:179], v224 offset:7168
	s_add_i32 s54, 0, 0x14000
	v_add_u32_e32 v202, s54, v1
	ds_read_b128 v[180:183], v202
	ds_read_b128 v[184:187], v202 offset:1024
	ds_read_b128 v[188:191], v202 offset:2048
	ds_read_b128 v[202:205], v202 offset:3072
	s_add_i32 m0, s31, 0xc000
	s_nop 0
	global_load_lds_dwordx4 v198, s[6:7]
	s_add_i32 m0, s31, 0xe000
	s_nop 0
	global_load_lds_dwordx4 v200, s[6:7]
	s_waitcnt lgkmcnt(0)
	s_setprio 1
	s_barrier
	v_mfma_f32_16x16x32_bf16 v[128:131], v[132:135], v[148:151], v[128:131]
	v_mfma_f32_16x16x32_bf16 v[124:127], v[140:143], v[148:151], v[124:127]
	v_mfma_f32_16x16x32_bf16 v[112:115], v[132:135], v[156:159], v[112:115]
	v_mfma_f32_16x16x32_bf16 v[108:111], v[140:143], v[156:159], v[108:111]
	v_mfma_f32_16x16x32_bf16 v[100:103], v[132:135], v[164:167], v[100:103]
	v_mfma_f32_16x16x32_bf16 v[92:95], v[140:143], v[164:167], v[92:95]
	v_mfma_f32_16x16x32_bf16 v[84:87], v[132:135], v[172:175], v[84:87]
	v_mfma_f32_16x16x32_bf16 v[76:79], v[140:143], v[172:175], v[76:79]
	v_mfma_f32_16x16x32_bf16 v[128:131], v[136:139], v[152:155], v[128:131]
	v_mfma_f32_16x16x32_bf16 v[124:127], v[144:147], v[152:155], v[124:127]
	v_mfma_f32_16x16x32_bf16 v[112:115], v[136:139], v[160:163], v[112:115]
	v_mfma_f32_16x16x32_bf16 v[108:111], v[144:147], v[160:163], v[108:111]
	v_mfma_f32_16x16x32_bf16 v[100:103], v[136:139], v[168:171], v[100:103]
	v_mfma_f32_16x16x32_bf16 v[92:95], v[144:147], v[168:171], v[92:95]
	v_mfma_f32_16x16x32_bf16 v[84:87], v[136:139], v[176:179], v[84:87]
	v_mfma_f32_16x16x32_bf16 v[76:79], v[144:147], v[176:179], v[76:79]
	v_mfma_f32_16x16x32_bf16 v[120:123], v[180:183], v[148:151], v[120:123]
	v_mfma_f32_16x16x32_bf16 v[116:119], v[188:191], v[148:151], v[116:119]
	v_mfma_f32_16x16x32_bf16 v[104:107], v[180:183], v[156:159], v[104:107]
	v_mfma_f32_16x16x32_bf16 v[96:99], v[188:191], v[156:159], v[96:99]
	v_mfma_f32_16x16x32_bf16 v[88:91], v[180:183], v[164:167], v[88:91]
	v_mfma_f32_16x16x32_bf16 v[80:83], v[188:191], v[164:167], v[80:83]
	v_mfma_f32_16x16x32_bf16 v[72:75], v[180:183], v[172:175], v[72:75]
	v_mfma_f32_16x16x32_bf16 v[68:71], v[188:191], v[172:175], v[68:71]
	v_mfma_f32_16x16x32_bf16 v[120:123], v[184:187], v[152:155], v[120:123]
	v_mfma_f32_16x16x32_bf16 v[116:119], v[202:205], v[152:155], v[116:119]
	v_mfma_f32_16x16x32_bf16 v[104:107], v[184:187], v[160:163], v[104:107]
	v_mfma_f32_16x16x32_bf16 v[96:99], v[202:205], v[160:163], v[96:99]
	v_mfma_f32_16x16x32_bf16 v[88:91], v[184:187], v[168:171], v[88:91]
	v_mfma_f32_16x16x32_bf16 v[80:83], v[202:205], v[168:171], v[80:83]
	v_mfma_f32_16x16x32_bf16 v[72:75], v[184:187], v[176:179], v[72:75]
	v_mfma_f32_16x16x32_bf16 v[68:71], v[202:205], v[176:179], v[68:71]
	s_barrier
	s_setprio 0
	ds_read_b128 v[148:151], v224 offset:16384
	ds_read_b128 v[152:155], v224 offset:17408
	ds_read_b128 v[156:159], v224 offset:18432
	ds_read_b128 v[160:163], v224 offset:19456
	ds_read_b128 v[164:167], v224 offset:20480
	ds_read_b128 v[168:171], v224 offset:21504
	ds_read_b128 v[172:175], v224 offset:22528
	ds_read_b128 v[176:179], v224 offset:23552
	s_add_i32 s52, s52, s30
	v_lshl_add_u64 v[206:207], s[20:21], 0, v[2:3]
	s_mov_b32 m0, s52
	s_nop 0
	global_load_lds_dwordx4 v[206:207], off
	v_lshl_add_u64 v[208:209], s[20:21], 0, v[192:193]
	s_add_i32 m0, s52, 0x2000
	s_nop 0
	global_load_lds_dwordx4 v[208:209], off
	s_mov_b32 m0, s31
	v_lshl_add_u64 v[210:211], s[24:25], 0, v[196:197]
	global_load_lds_dwordx4 v[210:211], off
	v_lshl_add_u64 v[212:213], s[24:25], 0, v[194:195]
	s_mov_b32 m0, s35
	s_nop 0
	global_load_lds_dwordx4 v[212:213], off
	s_add_u32 s52, s20, 0x80000
	s_addc_u32 s53, s21, 0
	s_add_i32 s54, s54, s30
	s_mov_b32 m0, s54
	s_nop 0
	global_load_lds_dwordx4 v2, s[52:53]
	s_add_i32 m0, s54, 0x2000
	s_nop 0
	global_load_lds_dwordx4 v192, s[52:53]
	s_waitcnt lgkmcnt(0)
	s_waitcnt vmcnt(6)
	s_setprio 1
	s_barrier
; #define PG8_STAGE(bufoff, gbase, voff) do { _Pragma("unroll") for (int _i = 0; _i < 2; ++_i) \
;         __builtin_amdgcn_global_load_lds((const unsigned*)((const char*)(gbase) + (voff)[_i]), (LAS unsigned*)(lds + (bufoff) + ldsw + _i * 8192), 16, 0, 0); } while (0)
; #define PG8_LDA(dst, b, h) do { _Pragma("unroll") for (int m = 0; m < 4; ++m) _Pragma("unroll") for (int k = 0; k < 2; ++k) dst[m][k] = *(const LAS bf16x8*)(lds + PG8_SA(b, h) + aoff + m * 2048 + k * 1024); } while (0)
; #define PG8_LDB(dst, b, h) do { _Pragma("unroll") for (int n = 0; n < 2; ++n) _Pragma("unroll") for (int k = 0; k < 2; ++k) dst[n][k] = *(const LAS bf16x8*)(lds + PG8_SB(b, h) + boff + n * 2048 + k * 1024); } while (0)
; #define PG8_MMA(ai, bj, At, Bt) do { __builtin_amdgcn_s_setprio(1); _Pragma("unroll") for (int m = 0; m < 4; ++m) _Pragma("unroll") for (int n = 0; n < 2; ++n) _Pragma("unroll") for (int k = 0; k < 2; ++k) \
;         acc[ai][bj][m][n] = __builtin_amdgcn_mfma_f32_16x16x32_bf16(Bt[n][k], At[m][k], acc[ai][bj][m][n], 0, 0, 0); __builtin_amdgcn_s_setprio(0); } while (0)
; #define PG8_WAIT_V(n) asm volatile("s_waitcnt vmcnt(" #n ")" ::: "memory")
; #define PG8_WAIT_L(n) asm volatile("s_waitcnt lgkmcnt(" #n ")" ::: "memory")
; #define PG8_BAR __builtin_amdgcn_s_barrier()
; #define PG8_SCHED __builtin_amdgcn_sched_barrier(0)
; template <class Epi, class Sched>
; __device__ __forceinline__ void gemm_phase(LAS unsigned char* lds, const Gemm g, const Sched& S, const Epi& E) {
;     ...
;             PG8_WAIT_V(6); PG8_BAR; PG8_MMA(1, 1, At, B1); PG8_BAR;
;             PG8_LDB(B0, 1, 0); PG8_SCHED; PG8_LDA(At, 1, 0); PG8_STAGE(PG8_SA(0, 1), a2 + hstepA, voffA);
;             PG8_WAIT_L(8); PG8_BAR; PG8_WAIT_L(0); PG8_MMA(0, 0, At, B0); PG8_BAR; PG8_SCHED;
;             PG8_LDB(B1, 1, 1); PG8_STAGE(PG8_SB(1, 0), b3, voffB);
;             PG8_BAR; PG8_WAIT_L(0); PG8_MMA(0, 1, At, B1); PG8_BAR;
;             PG8_LDA(At, 1, 1); PG8_STAGE(PG8_SA(1, 0), a3, voffA);
	v_mfma_f32_16x16x32_bf16 v[64:67], v[132:135], v[148:151], v[64:67]
	v_mfma_f32_16x16x32_bf16 v[60:63], v[140:143], v[148:151], v[60:63]
	v_mfma_f32_16x16x32_bf16 v[52:55], v[132:135], v[156:159], v[52:55]
	v_mfma_f32_16x16x32_bf16 v[44:47], v[140:143], v[156:159], v[44:47]
	v_mfma_f32_16x16x32_bf16 v[36:39], v[132:135], v[164:167], v[36:39]
	v_mfma_f32_16x16x32_bf16 v[28:31], v[140:143], v[164:167], v[28:31]
	v_mfma_f32_16x16x32_bf16 v[20:23], v[132:135], v[172:175], v[20:23]
	v_mfma_f32_16x16x32_bf16 v[12:15], v[140:143], v[172:175], v[12:15]
	v_mfma_f32_16x16x32_bf16 v[64:67], v[136:139], v[152:155], v[64:67]
	v_mfma_f32_16x16x32_bf16 v[60:63], v[144:147], v[152:155], v[60:63]
	v_mfma_f32_16x16x32_bf16 v[52:55], v[136:139], v[160:163], v[52:55]
	v_mfma_f32_16x16x32_bf16 v[44:47], v[144:147], v[160:163], v[44:47]
	v_mfma_f32_16x16x32_bf16 v[36:39], v[136:139], v[168:171], v[36:39]
	v_mfma_f32_16x16x32_bf16 v[28:31], v[144:147], v[168:171], v[28:31]
	v_mfma_f32_16x16x32_bf16 v[20:23], v[136:139], v[176:179], v[20:23]
	v_mfma_f32_16x16x32_bf16 v[12:15], v[144:147], v[176:179], v[12:15]
	v_mfma_f32_16x16x32_bf16 v[56:59], v[180:183], v[148:151], v[56:59]
	v_mfma_f32_16x16x32_bf16 v[48:51], v[188:191], v[148:151], v[48:51]
	v_mfma_f32_16x16x32_bf16 v[40:43], v[180:183], v[156:159], v[40:43]
	v_mfma_f32_16x16x32_bf16 v[32:35], v[188:191], v[156:159], v[32:35]
	v_mfma_f32_16x16x32_bf16 v[24:27], v[180:183], v[164:167], v[24:27]
	v_mfma_f32_16x16x32_bf16 v[16:19], v[188:191], v[164:167], v[16:19]
	v_mfma_f32_16x16x32_bf16 v[8:11], v[180:183], v[172:175], v[8:11]
	v_mfma_f32_16x16x32_bf16 v[4:7], v[188:191], v[172:175], v[4:7]
	v_mfma_f32_16x16x32_bf16 v[56:59], v[184:187], v[152:155], v[56:59]
	v_mfma_f32_16x16x32_bf16 v[48:51], v[202:205], v[152:155], v[48:51]
	v_mfma_f32_16x16x32_bf16 v[40:43], v[184:187], v[160:163], v[40:43]
	v_mfma_f32_16x16x32_bf16 v[32:35], v[202:205], v[160:163], v[32:35]
	v_mfma_f32_16x16x32_bf16 v[24:27], v[184:187], v[168:171], v[24:27]
	v_mfma_f32_16x16x32_bf16 v[16:19], v[202:205], v[168:171], v[16:19]
	v_mfma_f32_16x16x32_bf16 v[8:11], v[184:187], v[176:179], v[8:11]
	v_mfma_f32_16x16x32_bf16 v[4:7], v[202:205], v[176:179], v[4:7]
	s_barrier
	s_setprio 0
	s_add_i32 s52, 0, 0x18000
	v_add_u32_e32 v144, s52, v1
	ds_read_b128 v[132:135], v144
	ds_read_b128 v[136:139], v144 offset:1024
	ds_read_b128 v[140:143], v144 offset:2048
	ds_read_b128 v[144:147], v144 offset:3072
	s_add_u32 s24, s24, 0x80000
	s_addc_u32 s25, s25, 0
	ds_read_b128 v[148:151], v224 offset:32768
	ds_read_b128 v[152:155], v224 offset:33792
	ds_read_b128 v[156:159], v224 offset:34816
	ds_read_b128 v[160:163], v224 offset:35840
	ds_read_b128 v[164:167], v224 offset:36864
	ds_read_b128 v[168:171], v224 offset:37888
	ds_read_b128 v[172:175], v224 offset:38912
	ds_read_b128 v[176:179], v224 offset:39936
	s_mov_b32 m0, s36
	s_nop 0
	global_load_lds_dwordx4 v196, s[24:25]
	s_mov_b32 m0, s37
	s_nop 0
	global_load_lds_dwordx4 v194, s[24:25]
	s_add_i32 s24, 0, 0x1c000
	v_add_u32_e32 v202, s24, v1
	ds_read_b128 v[180:183], v202
	ds_read_b128 v[184:187], v202 offset:1024
	ds_read_b128 v[188:191], v202 offset:2048
	ds_read_b128 v[202:205], v202 offset:3072
	s_waitcnt lgkmcnt(0)
	s_setprio 1
	s_barrier
	v_mfma_f32_16x16x32_bf16 v[128:131], v[132:135], v[148:151], v[128:131]
	v_mfma_f32_16x16x32_bf16 v[124:127], v[140:143], v[148:151], v[124:127]
	v_mfma_f32_16x16x32_bf16 v[112:115], v[132:135], v[156:159], v[112:115]
	v_mfma_f32_16x16x32_bf16 v[108:111], v[140:143], v[156:159], v[108:111]
	v_mfma_f32_16x16x32_bf16 v[100:103], v[132:135], v[164:167], v[100:103]
	v_mfma_f32_16x16x32_bf16 v[92:95], v[140:143], v[164:167], v[92:95]
	v_mfma_f32_16x16x32_bf16 v[84:87], v[132:135], v[172:175], v[84:87]
	v_mfma_f32_16x16x32_bf16 v[76:79], v[140:143], v[172:175], v[76:79]
	v_mfma_f32_16x16x32_bf16 v[128:131], v[136:139], v[152:155], v[128:131]
	v_mfma_f32_16x16x32_bf16 v[124:127], v[144:147], v[152:155], v[124:127]
	v_mfma_f32_16x16x32_bf16 v[112:115], v[136:139], v[160:163], v[112:115]
	v_mfma_f32_16x16x32_bf16 v[108:111], v[144:147], v[160:163], v[108:111]
	v_mfma_f32_16x16x32_bf16 v[100:103], v[136:139], v[168:171], v[100:103]
	v_mfma_f32_16x16x32_bf16 v[92:95], v[144:147], v[168:171], v[92:95]
	v_mfma_f32_16x16x32_bf16 v[84:87], v[136:139], v[176:179], v[84:87]
	v_mfma_f32_16x16x32_bf16 v[76:79], v[144:147], v[176:179], v[76:79]
	v_mfma_f32_16x16x32_bf16 v[120:123], v[180:183], v[148:151], v[120:123]
	v_mfma_f32_16x16x32_bf16 v[116:119], v[188:191], v[148:151], v[116:119]
	v_mfma_f32_16x16x32_bf16 v[104:107], v[180:183], v[156:159], v[104:107]
	v_mfma_f32_16x16x32_bf16 v[96:99], v[188:191], v[156:159], v[96:99]
	v_mfma_f32_16x16x32_bf16 v[88:91], v[180:183], v[164:167], v[88:91]
	v_mfma_f32_16x16x32_bf16 v[80:83], v[188:191], v[164:167], v[80:83]
	v_mfma_f32_16x16x32_bf16 v[72:75], v[180:183], v[172:175], v[72:75]
	v_mfma_f32_16x16x32_bf16 v[68:71], v[188:191], v[172:175], v[68:71]
	v_mfma_f32_16x16x32_bf16 v[120:123], v[184:187], v[152:155], v[120:123]
	v_mfma_f32_16x16x32_bf16 v[116:119], v[202:205], v[152:155], v[116:119]
	v_mfma_f32_16x16x32_bf16 v[104:107], v[184:187], v[160:163], v[104:107]
	v_mfma_f32_16x16x32_bf16 v[96:99], v[202:205], v[160:163], v[96:99]
	v_mfma_f32_16x16x32_bf16 v[88:91], v[184:187], v[168:171], v[88:91]
	v_mfma_f32_16x16x32_bf16 v[80:83], v[202:205], v[168:171], v[80:83]
	v_mfma_f32_16x16x32_bf16 v[72:75], v[184:187], v[176:179], v[72:75]
	v_mfma_f32_16x16x32_bf16 v[68:71], v[202:205], v[176:179], v[68:71]
	s_barrier
; #define PG8_STAGE(bufoff, gbase, voff) do { _Pragma("unroll") for (int _i = 0; _i < 2; ++_i) \
;         __builtin_amdgcn_global_load_lds((const unsigned*)((const char*)(gbase) + (voff)[_i]), (LAS unsigned*)(lds + (bufoff) + ldsw + _i * 8192), 16, 0, 0); } while (0)
; #define PG8_LDA(dst, b, h) do { _Pragma("unroll") for (int m = 0; m < 4; ++m) _Pragma("unroll") for (int k = 0; k < 2; ++k) dst[m][k] = *(const LAS bf16x8*)(lds + PG8_SA(b, h) + aoff + m * 2048 + k * 1024); } while (0)
; #define PG8_MMA(ai, bj, At, Bt) do { __builtin_amdgcn_s_setprio(1); _Pragma("unroll") for (int m = 0; m < 4; ++m) _Pragma("unroll") for (int n = 0; n < 2; ++n) _Pragma("unroll") for (int k = 0; k < 2; ++k) \
;         acc[ai][bj][m][n] = __builtin_amdgcn_mfma_f32_16x16x32_bf16(Bt[n][k], At[m][k], acc[ai][bj][m][n], 0, 0, 0); __builtin_amdgcn_s_setprio(0); } while (0)
; #define PG8_WAIT_V(n) asm volatile("s_waitcnt vmcnt(" #n ")" ::: "memory")
; #define PG8_WAIT_L(n) asm volatile("s_waitcnt lgkmcnt(" #n ")" ::: "memory")
; #define PG8_BAR __builtin_amdgcn_s_barrier()
; #define PG8_SCHED __builtin_amdgcn_sched_barrier(0)
;     __device__ __forceinline__ void operator()(const f32x4 (&acc)[2][2][4][2], const Unit& u, int wr, int wc, int, int) const {
;     ...
; #pragma unroll
;         for (int ai = 0; ai < 2; ++ai)
; #pragma unroll
;             for (int m = 0; m < 4; ++m)
; #pragma unroll
;                 for (int bj = 0; bj < 2; ++bj) cin[ai][m][bj] = *(const u32x4*)(C + (size_t)(row0 + ai * HALF + m * 16) * ldc + col0 + bj * HALF);
; template <class Epi, class Sched>
; __device__ __forceinline__ void gemm_phase(LAS unsigned char* lds, const Gemm g, const Sched& S, const Epi& E) {
;     ...
;             PG8_LDA(At, 1, 1); PG8_STAGE(PG8_SA(1, 0), a3, voffA);
;             PG8_BAR; PG8_WAIT_L(0); PG8_MMA(1, 0, At, B0); PG8_BAR; PG8_SCHED;
;             PG8_STAGE(PG8_SB(1, 1), b3 + hstepB, voffB);
;             PG8_WAIT_V(6); PG8_BAR; PG8_MMA(1, 1, At, B1); PG8_BAR;
;         }
;         E(acc, cur, wr, wc, ui, fq);
;         S.done(cur);
;         if (!has_next) break;
	s_setprio 0
	ds_read_b128 v[148:151], v224 offset:49152
	ds_read_b128 v[152:155], v224 offset:50176
	ds_read_b128 v[156:159], v224 offset:51200
	ds_read_b128 v[160:163], v224 offset:52224
	ds_read_b128 v[164:167], v224 offset:53248
	ds_read_b128 v[168:171], v224 offset:54272
	ds_read_b128 v[172:175], v224 offset:55296
	ds_read_b128 v[176:179], v224 offset:56320
	s_add_i32 s25, s52, s30
	v_lshl_add_u64 v[206:207], v[206:207], 0, s[8:9]
	s_mov_b32 m0, s25
	s_nop 0
	global_load_lds_dwordx4 v[206:207], off
	v_lshl_add_u64 v[206:207], v[208:209], 0, s[8:9]
	s_add_i32 m0, s25, 0x2000
	s_nop 0
	global_load_lds_dwordx4 v[206:207], off
	s_mov_b32 m0, s40
	v_lshl_add_u64 v[206:207], v[210:211], 0, s[8:9]
	global_load_lds_dwordx4 v[206:207], off
	v_lshl_add_u64 v[206:207], v[212:213], 0, s[8:9]
	s_mov_b32 m0, s41
	s_nop 0
	global_load_lds_dwordx4 v[206:207], off
	s_add_u32 s20, s20, 0x80080
	s_addc_u32 s21, s21, 0
	s_add_i32 s24, s24, s30
	s_mov_b32 m0, s24
	s_nop 0
	global_load_lds_dwordx4 v2, s[20:21]
	s_add_i32 m0, s24, 0x2000
	s_nop 0
	global_load_lds_dwordx4 v192, s[20:21]
	s_add_i32 s51, s51, 2
	s_add_u32 s6, s6, 0x100
	s_addc_u32 s7, s7, 0
	s_add_u32 s49, s49, 0x100
	s_addc_u32 s50, s50, 0
	s_cmp_gt_u32 s51, 29
	s_waitcnt lgkmcnt(0)
	s_waitcnt vmcnt(6)
	s_setprio 1
	s_barrier
	v_mfma_f32_16x16x32_bf16 v[64:67], v[132:135], v[148:151], v[64:67]
	v_mfma_f32_16x16x32_bf16 v[60:63], v[140:143], v[148:151], v[60:63]
	v_mfma_f32_16x16x32_bf16 v[52:55], v[132:135], v[156:159], v[52:55]
	v_mfma_f32_16x16x32_bf16 v[44:47], v[140:143], v[156:159], v[44:47]
	v_mfma_f32_16x16x32_bf16 v[36:39], v[132:135], v[164:167], v[36:39]
	v_mfma_f32_16x16x32_bf16 v[28:31], v[140:143], v[164:167], v[28:31]
	v_mfma_f32_16x16x32_bf16 v[20:23], v[132:135], v[172:175], v[20:23]
	v_mfma_f32_16x16x32_bf16 v[12:15], v[140:143], v[172:175], v[12:15]
	v_mfma_f32_16x16x32_bf16 v[64:67], v[136:139], v[152:155], v[64:67]
	v_mfma_f32_16x16x32_bf16 v[60:63], v[144:147], v[152:155], v[60:63]
	v_mfma_f32_16x16x32_bf16 v[52:55], v[136:139], v[160:163], v[52:55]
	v_mfma_f32_16x16x32_bf16 v[44:47], v[144:147], v[160:163], v[44:47]
	v_mfma_f32_16x16x32_bf16 v[36:39], v[136:139], v[168:171], v[36:39]
	v_mfma_f32_16x16x32_bf16 v[28:31], v[144:147], v[168:171], v[28:31]
	v_mfma_f32_16x16x32_bf16 v[20:23], v[136:139], v[176:179], v[20:23]
	v_mfma_f32_16x16x32_bf16 v[12:15], v[144:147], v[176:179], v[12:15]
	v_mfma_f32_16x16x32_bf16 v[56:59], v[180:183], v[148:151], v[56:59]
	v_mfma_f32_16x16x32_bf16 v[48:51], v[188:191], v[148:151], v[48:51]
	v_mfma_f32_16x16x32_bf16 v[40:43], v[180:183], v[156:159], v[40:43]
	v_mfma_f32_16x16x32_bf16 v[32:35], v[188:191], v[156:159], v[32:35]
	v_mfma_f32_16x16x32_bf16 v[24:27], v[180:183], v[164:167], v[24:27]
	v_mfma_f32_16x16x32_bf16 v[16:19], v[188:191], v[164:167], v[16:19]
	v_mfma_f32_16x16x32_bf16 v[8:11], v[180:183], v[172:175], v[8:11]
	v_mfma_f32_16x16x32_bf16 v[4:7], v[188:191], v[172:175], v[4:7]
	v_mfma_f32_16x16x32_bf16 v[56:59], v[184:187], v[152:155], v[56:59]
	v_mfma_f32_16x16x32_bf16 v[48:51], v[202:205], v[152:155], v[48:51]
	v_mfma_f32_16x16x32_bf16 v[40:43], v[184:187], v[160:163], v[40:43]
	v_mfma_f32_16x16x32_bf16 v[32:35], v[202:205], v[160:163], v[32:35]
	v_mfma_f32_16x16x32_bf16 v[24:27], v[184:187], v[168:171], v[24:27]
	v_mfma_f32_16x16x32_bf16 v[16:19], v[202:205], v[168:171], v[16:19]
	v_mfma_f32_16x16x32_bf16 v[8:11], v[184:187], v[176:179], v[8:11]
	v_mfma_f32_16x16x32_bf16 v[4:7], v[202:205], v[176:179], v[4:7]
	s_barrier
	s_cbranch_scc0 .LBB0_966
	s_setprio 0
	v_mov_b32_e32 v133, v0
	s_lshl_b32 s1, s46, 8
	s_add_i32 s1, s1, s38
	v_and_or_b32 v132, v133, 15, s1
	s_lshl_b32 s1, s45, 8
	v_lshrrev_b32_e32 v133, 1, v133
	v_and_or_b32 v133, v133, 24, s1
	v_or_b32_e32 v134, s39, v133
	v_ashrrev_i32_e32 v135, 31, v134
	v_lshlrev_b64 v[202:203], 1, v[134:135]
	v_ashrrev_i32_e32 v133, 31, v132
	v_lshl_add_u64 v[134:135], s[88:89], 0, v[202:203]
	v_lshlrev_b64 v[226:227], 12, v[132:133]
	v_lshl_add_u64 v[136:137], v[134:135], 0, v[226:227]
	global_load_dwordx4 v[216:219], v[136:137], off
	global_load_dwordx4 v[188:191], v[136:137], off offset:256
	v_or_b32_e32 v136, 16, v132
	v_ashrrev_i32_e32 v137, 31, v136
	v_lshlrev_b64 v[222:223], 12, v[136:137]
	v_lshl_add_u64 v[136:137], v[134:135], 0, v[222:223]
	global_load_dwordx4 v[184:187], v[136:137], off
	global_load_dwordx4 v[180:183], v[136:137], off offset:256
	v_or_b32_e32 v136, 32, v132
	v_ashrrev_i32_e32 v137, 31, v136
	v_lshlrev_b64 v[220:221], 12, v[136:137]
	v_lshl_add_u64 v[136:137], v[134:135], 0, v[220:221]
	global_load_dwordx4 v[176:179], v[136:137], off
	global_load_dwordx4 v[168:171], v[136:137], off offset:256
	v_or_b32_e32 v132, 48, v132
	v_ashrrev_i32_e32 v133, 31, v132
	v_lshlrev_b64 v[212:213], 12, v[132:133]
	v_lshl_add_u64 v[132:133], v[134:135], 0, v[212:213]
	global_load_dwordx4 v[172:175], v[132:133], off
	global_load_dwordx4 v[164:167], v[132:133], off offset:256
	s_mov_b64 s[6:7], 0x80000
	v_lshl_add_u64 v[210:211], v[226:227], 0, s[6:7]
	v_lshl_add_u64 v[132:133], v[134:135], 0, v[210:211]
	global_load_dwordx4 v[160:163], v[132:133], off
	global_load_dwordx4 v[156:159], v[132:133], off offset:256
	s_mov_b64 s[6:7], 0x90000
	v_lshl_add_u64 v[208:209], v[226:227], 0, s[6:7]
	v_lshl_add_u64 v[132:133], v[134:135], 0, v[208:209]
	global_load_dwordx4 v[152:155], v[132:133], off
	global_load_dwordx4 v[148:151], v[132:133], off offset:256
	s_mov_b64 s[6:7], 0xa0000
	v_lshl_add_u64 v[206:207], v[226:227], 0, s[6:7]
	v_lshl_add_u64 v[132:133], v[134:135], 0, v[206:207]
	global_load_dwordx4 v[144:147], v[132:133], off
	global_load_dwordx4 v[140:143], v[132:133], off offset:256
	s_mov_b64 s[6:7], 0xb0000
	v_lshl_add_u64 v[204:205], v[226:227], 0, s[6:7]
	v_lshl_add_u64 v[132:133], v[134:135], 0, v[204:205]
	global_load_dwordx4 v[136:139], v[132:133], off
	s_nop 0
	global_load_dwordx4 v[132:135], v[132:133], off offset:256
	s_and_b64 vcc, exec, s[42:43]
	s_mov_b32 s45, s0
	s_mov_b32 s46, s14
	s_mov_b64 s[20:21], s[18:19]
	s_mov_b64 s[6:7], s[4:5]
	s_waitcnt vmcnt(15)
; __device__ __forceinline__ unsigned cvt_pk_bf16(float lo, float hi) { const f32x2 v = {lo, hi}; const bf16v2_ r = __builtin_convertvector(v, bf16v2_); return __builtin_bit_cast(unsigned, r); }
; __device__ __forceinline__ float bflo(unsigned w) { return __uint_as_float(w << 16); }
; __device__ __forceinline__ float bfhi(unsigned w) { return __uint_as_float(w & 0xffff0000u); }
;     __device__ __forceinline__ void operator()(const f32x4 (&acc)[2][2][4][2], const Unit& u, int wr, int wc, int, int) const {
;     ...
; #pragma unroll
;         for (int ai = 0; ai < 2; ++ai)
; #pragma unroll
;             for (int m = 0; m < 4; ++m)
; #pragma unroll
;                 for (int bj = 0; bj < 2; ++bj) { const u32x4 c = cin[ai][m][bj]; const f32x4 v0 = acc[ai][bj][m][0], v1 = acc[ai][bj][m][1];
;                     u32x4 w; w.x = cvt_pk_bf16(bflo(c.x) + v0[0], bfhi(c.x) + v0[1]); w.y = cvt_pk_bf16(bflo(c.y) + v0[2], bfhi(c.y) + v0[3]);
;                     w.z = cvt_pk_bf16(bflo(c.z) + v1[0], bfhi(c.z) + v1[1]); w.w = cvt_pk_bf16(bflo(c.w) + v1[2], bfhi(c.w) + v1[3]);
;                     *(u32x4*)(C + (size_t)(row0 + ai * HALF + m * 16) * ldc + col0 + bj * HALF) = w; }
	v_lshlrev_b32_e32 v228, 16, v216
	v_and_b32_e32 v229, 0xffff0000, v216
	v_lshlrev_b32_e32 v216, 16, v217
	v_and_b32_e32 v217, 0xffff0000, v217
	v_pk_add_f32 v[128:129], v[128:129], v[228:229]
	v_pk_add_f32 v[130:131], v[130:131], v[216:217]
	v_cvt_pk_bf16_f32 v128, v128, v129
	v_cvt_pk_bf16_f32 v129, v130, v131
	v_lshlrev_b32_e32 v130, 16, v218
	v_and_b32_e32 v131, 0xffff0000, v218
	v_pk_add_f32 v[124:125], v[124:125], v[130:131]
	s_nop 0
	v_cvt_pk_bf16_f32 v130, v124, v125
	v_lshlrev_b32_e32 v124, 16, v219
	v_and_b32_e32 v125, 0xffff0000, v219
	v_pk_add_f32 v[124:125], v[126:127], v[124:125]
	s_waitcnt vmcnt(14)
	v_lshlrev_b32_e32 v126, 16, v188
	v_and_b32_e32 v127, 0xffff0000, v188
	v_pk_add_f32 v[120:121], v[120:121], v[126:127]
	v_lshlrev_b32_e32 v126, 16, v189
	v_and_b32_e32 v127, 0xffff0000, v189
	v_pk_add_f32 v[122:123], v[122:123], v[126:127]
	v_cvt_pk_bf16_f32 v120, v120, v121
	v_cvt_pk_bf16_f32 v121, v122, v123
	v_lshlrev_b32_e32 v122, 16, v190
	v_and_b32_e32 v123, 0xffff0000, v190
	v_pk_add_f32 v[116:117], v[116:117], v[122:123]
	v_cvt_pk_bf16_f32 v131, v124, v125
	v_cvt_pk_bf16_f32 v122, v116, v117
	v_lshlrev_b32_e32 v116, 16, v191
	v_and_b32_e32 v117, 0xffff0000, v191
	v_pk_add_f32 v[116:117], v[118:119], v[116:117]
	v_lshl_add_u64 v[124:125], s[88:89], 0, v[226:227]
	v_cvt_pk_bf16_f32 v123, v116, v117
	s_waitcnt vmcnt(13)
	v_lshlrev_b32_e32 v116, 16, v184
	v_and_b32_e32 v117, 0xffff0000, v184
	v_pk_add_f32 v[112:113], v[112:113], v[116:117]
	v_lshlrev_b32_e32 v116, 16, v185
	v_and_b32_e32 v117, 0xffff0000, v185
	v_pk_add_f32 v[114:115], v[114:115], v[116:117]
	v_cvt_pk_bf16_f32 v112, v112, v113
	v_cvt_pk_bf16_f32 v113, v114, v115
	v_lshlrev_b32_e32 v114, 16, v186
	v_and_b32_e32 v115, 0xffff0000, v186
	v_pk_add_f32 v[108:109], v[108:109], v[114:115]
	v_lshl_add_u64 v[124:125], v[124:125], 0, v[202:203]
	v_cvt_pk_bf16_f32 v114, v108, v109
	v_lshlrev_b32_e32 v108, 16, v187
	v_and_b32_e32 v109, 0xffff0000, v187
	v_pk_add_f32 v[108:109], v[110:111], v[108:109]
	s_waitcnt vmcnt(12)
	v_lshlrev_b32_e32 v110, 16, v180
	v_and_b32_e32 v111, 0xffff0000, v180
	v_pk_add_f32 v[104:105], v[104:105], v[110:111]
	v_lshlrev_b32_e32 v110, 16, v181
	v_and_b32_e32 v111, 0xffff0000, v181
	v_pk_add_f32 v[106:107], v[106:107], v[110:111]
	v_cvt_pk_bf16_f32 v104, v104, v105
	v_cvt_pk_bf16_f32 v105, v106, v107
	v_lshlrev_b32_e32 v106, 16, v182
	v_and_b32_e32 v107, 0xffff0000, v182
	v_pk_add_f32 v[96:97], v[96:97], v[106:107]
	v_cvt_pk_bf16_f32 v115, v108, v109
	v_cvt_pk_bf16_f32 v106, v96, v97
	v_lshlrev_b32_e32 v96, 16, v183
	v_and_b32_e32 v97, 0xffff0000, v183
	v_pk_add_f32 v[96:97], v[98:99], v[96:97]
	s_waitcnt vmcnt(11)
	v_lshlrev_b32_e32 v98, 16, v177
	v_cvt_pk_bf16_f32 v107, v96, v97
	v_lshlrev_b32_e32 v96, 16, v176
	v_and_b32_e32 v97, 0xffff0000, v176
	v_and_b32_e32 v99, 0xffff0000, v177
	v_pk_add_f32 v[96:97], v[100:101], v[96:97]
	v_pk_add_f32 v[98:99], v[102:103], v[98:99]
	v_cvt_pk_bf16_f32 v96, v96, v97
	v_cvt_pk_bf16_f32 v97, v98, v99
	v_lshlrev_b32_e32 v98, 16, v178
	v_and_b32_e32 v99, 0xffff0000, v178
	v_pk_add_f32 v[92:93], v[92:93], v[98:99]
	v_lshl_add_u64 v[108:109], s[88:89], 0, v[222:223]
	v_cvt_pk_bf16_f32 v98, v92, v93
	v_lshlrev_b32_e32 v92, 16, v179
	v_and_b32_e32 v93, 0xffff0000, v179
	v_pk_add_f32 v[92:93], v[94:95], v[92:93]
	s_waitcnt vmcnt(10)
	v_lshlrev_b32_e32 v94, 16, v168
	v_and_b32_e32 v95, 0xffff0000, v168
	v_pk_add_f32 v[88:89], v[88:89], v[94:95]
	v_lshlrev_b32_e32 v94, 16, v169
	v_and_b32_e32 v95, 0xffff0000, v169
	v_pk_add_f32 v[90:91], v[90:91], v[94:95]
	v_cvt_pk_bf16_f32 v88, v88, v89
	v_cvt_pk_bf16_f32 v89, v90, v91
	v_lshlrev_b32_e32 v90, 16, v170
	v_and_b32_e32 v91, 0xffff0000, v170
	v_pk_add_f32 v[80:81], v[80:81], v[90:91]
	v_cvt_pk_bf16_f32 v99, v92, v93
	v_cvt_pk_bf16_f32 v90, v80, v81
	v_lshlrev_b32_e32 v80, 16, v171
	v_and_b32_e32 v81, 0xffff0000, v171
	v_pk_add_f32 v[80:81], v[82:83], v[80:81]
	s_waitcnt vmcnt(9)
	v_lshlrev_b32_e32 v82, 16, v173
	v_cvt_pk_bf16_f32 v91, v80, v81
	v_lshlrev_b32_e32 v80, 16, v172
	v_and_b32_e32 v81, 0xffff0000, v172
	v_and_b32_e32 v83, 0xffff0000, v173
	v_pk_add_f32 v[80:81], v[84:85], v[80:81]
	v_pk_add_f32 v[82:83], v[86:87], v[82:83]
	v_cvt_pk_bf16_f32 v80, v80, v81
	v_cvt_pk_bf16_f32 v81, v82, v83
	v_lshlrev_b32_e32 v82, 16, v174
	v_and_b32_e32 v83, 0xffff0000, v174
	v_pk_add_f32 v[76:77], v[76:77], v[82:83]
	v_lshl_add_u64 v[92:93], s[88:89], 0, v[220:221]
	v_cvt_pk_bf16_f32 v82, v76, v77
	v_lshlrev_b32_e32 v76, 16, v175
	v_and_b32_e32 v77, 0xffff0000, v175
	v_pk_add_f32 v[76:77], v[78:79], v[76:77]
	s_waitcnt vmcnt(8)
	v_lshlrev_b32_e32 v78, 16, v164
	v_and_b32_e32 v79, 0xffff0000, v164
	v_pk_add_f32 v[72:73], v[72:73], v[78:79]
	v_lshlrev_b32_e32 v78, 16, v165
	v_and_b32_e32 v79, 0xffff0000, v165
	v_pk_add_f32 v[74:75], v[74:75], v[78:79]
	v_cvt_pk_bf16_f32 v72, v72, v73
	v_cvt_pk_bf16_f32 v73, v74, v75
	v_lshlrev_b32_e32 v74, 16, v166
	v_and_b32_e32 v75, 0xffff0000, v166
	v_pk_add_f32 v[68:69], v[68:69], v[74:75]
	v_cvt_pk_bf16_f32 v83, v76, v77
	v_cvt_pk_bf16_f32 v74, v68, v69
	v_lshlrev_b32_e32 v68, 16, v167
	v_and_b32_e32 v69, 0xffff0000, v167
	v_pk_add_f32 v[68:69], v[70:71], v[68:69]
	v_lshl_add_u64 v[76:77], s[88:89], 0, v[212:213]
	v_cvt_pk_bf16_f32 v75, v68, v69
	s_waitcnt vmcnt(7)
	v_lshlrev_b32_e32 v68, 16, v160
	v_and_b32_e32 v69, 0xffff0000, v160
	v_pk_add_f32 v[64:65], v[64:65], v[68:69]
	v_lshlrev_b32_e32 v68, 16, v161
	v_and_b32_e32 v69, 0xffff0000, v161
	v_pk_add_f32 v[66:67], v[66:67], v[68:69]
	v_cvt_pk_bf16_f32 v64, v64, v65
	v_cvt_pk_bf16_f32 v65, v66, v67
	v_lshlrev_b32_e32 v66, 16, v162
	v_and_b32_e32 v67, 0xffff0000, v162
	v_pk_add_f32 v[60:61], v[60:61], v[66:67]
	v_lshl_add_u64 v[108:109], v[108:109], 0, v[202:203]
	v_cvt_pk_bf16_f32 v66, v60, v61
	v_lshlrev_b32_e32 v60, 16, v163
	v_and_b32_e32 v61, 0xffff0000, v163
	v_pk_add_f32 v[60:61], v[62:63], v[60:61]
	s_waitcnt vmcnt(6)
; __device__ __forceinline__ unsigned cvt_pk_bf16(float lo, float hi) { const f32x2 v = {lo, hi}; const bf16v2_ r = __builtin_convertvector(v, bf16v2_); return __builtin_bit_cast(unsigned, r); }
; __device__ __forceinline__ float bflo(unsigned w) { return __uint_as_float(w << 16); }
; __device__ __forceinline__ float bfhi(unsigned w) { return __uint_as_float(w & 0xffff0000u); }
;     __device__ __forceinline__ void operator()(const f32x4 (&acc)[2][2][4][2], const Unit& u, int wr, int wc, int, int) const {
;     ...
;         for (int ai = 0; ai < 2; ++ai)
; #pragma unroll
;             for (int m = 0; m < 4; ++m)
; #pragma unroll
;                 for (int bj = 0; bj < 2; ++bj) { const u32x4 c = cin[ai][m][bj]; const f32x4 v0 = acc[ai][bj][m][0], v1 = acc[ai][bj][m][1];
;                     u32x4 w; w.x = cvt_pk_bf16(bflo(c.x) + v0[0], bfhi(c.x) + v0[1]); w.y = cvt_pk_bf16(bflo(c.y) + v0[2], bfhi(c.y) + v0[3]);
;                     w.z = cvt_pk_bf16(bflo(c.z) + v1[0], bfhi(c.z) + v1[1]); w.w = cvt_pk_bf16(bflo(c.w) + v1[2], bfhi(c.w) + v1[3]);
;                     *(u32x4*)(C + (size_t)(row0 + ai * HALF + m * 16) * ldc + col0 + bj * HALF) = w; }
	v_lshlrev_b32_e32 v62, 16, v156
	v_and_b32_e32 v63, 0xffff0000, v156
	v_pk_add_f32 v[56:57], v[56:57], v[62:63]
	v_lshlrev_b32_e32 v62, 16, v157
	v_and_b32_e32 v63, 0xffff0000, v157
	v_pk_add_f32 v[58:59], v[58:59], v[62:63]
	v_cvt_pk_bf16_f32 v56, v56, v57
	v_cvt_pk_bf16_f32 v57, v58, v59
	v_lshlrev_b32_e32 v58, 16, v158
	v_and_b32_e32 v59, 0xffff0000, v158
	v_pk_add_f32 v[48:49], v[48:49], v[58:59]
	v_cvt_pk_bf16_f32 v67, v60, v61
	v_cvt_pk_bf16_f32 v58, v48, v49
	v_lshlrev_b32_e32 v48, 16, v159
	v_and_b32_e32 v49, 0xffff0000, v159
	v_pk_add_f32 v[48:49], v[50:51], v[48:49]
	s_waitcnt vmcnt(5)
	v_lshlrev_b32_e32 v50, 16, v153
	v_cvt_pk_bf16_f32 v59, v48, v49
	v_lshlrev_b32_e32 v48, 16, v152
	v_and_b32_e32 v49, 0xffff0000, v152
	v_and_b32_e32 v51, 0xffff0000, v153
	v_pk_add_f32 v[48:49], v[52:53], v[48:49]
	v_pk_add_f32 v[50:51], v[54:55], v[50:51]
	v_cvt_pk_bf16_f32 v48, v48, v49
	v_cvt_pk_bf16_f32 v49, v50, v51
	v_lshlrev_b32_e32 v50, 16, v154
	v_and_b32_e32 v51, 0xffff0000, v154
	v_pk_add_f32 v[44:45], v[44:45], v[50:51]
	v_lshl_add_u64 v[60:61], s[88:89], 0, v[210:211]
	v_cvt_pk_bf16_f32 v50, v44, v45
	v_lshlrev_b32_e32 v44, 16, v155
	v_and_b32_e32 v45, 0xffff0000, v155
	v_pk_add_f32 v[44:45], v[46:47], v[44:45]
	s_waitcnt vmcnt(4)
	v_lshlrev_b32_e32 v46, 16, v148
	v_and_b32_e32 v47, 0xffff0000, v148
	v_pk_add_f32 v[40:41], v[40:41], v[46:47]
	v_lshlrev_b32_e32 v46, 16, v149
	v_and_b32_e32 v47, 0xffff0000, v149
	v_pk_add_f32 v[42:43], v[42:43], v[46:47]
	v_cvt_pk_bf16_f32 v40, v40, v41
	v_cvt_pk_bf16_f32 v41, v42, v43
	v_lshlrev_b32_e32 v42, 16, v150
	v_and_b32_e32 v43, 0xffff0000, v150
	v_pk_add_f32 v[32:33], v[32:33], v[42:43]
	v_cvt_pk_bf16_f32 v51, v44, v45
	v_cvt_pk_bf16_f32 v42, v32, v33
	v_lshlrev_b32_e32 v32, 16, v151
	v_and_b32_e32 v33, 0xffff0000, v151
	v_pk_add_f32 v[32:33], v[34:35], v[32:33]
	s_waitcnt vmcnt(3)
	v_lshlrev_b32_e32 v34, 16, v145
	v_cvt_pk_bf16_f32 v43, v32, v33
	v_lshlrev_b32_e32 v32, 16, v144
	v_and_b32_e32 v33, 0xffff0000, v144
	v_and_b32_e32 v35, 0xffff0000, v145
	v_pk_add_f32 v[32:33], v[36:37], v[32:33]
	v_pk_add_f32 v[34:35], v[38:39], v[34:35]
	v_cvt_pk_bf16_f32 v32, v32, v33
	v_cvt_pk_bf16_f32 v33, v34, v35
	v_lshlrev_b32_e32 v34, 16, v146
	v_and_b32_e32 v35, 0xffff0000, v146
	v_pk_add_f32 v[28:29], v[28:29], v[34:35]
	v_lshl_add_u64 v[44:45], s[88:89], 0, v[208:209]
	v_cvt_pk_bf16_f32 v34, v28, v29
	v_lshlrev_b32_e32 v28, 16, v147
	v_and_b32_e32 v29, 0xffff0000, v147
	v_pk_add_f32 v[28:29], v[30:31], v[28:29]
	s_waitcnt vmcnt(2)
	v_lshlrev_b32_e32 v30, 16, v140
	v_and_b32_e32 v31, 0xffff0000, v140
	v_pk_add_f32 v[24:25], v[24:25], v[30:31]
	v_lshlrev_b32_e32 v30, 16, v141
	v_and_b32_e32 v31, 0xffff0000, v141
	v_pk_add_f32 v[26:27], v[26:27], v[30:31]
	v_cvt_pk_bf16_f32 v24, v24, v25
	v_cvt_pk_bf16_f32 v25, v26, v27
	v_lshlrev_b32_e32 v26, 16, v142
	v_and_b32_e32 v27, 0xffff0000, v142
	v_pk_add_f32 v[16:17], v[16:17], v[26:27]
	v_cvt_pk_bf16_f32 v35, v28, v29
	v_cvt_pk_bf16_f32 v26, v16, v17
	v_lshlrev_b32_e32 v16, 16, v143
	v_and_b32_e32 v17, 0xffff0000, v143
	v_pk_add_f32 v[16:17], v[18:19], v[16:17]
	s_waitcnt vmcnt(1)
	v_lshlrev_b32_e32 v18, 16, v137
	v_cvt_pk_bf16_f32 v27, v16, v17
	v_lshlrev_b32_e32 v16, 16, v136
	v_and_b32_e32 v17, 0xffff0000, v136
	v_and_b32_e32 v19, 0xffff0000, v137
	v_pk_add_f32 v[16:17], v[20:21], v[16:17]
	v_pk_add_f32 v[18:19], v[22:23], v[18:19]
	v_cvt_pk_bf16_f32 v16, v16, v17
	v_cvt_pk_bf16_f32 v17, v18, v19
	v_lshlrev_b32_e32 v18, 16, v138
	v_and_b32_e32 v19, 0xffff0000, v138
	v_pk_add_f32 v[12:13], v[12:13], v[18:19]
	v_lshl_add_u64 v[28:29], s[88:89], 0, v[206:207]
	v_cvt_pk_bf16_f32 v18, v12, v13
	v_lshlrev_b32_e32 v12, 16, v139
	v_and_b32_e32 v13, 0xffff0000, v139
	v_pk_add_f32 v[12:13], v[14:15], v[12:13]
	s_waitcnt vmcnt(0)
; __device__ __forceinline__ unsigned cvt_pk_bf16(float lo, float hi) { const f32x2 v = {lo, hi}; const bf16v2_ r = __builtin_convertvector(v, bf16v2_); return __builtin_bit_cast(unsigned, r); }
; __device__ __forceinline__ float bflo(unsigned w) { return __uint_as_float(w << 16); }
; __device__ __forceinline__ float bfhi(unsigned w) { return __uint_as_float(w & 0xffff0000u); }
; __device__ __forceinline__ float wave_sum(float v) { v = row16_sum(v); v += shx(v, 16); v += shx(v, 32); return v; }
;     __device__ __forceinline__ void operator()(const f32x4 (&acc)[2][2][4][2], const Unit& u, int wr, int wc, int, int) const {
;     ...
;         for (int ai = 0; ai < 2; ++ai)
; #pragma unroll
;             for (int m = 0; m < 4; ++m)
; #pragma unroll
;                 for (int bj = 0; bj < 2; ++bj) { const u32x4 c = cin[ai][m][bj]; const f32x4 v0 = acc[ai][bj][m][0], v1 = acc[ai][bj][m][1];
;                     u32x4 w; w.x = cvt_pk_bf16(bflo(c.x) + v0[0], bfhi(c.x) + v0[1]); w.y = cvt_pk_bf16(bflo(c.y) + v0[2], bfhi(c.y) + v0[3]);
;                     w.z = cvt_pk_bf16(bflo(c.z) + v1[0], bfhi(c.z) + v1[1]); w.w = cvt_pk_bf16(bflo(c.w) + v1[2], bfhi(c.w) + v1[3]);
;                     *(u32x4*)(C + (size_t)(row0 + ai * HALF + m * 16) * ldc + col0 + bj * HALF) = w; }
; __device__ __forceinline__ void rowstat_phase(const Frame& F, const bf16_t* __restrict__ res, float* __restrict__ rstd_out) {
;     ...
;         for (int r = 0; r < 4; ++r) { ss[r] = 0.f;
; #pragma unroll
;             for (int i = 0; i < 4; ++i) { const u32x4 x = v[r][i];
;                 ss[r] += bflo(x.x) * bflo(x.x) + bfhi(x.x) * bfhi(x.x) + bflo(x.y) * bflo(x.y) + bfhi(x.y) * bfhi(x.y) + bflo(x.z) * bflo(x.z) + bfhi(x.z) * bfhi(x.z) + bflo(x.w) * bflo(x.w) + bfhi(x.w) * bfhi(x.w); }
;             ss[r] = wave_sum(ss[r]); }
	v_lshlrev_b32_e32 v14, 16, v132
	v_and_b32_e32 v15, 0xffff0000, v132
	v_pk_add_f32 v[8:9], v[8:9], v[14:15]
	v_lshlrev_b32_e32 v14, 16, v133
	v_and_b32_e32 v15, 0xffff0000, v133
	v_pk_add_f32 v[10:11], v[10:11], v[14:15]
	v_cvt_pk_bf16_f32 v8, v8, v9
	v_cvt_pk_bf16_f32 v9, v10, v11
	v_lshlrev_b32_e32 v10, 16, v134
	v_and_b32_e32 v11, 0xffff0000, v134
	v_pk_add_f32 v[4:5], v[4:5], v[10:11]
	v_cvt_pk_bf16_f32 v19, v12, v13
	v_cvt_pk_bf16_f32 v10, v4, v5
	v_lshlrev_b32_e32 v4, 16, v135
	v_and_b32_e32 v5, 0xffff0000, v135
	v_lshl_add_u64 v[12:13], s[88:89], 0, v[204:205]
	v_pk_add_f32 v[4:5], v[6:7], v[4:5]
	v_lshl_add_u64 v[92:93], v[92:93], 0, v[202:203]
	v_lshl_add_u64 v[76:77], v[76:77], 0, v[202:203]
	v_lshl_add_u64 v[60:61], v[60:61], 0, v[202:203]
	v_lshl_add_u64 v[44:45], v[44:45], 0, v[202:203]
	v_lshl_add_u64 v[28:29], v[28:29], 0, v[202:203]
	v_lshl_add_u64 v[12:13], v[12:13], 0, v[202:203]
	v_cvt_pk_bf16_f32 v11, v4, v5
	global_store_dwordx4 v[124:125], v[128:131], off
	global_store_dwordx4 v[124:125], v[120:123], off offset:256
	global_store_dwordx4 v[108:109], v[112:115], off
	global_store_dwordx4 v[108:109], v[104:107], off offset:256
	global_store_dwordx4 v[92:93], v[96:99], off
	global_store_dwordx4 v[92:93], v[88:91], off offset:256
	global_store_dwordx4 v[76:77], v[80:83], off
	global_store_dwordx4 v[76:77], v[72:75], off offset:256
	global_store_dwordx4 v[60:61], v[64:67], off
	global_store_dwordx4 v[60:61], v[56:59], off offset:256
	global_store_dwordx4 v[44:45], v[48:51], off
	global_store_dwordx4 v[44:45], v[40:43], off offset:256
	global_store_dwordx4 v[28:29], v[32:35], off
	global_store_dwordx4 v[28:29], v[24:27], off offset:256
	global_store_dwordx4 v[12:13], v[16:19], off
	global_store_dwordx4 v[12:13], v[8:11], off offset:256
	v_subrev_u32_e32 v216, s88, v124
	v_bfe_u32 v217, v216, 4, 8
	v_lshrrev_b32_e32 v216, 12, v216
	v_and_b32_e32 v218, 15, v217
	v_lshrrev_b32_e32 v217, 5, v217
	v_lshl_or_b32 v217, v217, 4, v218
	v_lshlrev_b32_e32 v217, 10, v217
	v_and_b32_e32 v218, 15, v216
	v_and_b32_e32 v219, 0xc0, v216
	v_lshl_or_b32 v218, v218, 2, v219
	v_lshl_add_u32 v217, v218, 2, v217
	v_lshrrev_b32_e32 v216, 8, v216
	v_lshl_add_u32 v216, v216, 17, v217
	v_add_u32_e32 v216, 0x1e000000, v216
	v_mov_b32_e32 v188, 0
	v_dot2c_f32_bf16_e32 v188, v128, v128
	v_dot2c_f32_bf16_e32 v188, v129, v129
	v_dot2c_f32_bf16_e32 v188, v130, v130
	v_dot2c_f32_bf16_e32 v188, v131, v131
	v_dot2c_f32_bf16_e32 v188, v120, v120
	v_dot2c_f32_bf16_e32 v188, v121, v121
	v_dot2c_f32_bf16_e32 v188, v122, v122
	v_dot2c_f32_bf16_e32 v188, v123, v123
	v_mov_b32_e32 v189, 0
	v_dot2c_f32_bf16_e32 v189, v112, v112
	v_dot2c_f32_bf16_e32 v189, v113, v113
	v_dot2c_f32_bf16_e32 v189, v114, v114
	v_dot2c_f32_bf16_e32 v189, v115, v115
	v_dot2c_f32_bf16_e32 v189, v104, v104
	v_dot2c_f32_bf16_e32 v189, v105, v105
	v_dot2c_f32_bf16_e32 v189, v106, v106
	v_dot2c_f32_bf16_e32 v189, v107, v107
	v_mov_b32_e32 v190, 0
	v_dot2c_f32_bf16_e32 v190, v96, v96
	v_dot2c_f32_bf16_e32 v190, v97, v97
	v_dot2c_f32_bf16_e32 v190, v98, v98
	v_dot2c_f32_bf16_e32 v190, v99, v99
	v_dot2c_f32_bf16_e32 v190, v88, v88
	v_dot2c_f32_bf16_e32 v190, v89, v89
	v_dot2c_f32_bf16_e32 v190, v90, v90
	v_dot2c_f32_bf16_e32 v190, v91, v91
	v_mov_b32_e32 v191, 0
	v_dot2c_f32_bf16_e32 v191, v80, v80
	v_dot2c_f32_bf16_e32 v191, v81, v81
	v_dot2c_f32_bf16_e32 v191, v82, v82
	v_dot2c_f32_bf16_e32 v191, v83, v83
	v_dot2c_f32_bf16_e32 v191, v72, v72
	v_dot2c_f32_bf16_e32 v191, v73, v73
	v_dot2c_f32_bf16_e32 v191, v74, v74
	v_dot2c_f32_bf16_e32 v191, v75, v75
	s_nop 2
	global_store_dwordx4 v216, v[188:191], s[88:89]
	s_nop 1
	v_mov_b32_e32 v188, 0
	v_dot2c_f32_bf16_e32 v188, v64, v64
	v_dot2c_f32_bf16_e32 v188, v65, v65
	v_dot2c_f32_bf16_e32 v188, v66, v66
	v_dot2c_f32_bf16_e32 v188, v67, v67
	v_dot2c_f32_bf16_e32 v188, v56, v56
	v_dot2c_f32_bf16_e32 v188, v57, v57
	v_dot2c_f32_bf16_e32 v188, v58, v58
	v_dot2c_f32_bf16_e32 v188, v59, v59
	v_mov_b32_e32 v189, 0
	v_dot2c_f32_bf16_e32 v189, v48, v48
	v_dot2c_f32_bf16_e32 v189, v49, v49
	v_dot2c_f32_bf16_e32 v189, v50, v50
	v_dot2c_f32_bf16_e32 v189, v51, v51
	v_dot2c_f32_bf16_e32 v189, v40, v40
	v_dot2c_f32_bf16_e32 v189, v41, v41
	v_dot2c_f32_bf16_e32 v189, v42, v42
	v_dot2c_f32_bf16_e32 v189, v43, v43
	v_mov_b32_e32 v190, 0
	v_dot2c_f32_bf16_e32 v190, v32, v32
	v_dot2c_f32_bf16_e32 v190, v33, v33
	v_dot2c_f32_bf16_e32 v190, v34, v34
	v_dot2c_f32_bf16_e32 v190, v35, v35
	v_dot2c_f32_bf16_e32 v190, v24, v24
	v_dot2c_f32_bf16_e32 v190, v25, v25
	v_dot2c_f32_bf16_e32 v190, v26, v26
	v_dot2c_f32_bf16_e32 v190, v27, v27
	v_mov_b32_e32 v191, 0
	v_dot2c_f32_bf16_e32 v191, v16, v16
	v_dot2c_f32_bf16_e32 v191, v17, v17
	v_dot2c_f32_bf16_e32 v191, v18, v18
	v_dot2c_f32_bf16_e32 v191, v19, v19
	v_dot2c_f32_bf16_e32 v191, v8, v8
	v_dot2c_f32_bf16_e32 v191, v9, v9
	v_dot2c_f32_bf16_e32 v191, v10, v10
	v_dot2c_f32_bf16_e32 v191, v11, v11
	s_nop 2
	global_store_dwordx4 v216, v[188:191], s[88:89] offset:512
	s_nop 1
	s_cbranch_vccz .LBB0_959
	s_waitcnt vmcnt(0)
	s_cmpk_gt_u32 s2, 0xff
	s_cbranch_scc1 .LBB0_970
	s_barrier

; __device__ __forceinline__ float bflo(unsigned w) { return __uint_as_float(w << 16); }
; __device__ __forceinline__ float bfhi(unsigned w) { return __uint_as_float(w & 0xffff0000u); }
; __device__ __forceinline__ float wave_sum(float v) { v = row16_sum(v); v += shx(v, 16); v += shx(v, 32); return v; }
; #define WAVE (__builtin_amdgcn_readfirstlane(opaque_tid() >> 6))
; __device__ __forceinline__ void rowstat_phase(const Frame& F, const bf16_t* __restrict__ res, float* __restrict__ rstd_out) {
;     for (int row0 = (F.bid * NWAVE + WAVE) * 4; row0 < M; row0 += F.G * NWAVE * 4) {
;         u32x4 v[4][4];
; #pragma unroll
;         for (int r = 0; r < 4; ++r)
; #pragma unroll
;             for (int i = 0; i < 4; ++i) v[r][i] = *(const u32x4*)(res + (size_t)(row0 + r) * D + LANE * 8 + i * 512);
;         float ss[4];
; #pragma unroll
;         for (int r = 0; r < 4; ++r) { ss[r] = 0.f;
; #pragma unroll
;             for (int i = 0; i < 4; ++i) { const u32x4 x = v[r][i];
;                 ss[r] += bflo(x.x) * bflo(x.x) + bfhi(x.x) * bfhi(x.x) + bflo(x.y) * bflo(x.y) + bfhi(x.y) * bfhi(x.y) + bflo(x.z) * bflo(x.z) + bfhi(x.z) * bfhi(x.z) + bflo(x.w) * bflo(x.w) + bfhi(x.w) * bfhi(x.w); }
;             ss[r] = wave_sum(ss[r]); }
;         if (LANE < 4) rstd_out[row0 + LANE] = rsqrtf((LANE == 0 ? ss[0] : LANE == 1 ? ss[1] : LANE == 2 ? ss[2] : ss[3]) * (1.f / D) + EPS);
;     }
.Lrsp_loop_a:
	s_cmp_lt_i32 s4, 0x8000
	s_cbranch_scc0 .Lrsp_done_a
	v_and_b32_e32 v1, 0x7f, v0
	v_lshrrev_b32_e32 v2, 7, v0
	v_add_u32_e32 v1, s4, v1
	v_and_b32_e32 v7, 15, v1
	v_bfe_u32 v8, v1, 4, 2
	v_lshl_or_b32 v7, v7, 2, v8
	v_and_b32_e32 v8, 0xc0, v1
	v_or_b32_e32 v7, v7, v8
	v_lshlrev_b32_e32 v4, 15, v2
	v_lshl_add_u32 v4, v7, 2, v4
	v_lshrrev_b32_e32 v8, 8, v1
	v_lshl_add_u32 v4, v8, 17, v4
	v_add_u32_e32 v4, 0x1e000000, v4
	s_mov_b32 s6, s88
	s_mov_b32 s7, s89
	global_load_dword v10, v4, s[6:7]
	global_load_dword v11, v4, s[6:7] offset:1024
	global_load_dword v12, v4, s[6:7] offset:2048
	global_load_dword v13, v4, s[6:7] offset:3072
	s_add_u32 s6, s6, 0x1000
	s_addc_u32 s7, s7, 0
	global_load_dword v14, v4, s[6:7]
	global_load_dword v15, v4, s[6:7] offset:1024
	global_load_dword v16, v4, s[6:7] offset:2048
	global_load_dword v17, v4, s[6:7] offset:3072
	s_add_u32 s6, s6, 0x1000
	s_addc_u32 s7, s7, 0
	global_load_dword v18, v4, s[6:7]
	global_load_dword v19, v4, s[6:7] offset:1024
	global_load_dword v20, v4, s[6:7] offset:2048
	global_load_dword v21, v4, s[6:7] offset:3072
	s_add_u32 s6, s6, 0x1000
	s_addc_u32 s7, s7, 0
	global_load_dword v22, v4, s[6:7]
	global_load_dword v23, v4, s[6:7] offset:1024
	global_load_dword v24, v4, s[6:7] offset:2048
	global_load_dword v25, v4, s[6:7] offset:3072
	s_add_u32 s6, s6, 0x1000
	s_addc_u32 s7, s7, 0
	global_load_dword v26, v4, s[6:7]
	global_load_dword v27, v4, s[6:7] offset:1024
	global_load_dword v28, v4, s[6:7] offset:2048
	global_load_dword v29, v4, s[6:7] offset:3072
	s_add_u32 s6, s6, 0x1000
	s_addc_u32 s7, s7, 0
	global_load_dword v30, v4, s[6:7]
	global_load_dword v31, v4, s[6:7] offset:1024
	global_load_dword v32, v4, s[6:7] offset:2048
	global_load_dword v33, v4, s[6:7] offset:3072
	s_add_u32 s6, s6, 0x1000
	s_addc_u32 s7, s7, 0
	global_load_dword v34, v4, s[6:7]
	global_load_dword v35, v4, s[6:7] offset:1024
	global_load_dword v36, v4, s[6:7] offset:2048
	global_load_dword v37, v4, s[6:7] offset:3072
	s_add_u32 s6, s6, 0x1000
	s_addc_u32 s7, s7, 0
	global_load_dword v38, v4, s[6:7]
	global_load_dword v39, v4, s[6:7] offset:1024
	global_load_dword v40, v4, s[6:7] offset:2048
	global_load_dword v41, v4, s[6:7] offset:3072
	s_waitcnt vmcnt(0)
	v_add_f32_e32 v10, v10, v11
	v_add_f32_e32 v12, v12, v13
	v_add_f32_e32 v14, v14, v15
	v_add_f32_e32 v16, v16, v17
	v_add_f32_e32 v18, v18, v19
	v_add_f32_e32 v20, v20, v21
	v_add_f32_e32 v22, v22, v23
	v_add_f32_e32 v24, v24, v25
	v_add_f32_e32 v26, v26, v27
	v_add_f32_e32 v28, v28, v29
	v_add_f32_e32 v30, v30, v31
	v_add_f32_e32 v32, v32, v33
	v_add_f32_e32 v34, v34, v35
	v_add_f32_e32 v36, v36, v37
	v_add_f32_e32 v38, v38, v39
	v_add_f32_e32 v40, v40, v41
	v_add_f32_e32 v10, v10, v12
	v_add_f32_e32 v14, v14, v16
	v_add_f32_e32 v18, v18, v20
	v_add_f32_e32 v22, v22, v24
	v_add_f32_e32 v26, v26, v28
	v_add_f32_e32 v30, v30, v32
	v_add_f32_e32 v34, v34, v36
	v_add_f32_e32 v38, v38, v40
	v_add_f32_e32 v10, v10, v14
	v_add_f32_e32 v18, v18, v22
	v_add_f32_e32 v26, v26, v30
	v_add_f32_e32 v34, v34, v38
	v_add_f32_e32 v10, v10, v18
	v_add_f32_e32 v26, v26, v34
	v_add_f32_e32 v10, v10, v26
	v_lshlrev_b32_e32 v5, 2, v0
	ds_write_b32 v5, v10
	s_waitcnt lgkmcnt(0)
	s_barrier
	v_cmp_gt_u32_e32 vcc, 0x80, v0
	s_and_saveexec_b64 s[14:15], vcc
	s_cbranch_execz .Lrsp_skip_a
	ds_read_b32 v11, v5
	ds_read_b32 v12, v5 offset:512
	ds_read_b32 v13, v5 offset:1024
	ds_read_b32 v14, v5 offset:1536
	v_readlane_b32 s18, v252, 14
	v_readlane_b32 s19, v252, 15
	v_mov_b32_e32 v15, 0x358637bd
	v_lshlrev_b32_e32 v6, 2, v1
	s_waitcnt lgkmcnt(0)
	v_add_f32_e32 v11, v11, v12
	v_add_f32_e32 v13, v13, v14
	v_add_f32_e32 v11, v11, v13
	v_fmamk_f32 v11, v11, 0x3a000000, v15
	v_rsq_f32_e32 v11, v11
	s_nop 1
	global_store_dword v6, v11, s[18:19]

; #define PG8_STAGE(bufoff, gbase, voff) do { _Pragma("unroll") for (int _i = 0; _i < 2; ++_i) \
;         __builtin_amdgcn_global_load_lds((const unsigned*)((const char*)(gbase) + (voff)[_i]), (LAS unsigned*)(lds + (bufoff) + ldsw + _i * 8192), 16, 0, 0); } while (0)
; #define PG8_LDA(dst, b, h) do { _Pragma("unroll") for (int m = 0; m < 4; ++m) _Pragma("unroll") for (int k = 0; k < 2; ++k) dst[m][k] = *(const LAS bf16x8*)(lds + PG8_SA(b, h) + aoff + m * 2048 + k * 1024); } while (0)
; #define PG8_LDB(dst, b, h) do { _Pragma("unroll") for (int n = 0; n < 2; ++n) _Pragma("unroll") for (int k = 0; k < 2; ++k) dst[n][k] = *(const LAS bf16x8*)(lds + PG8_SB(b, h) + boff + n * 2048 + k * 1024); } while (0)
; #define PG8_WAIT_V(n) asm volatile("s_waitcnt vmcnt(" #n ")" ::: "memory")
; #define PG8_WAIT_L(n) asm volatile("s_waitcnt lgkmcnt(" #n ")" ::: "memory")
; #define PG8_BAR __builtin_amdgcn_s_barrier()
; #define PG8_SCHED __builtin_amdgcn_sched_barrier(0)
; template <class Epi, class Sched>
; __device__ __forceinline__ void gemm_phase(LAS unsigned char* lds, const Gemm g, const Sched& S, const Epi& E) {
;     ...
;             PG8_LDB(B0, 0, 0); PG8_SCHED; PG8_LDA(At, 0, 0); PG8_STAGE(PG8_SA(1, 1), a1 + hstepA, voffA);
;             PG8_WAIT_L(8); PG8_BAR; PG8_WAIT_L(0); PG8_MMA(0, 0, At, B0); PG8_BAR; PG8_SCHED;
;             PG8_LDB(B1, 0, 1); PG8_STAGE(PG8_SB(0, 0), b2, voffB);
;             PG8_BAR; PG8_WAIT_L(0); PG8_MMA(0, 1, At, B1); PG8_BAR;
;             PG8_LDA(At, 0, 1); PG8_STAGE(PG8_SA(0, 0), a2, voffA);
;             PG8_BAR; PG8_WAIT_L(0); PG8_MMA(1, 0, At, B0); PG8_BAR; PG8_SCHED;
;             PG8_STAGE(PG8_SB(0, 1), b2 + hstepB, voffB);
;             PG8_WAIT_V(6); PG8_BAR; PG8_MMA(1, 1, At, B1); PG8_BAR;
;             PG8_LDB(B0, 1, 0); PG8_SCHED; PG8_LDA(At, 1, 0); PG8_STAGE(PG8_SA(0, 1), a2 + hstepA, voffA);
;             PG8_WAIT_L(8); PG8_BAR; PG8_WAIT_L(0); PG8_MMA(0, 0, At, B0); PG8_BAR; PG8_SCHED;
;             PG8_LDB(B1, 1, 1); PG8_STAGE(PG8_SB(1, 0), b3, voffB);
;             PG8_BAR; PG8_WAIT_L(0); PG8_MMA(0, 1, At, B1); PG8_BAR;
;             PG8_LDA(At, 1, 1); PG8_STAGE(PG8_SA(1, 0), a3, voffA);
;             PG8_BAR; PG8_WAIT_L(0); PG8_MMA(1, 0, At, B0); PG8_BAR; PG8_SCHED;
;             PG8_STAGE(PG8_SB(1, 1), b3 + hstepB, voffB);
;             PG8_WAIT_V(6); PG8_BAR; PG8_MMA(1, 1, At, B1); PG8_BAR;
.LBB0_1396:
	s_setprio 0
	s_add_u32 s20, s6, 0xfff80080
	s_addc_u32 s21, s7, -1
	s_add_i32 s52, 0, 0x10000
	v_add_u32_e32 v144, s52, v1
	ds_read_b128 v[132:135], v144
	ds_read_b128 v[136:139], v144 offset:1024
	ds_read_b128 v[140:143], v144 offset:2048
	ds_read_b128 v[144:147], v144 offset:3072
	s_cmp_eq_u32 s51, 28
	s_cselect_b32 s25, s15, s21
	s_cselect_b32 s24, s47, s20
	s_cselect_b32 s21, s1, s50
	s_cselect_b32 s20, s48, s49
	ds_read_b128 v[148:151], v224
	ds_read_b128 v[152:155], v224 offset:1024
	ds_read_b128 v[156:159], v224 offset:2048
	ds_read_b128 v[160:163], v224 offset:3072
	ds_read_b128 v[164:167], v224 offset:4096
	ds_read_b128 v[168:171], v224 offset:5120
	ds_read_b128 v[172:175], v224 offset:6144
	ds_read_b128 v[176:179], v224 offset:7168
	s_add_i32 s54, 0, 0x14000
	v_add_u32_e32 v202, s54, v1
	ds_read_b128 v[180:183], v202
	ds_read_b128 v[184:187], v202 offset:1024
	ds_read_b128 v[188:191], v202 offset:2048
	ds_read_b128 v[202:205], v202 offset:3072
	s_add_i32 m0, s31, 0xc000
	s_nop 0
	global_load_lds_dwordx4 v198, s[6:7]
	s_add_i32 m0, s31, 0xe000
	s_nop 0
	global_load_lds_dwordx4 v200, s[6:7]
	s_waitcnt lgkmcnt(0)
	s_setprio 1
	s_barrier
	v_mfma_f32_16x16x32_bf16 v[128:131], v[132:135], v[148:151], v[128:131]
	v_mfma_f32_16x16x32_bf16 v[124:127], v[140:143], v[148:151], v[124:127]
	v_mfma_f32_16x16x32_bf16 v[112:115], v[132:135], v[156:159], v[112:115]
	v_mfma_f32_16x16x32_bf16 v[108:111], v[140:143], v[156:159], v[108:111]
	v_mfma_f32_16x16x32_bf16 v[100:103], v[132:135], v[164:167], v[100:103]
	v_mfma_f32_16x16x32_bf16 v[92:95], v[140:143], v[164:167], v[92:95]
	v_mfma_f32_16x16x32_bf16 v[84:87], v[132:135], v[172:175], v[84:87]
	v_mfma_f32_16x16x32_bf16 v[76:79], v[140:143], v[172:175], v[76:79]
	v_mfma_f32_16x16x32_bf16 v[128:131], v[136:139], v[152:155], v[128:131]
	v_mfma_f32_16x16x32_bf16 v[124:127], v[144:147], v[152:155], v[124:127]
	v_mfma_f32_16x16x32_bf16 v[112:115], v[136:139], v[160:163], v[112:115]
	v_mfma_f32_16x16x32_bf16 v[108:111], v[144:147], v[160:163], v[108:111]
	v_mfma_f32_16x16x32_bf16 v[100:103], v[136:139], v[168:171], v[100:103]
	v_mfma_f32_16x16x32_bf16 v[92:95], v[144:147], v[168:171], v[92:95]
	v_mfma_f32_16x16x32_bf16 v[84:87], v[136:139], v[176:179], v[84:87]
	v_mfma_f32_16x16x32_bf16 v[76:79], v[144:147], v[176:179], v[76:79]
	v_mfma_f32_16x16x32_bf16 v[120:123], v[180:183], v[148:151], v[120:123]
	v_mfma_f32_16x16x32_bf16 v[116:119], v[188:191], v[148:151], v[116:119]
	v_mfma_f32_16x16x32_bf16 v[104:107], v[180:183], v[156:159], v[104:107]
	v_mfma_f32_16x16x32_bf16 v[96:99], v[188:191], v[156:159], v[96:99]
	v_mfma_f32_16x16x32_bf16 v[88:91], v[180:183], v[164:167], v[88:91]
	v_mfma_f32_16x16x32_bf16 v[80:83], v[188:191], v[164:167], v[80:83]
	v_mfma_f32_16x16x32_bf16 v[72:75], v[180:183], v[172:175], v[72:75]
	v_mfma_f32_16x16x32_bf16 v[68:71], v[188:191], v[172:175], v[68:71]
	v_mfma_f32_16x16x32_bf16 v[120:123], v[184:187], v[152:155], v[120:123]
	v_mfma_f32_16x16x32_bf16 v[116:119], v[202:205], v[152:155], v[116:119]
	v_mfma_f32_16x16x32_bf16 v[104:107], v[184:187], v[160:163], v[104:107]
	v_mfma_f32_16x16x32_bf16 v[96:99], v[202:205], v[160:163], v[96:99]
	v_mfma_f32_16x16x32_bf16 v[88:91], v[184:187], v[168:171], v[88:91]
	v_mfma_f32_16x16x32_bf16 v[80:83], v[202:205], v[168:171], v[80:83]
	v_mfma_f32_16x16x32_bf16 v[72:75], v[184:187], v[176:179], v[72:75]
	v_mfma_f32_16x16x32_bf16 v[68:71], v[202:205], v[176:179], v[68:71]
	s_barrier
	s_setprio 0
	ds_read_b128 v[148:151], v224 offset:16384
	ds_read_b128 v[152:155], v224 offset:17408
	ds_read_b128 v[156:159], v224 offset:18432
	ds_read_b128 v[160:163], v224 offset:19456
	ds_read_b128 v[164:167], v224 offset:20480
	ds_read_b128 v[168:171], v224 offset:21504
	ds_read_b128 v[172:175], v224 offset:22528
	ds_read_b128 v[176:179], v224 offset:23552
	s_add_i32 s52, s52, s30
	v_lshl_add_u64 v[206:207], s[20:21], 0, v[2:3]
	s_mov_b32 m0, s52
	s_nop 0
	global_load_lds_dwordx4 v[206:207], off
	v_lshl_add_u64 v[208:209], s[20:21], 0, v[192:193]
	s_add_i32 m0, s52, 0x2000
	s_nop 0
	global_load_lds_dwordx4 v[208:209], off
	s_mov_b32 m0, s31
	v_lshl_add_u64 v[210:211], s[24:25], 0, v[196:197]
	global_load_lds_dwordx4 v[210:211], off
	v_lshl_add_u64 v[212:213], s[24:25], 0, v[194:195]
	s_mov_b32 m0, s35
	s_nop 0
	global_load_lds_dwordx4 v[212:213], off
	s_add_u32 s52, s20, 0x80000
	s_addc_u32 s53, s21, 0
	s_add_i32 s54, s54, s30
	s_mov_b32 m0, s54
	s_nop 0
	global_load_lds_dwordx4 v2, s[52:53]
	s_add_i32 m0, s54, 0x2000
	s_nop 0
	global_load_lds_dwordx4 v192, s[52:53]
	s_waitcnt lgkmcnt(0)
	s_waitcnt vmcnt(6)
	s_setprio 1
	s_barrier
; #define PG8_STAGE(bufoff, gbase, voff) do { _Pragma("unroll") for (int _i = 0; _i < 2; ++_i) \
;         __builtin_amdgcn_global_load_lds((const unsigned*)((const char*)(gbase) + (voff)[_i]), (LAS unsigned*)(lds + (bufoff) + ldsw + _i * 8192), 16, 0, 0); } while (0)
; #define PG8_LDA(dst, b, h) do { _Pragma("unroll") for (int m = 0; m < 4; ++m) _Pragma("unroll") for (int k = 0; k < 2; ++k) dst[m][k] = *(const LAS bf16x8*)(lds + PG8_SA(b, h) + aoff + m * 2048 + k * 1024); } while (0)
; #define PG8_LDB(dst, b, h) do { _Pragma("unroll") for (int n = 0; n < 2; ++n) _Pragma("unroll") for (int k = 0; k < 2; ++k) dst[n][k] = *(const LAS bf16x8*)(lds + PG8_SB(b, h) + boff + n * 2048 + k * 1024); } while (0)
; #define PG8_MMA(ai, bj, At, Bt) do { __builtin_amdgcn_s_setprio(1); _Pragma("unroll") for (int m = 0; m < 4; ++m) _Pragma("unroll") for (int n = 0; n < 2; ++n) _Pragma("unroll") for (int k = 0; k < 2; ++k) \
;         acc[ai][bj][m][n] = __builtin_amdgcn_mfma_f32_16x16x32_bf16(Bt[n][k], At[m][k], acc[ai][bj][m][n], 0, 0, 0); __builtin_amdgcn_s_setprio(0); } while (0)
; #define PG8_WAIT_V(n) asm volatile("s_waitcnt vmcnt(" #n ")" ::: "memory")
; #define PG8_WAIT_L(n) asm volatile("s_waitcnt lgkmcnt(" #n ")" ::: "memory")
; template <class Epi, class Sched>
; __device__ __forceinline__ void gemm_phase(LAS unsigned char* lds, const Gemm g, const Sched& S, const Epi& E) {
;     ...
;             PG8_WAIT_L(8); PG8_BAR; PG8_WAIT_L(0); PG8_MMA(0, 0, At, B0); PG8_BAR; PG8_SCHED;
;             PG8_LDB(B1, 0, 1); PG8_STAGE(PG8_SB(0, 0), b2, voffB);
;             PG8_BAR; PG8_WAIT_L(0); PG8_MMA(0, 1, At, B1); PG8_BAR;
;             PG8_LDA(At, 0, 1); PG8_STAGE(PG8_SA(0, 0), a2, voffA);
;             PG8_BAR; PG8_WAIT_L(0); PG8_MMA(1, 0, At, B0); PG8_BAR; PG8_SCHED;
;             PG8_STAGE(PG8_SB(0, 1), b2 + hstepB, voffB);
;             PG8_WAIT_V(6); PG8_BAR; PG8_MMA(1, 1, At, B1); PG8_BAR;
;             PG8_LDB(B0, 1, 0); PG8_SCHED; PG8_LDA(At, 1, 0); PG8_STAGE(PG8_SA(0, 1), a2 + hstepA, voffA);
;             PG8_WAIT_L(8); PG8_BAR; PG8_WAIT_L(0); PG8_MMA(0, 0, At, B0); PG8_BAR; PG8_SCHED;
;             PG8_LDB(B1, 1, 1); PG8_STAGE(PG8_SB(1, 0), b3, voffB);
;             PG8_BAR; PG8_WAIT_L(0); PG8_MMA(0, 1, At, B1); PG8_BAR;
;             PG8_LDA(At, 1, 1); PG8_STAGE(PG8_SA(1, 0), a3, voffA);
;             PG8_BAR; PG8_WAIT_L(0); PG8_MMA(1, 0, At, B0); PG8_BAR; PG8_SCHED;
	v_mfma_f32_16x16x32_bf16 v[64:67], v[132:135], v[148:151], v[64:67]
	v_mfma_f32_16x16x32_bf16 v[60:63], v[140:143], v[148:151], v[60:63]
	v_mfma_f32_16x16x32_bf16 v[52:55], v[132:135], v[156:159], v[52:55]
	v_mfma_f32_16x16x32_bf16 v[44:47], v[140:143], v[156:159], v[44:47]
	v_mfma_f32_16x16x32_bf16 v[36:39], v[132:135], v[164:167], v[36:39]
	v_mfma_f32_16x16x32_bf16 v[28:31], v[140:143], v[164:167], v[28:31]
	v_mfma_f32_16x16x32_bf16 v[20:23], v[132:135], v[172:175], v[20:23]
	v_mfma_f32_16x16x32_bf16 v[12:15], v[140:143], v[172:175], v[12:15]
	v_mfma_f32_16x16x32_bf16 v[64:67], v[136:139], v[152:155], v[64:67]
	v_mfma_f32_16x16x32_bf16 v[60:63], v[144:147], v[152:155], v[60:63]
	v_mfma_f32_16x16x32_bf16 v[52:55], v[136:139], v[160:163], v[52:55]
	v_mfma_f32_16x16x32_bf16 v[44:47], v[144:147], v[160:163], v[44:47]
	v_mfma_f32_16x16x32_bf16 v[36:39], v[136:139], v[168:171], v[36:39]
	v_mfma_f32_16x16x32_bf16 v[28:31], v[144:147], v[168:171], v[28:31]
	v_mfma_f32_16x16x32_bf16 v[20:23], v[136:139], v[176:179], v[20:23]
	v_mfma_f32_16x16x32_bf16 v[12:15], v[144:147], v[176:179], v[12:15]
	v_mfma_f32_16x16x32_bf16 v[56:59], v[180:183], v[148:151], v[56:59]
	v_mfma_f32_16x16x32_bf16 v[48:51], v[188:191], v[148:151], v[48:51]
	v_mfma_f32_16x16x32_bf16 v[40:43], v[180:183], v[156:159], v[40:43]
	v_mfma_f32_16x16x32_bf16 v[32:35], v[188:191], v[156:159], v[32:35]
	v_mfma_f32_16x16x32_bf16 v[24:27], v[180:183], v[164:167], v[24:27]
	v_mfma_f32_16x16x32_bf16 v[16:19], v[188:191], v[164:167], v[16:19]
	v_mfma_f32_16x16x32_bf16 v[8:11], v[180:183], v[172:175], v[8:11]
	v_mfma_f32_16x16x32_bf16 v[4:7], v[188:191], v[172:175], v[4:7]
	v_mfma_f32_16x16x32_bf16 v[56:59], v[184:187], v[152:155], v[56:59]
	v_mfma_f32_16x16x32_bf16 v[48:51], v[202:205], v[152:155], v[48:51]
	v_mfma_f32_16x16x32_bf16 v[40:43], v[184:187], v[160:163], v[40:43]
	v_mfma_f32_16x16x32_bf16 v[32:35], v[202:205], v[160:163], v[32:35]
	v_mfma_f32_16x16x32_bf16 v[24:27], v[184:187], v[168:171], v[24:27]
	v_mfma_f32_16x16x32_bf16 v[16:19], v[202:205], v[168:171], v[16:19]
	v_mfma_f32_16x16x32_bf16 v[8:11], v[184:187], v[176:179], v[8:11]
	v_mfma_f32_16x16x32_bf16 v[4:7], v[202:205], v[176:179], v[4:7]
	s_barrier
	s_setprio 0
	s_add_i32 s52, 0, 0x18000
	v_add_u32_e32 v144, s52, v1
	ds_read_b128 v[132:135], v144
	ds_read_b128 v[136:139], v144 offset:1024
	ds_read_b128 v[140:143], v144 offset:2048
	ds_read_b128 v[144:147], v144 offset:3072
	s_add_u32 s24, s24, 0x80000
	s_addc_u32 s25, s25, 0
	ds_read_b128 v[148:151], v224 offset:32768
	ds_read_b128 v[152:155], v224 offset:33792
	ds_read_b128 v[156:159], v224 offset:34816
	ds_read_b128 v[160:163], v224 offset:35840
	ds_read_b128 v[164:167], v224 offset:36864
	ds_read_b128 v[168:171], v224 offset:37888
	ds_read_b128 v[172:175], v224 offset:38912
	ds_read_b128 v[176:179], v224 offset:39936
	s_mov_b32 m0, s36
	s_nop 0
	global_load_lds_dwordx4 v196, s[24:25]
	s_mov_b32 m0, s37
	s_nop 0
	global_load_lds_dwordx4 v194, s[24:25]
	s_add_i32 s24, 0, 0x1c000
	v_add_u32_e32 v202, s24, v1
	ds_read_b128 v[180:183], v202
	ds_read_b128 v[184:187], v202 offset:1024
	ds_read_b128 v[188:191], v202 offset:2048
	ds_read_b128 v[202:205], v202 offset:3072
	s_waitcnt lgkmcnt(0)
	s_setprio 1
	s_barrier
	v_mfma_f32_16x16x32_bf16 v[128:131], v[132:135], v[148:151], v[128:131]
	v_mfma_f32_16x16x32_bf16 v[124:127], v[140:143], v[148:151], v[124:127]
	v_mfma_f32_16x16x32_bf16 v[112:115], v[132:135], v[156:159], v[112:115]
	v_mfma_f32_16x16x32_bf16 v[108:111], v[140:143], v[156:159], v[108:111]
	v_mfma_f32_16x16x32_bf16 v[100:103], v[132:135], v[164:167], v[100:103]
	v_mfma_f32_16x16x32_bf16 v[92:95], v[140:143], v[164:167], v[92:95]
	v_mfma_f32_16x16x32_bf16 v[84:87], v[132:135], v[172:175], v[84:87]
	v_mfma_f32_16x16x32_bf16 v[76:79], v[140:143], v[172:175], v[76:79]
	v_mfma_f32_16x16x32_bf16 v[128:131], v[136:139], v[152:155], v[128:131]
	v_mfma_f32_16x16x32_bf16 v[124:127], v[144:147], v[152:155], v[124:127]
	v_mfma_f32_16x16x32_bf16 v[112:115], v[136:139], v[160:163], v[112:115]
	v_mfma_f32_16x16x32_bf16 v[108:111], v[144:147], v[160:163], v[108:111]
	v_mfma_f32_16x16x32_bf16 v[100:103], v[136:139], v[168:171], v[100:103]
	v_mfma_f32_16x16x32_bf16 v[92:95], v[144:147], v[168:171], v[92:95]
	v_mfma_f32_16x16x32_bf16 v[84:87], v[136:139], v[176:179], v[84:87]
	v_mfma_f32_16x16x32_bf16 v[76:79], v[144:147], v[176:179], v[76:79]
	v_mfma_f32_16x16x32_bf16 v[120:123], v[180:183], v[148:151], v[120:123]
	v_mfma_f32_16x16x32_bf16 v[116:119], v[188:191], v[148:151], v[116:119]
	v_mfma_f32_16x16x32_bf16 v[104:107], v[180:183], v[156:159], v[104:107]
	v_mfma_f32_16x16x32_bf16 v[96:99], v[188:191], v[156:159], v[96:99]
	v_mfma_f32_16x16x32_bf16 v[88:91], v[180:183], v[164:167], v[88:91]
	v_mfma_f32_16x16x32_bf16 v[80:83], v[188:191], v[164:167], v[80:83]
	v_mfma_f32_16x16x32_bf16 v[72:75], v[180:183], v[172:175], v[72:75]
	v_mfma_f32_16x16x32_bf16 v[68:71], v[188:191], v[172:175], v[68:71]
	v_mfma_f32_16x16x32_bf16 v[120:123], v[184:187], v[152:155], v[120:123]
	v_mfma_f32_16x16x32_bf16 v[116:119], v[202:205], v[152:155], v[116:119]
	v_mfma_f32_16x16x32_bf16 v[104:107], v[184:187], v[160:163], v[104:107]
	v_mfma_f32_16x16x32_bf16 v[96:99], v[202:205], v[160:163], v[96:99]
	v_mfma_f32_16x16x32_bf16 v[88:91], v[184:187], v[168:171], v[88:91]
	v_mfma_f32_16x16x32_bf16 v[80:83], v[202:205], v[168:171], v[80:83]
	v_mfma_f32_16x16x32_bf16 v[72:75], v[184:187], v[176:179], v[72:75]
	v_mfma_f32_16x16x32_bf16 v[68:71], v[202:205], v[176:179], v[68:71]
	s_barrier
; __device__ __forceinline__ int opaque_tid() { int t = threadIdx.x; asm volatile("" : "+v"(t)); return t; }
; #define PG8_STAGE(bufoff, gbase, voff) do { _Pragma("unroll") for (int _i = 0; _i < 2; ++_i) \
;         __builtin_amdgcn_global_load_lds((const unsigned*)((const char*)(gbase) + (voff)[_i]), (LAS unsigned*)(lds + (bufoff) + ldsw + _i * 8192), 16, 0, 0); } while (0)
; #define PG8_LDA(dst, b, h) do { _Pragma("unroll") for (int m = 0; m < 4; ++m) _Pragma("unroll") for (int k = 0; k < 2; ++k) dst[m][k] = *(const LAS bf16x8*)(lds + PG8_SA(b, h) + aoff + m * 2048 + k * 1024); } while (0)
; #define PG8_LDB(dst, b, h) do { _Pragma("unroll") for (int n = 0; n < 2; ++n) _Pragma("unroll") for (int k = 0; k < 2; ++k) dst[n][k] = *(const LAS bf16x8*)(lds + PG8_SB(b, h) + boff + n * 2048 + k * 1024); } while (0)
; #define PG8_WAIT_V(n) asm volatile("s_waitcnt vmcnt(" #n ")" ::: "memory")
; #define PG8_BAR __builtin_amdgcn_s_barrier()
;     __device__ __forceinline__ void operator()(const f32x4 (&acc)[2][2][4][2], const Unit& u, int wr, int wc, int, int) const {
;         const int ol_ = opaque_tid() & 63, fr = ol_ & 15, fq = ol_ >> 4;
;         const int row0 = u.pm * BM + wr * 64 + fr, col0 = u.pn * BM + wc * 32 + 8 * fq;
;         u32x4 cin[2][4][2];
; #pragma unroll
;         for (int ai = 0; ai < 2; ++ai)
; #pragma unroll
;             for (int m = 0; m < 4; ++m)
; #pragma unroll
;                 for (int bj = 0; bj < 2; ++bj) cin[ai][m][bj] = *(const u32x4*)(C + (size_t)(row0 + ai * HALF + m * 16) * ldc + col0 + bj * HALF);
; template <class Epi, class Sched>
; __device__ __forceinline__ void gemm_phase(LAS unsigned char* lds, const Gemm g, const Sched& S, const Epi& E) {
;     ...
;             PG8_WAIT_V(6); PG8_BAR; PG8_MMA(1, 1, At, B1); PG8_BAR;
;             PG8_LDB(B0, 1, 0); PG8_SCHED; PG8_LDA(At, 1, 0); PG8_STAGE(PG8_SA(0, 1), a2 + hstepA, voffA);
;             PG8_WAIT_L(8); PG8_BAR; PG8_WAIT_L(0); PG8_MMA(0, 0, At, B0); PG8_BAR; PG8_SCHED;
;             PG8_LDB(B1, 1, 1); PG8_STAGE(PG8_SB(1, 0), b3, voffB);
;             PG8_BAR; PG8_WAIT_L(0); PG8_MMA(0, 1, At, B1); PG8_BAR;
;             PG8_LDA(At, 1, 1); PG8_STAGE(PG8_SA(1, 0), a3, voffA);
;             PG8_BAR; PG8_WAIT_L(0); PG8_MMA(1, 0, At, B0); PG8_BAR; PG8_SCHED;
;             PG8_STAGE(PG8_SB(1, 1), b3 + hstepB, voffB);
;             PG8_WAIT_V(6); PG8_BAR; PG8_MMA(1, 1, At, B1); PG8_BAR;
	s_setprio 0
	ds_read_b128 v[148:151], v224 offset:49152
	ds_read_b128 v[152:155], v224 offset:50176
	ds_read_b128 v[156:159], v224 offset:51200
	ds_read_b128 v[160:163], v224 offset:52224
	ds_read_b128 v[164:167], v224 offset:53248
	ds_read_b128 v[168:171], v224 offset:54272
	ds_read_b128 v[172:175], v224 offset:55296
	ds_read_b128 v[176:179], v224 offset:56320
	s_add_i32 s25, s52, s30
	v_lshl_add_u64 v[206:207], v[206:207], 0, s[8:9]
	s_mov_b32 m0, s25
	s_nop 0
	global_load_lds_dwordx4 v[206:207], off
	v_lshl_add_u64 v[206:207], v[208:209], 0, s[8:9]
	s_add_i32 m0, s25, 0x2000
	s_nop 0
	global_load_lds_dwordx4 v[206:207], off
	s_mov_b32 m0, s42
	v_lshl_add_u64 v[206:207], v[210:211], 0, s[8:9]
	global_load_lds_dwordx4 v[206:207], off
	v_lshl_add_u64 v[206:207], v[212:213], 0, s[8:9]
	s_mov_b32 m0, s43
	s_nop 0
	global_load_lds_dwordx4 v[206:207], off
	s_add_u32 s20, s20, 0x80080
	s_addc_u32 s21, s21, 0
	s_add_i32 s24, s24, s30
	s_mov_b32 m0, s24
	s_nop 0
	global_load_lds_dwordx4 v2, s[20:21]
	s_add_i32 m0, s24, 0x2000
	s_nop 0
	global_load_lds_dwordx4 v192, s[20:21]
	s_add_i32 s51, s51, 2
	s_add_u32 s6, s6, 0x100
	s_addc_u32 s7, s7, 0
	s_add_u32 s49, s49, 0x100
	s_addc_u32 s50, s50, 0
	s_cmp_gt_u32 s51, 29
	s_waitcnt lgkmcnt(0)
	s_waitcnt vmcnt(6)
	s_setprio 1
	s_barrier
	v_mfma_f32_16x16x32_bf16 v[64:67], v[132:135], v[148:151], v[64:67]
	v_mfma_f32_16x16x32_bf16 v[60:63], v[140:143], v[148:151], v[60:63]
	v_mfma_f32_16x16x32_bf16 v[52:55], v[132:135], v[156:159], v[52:55]
	v_mfma_f32_16x16x32_bf16 v[44:47], v[140:143], v[156:159], v[44:47]
	v_mfma_f32_16x16x32_bf16 v[36:39], v[132:135], v[164:167], v[36:39]
	v_mfma_f32_16x16x32_bf16 v[28:31], v[140:143], v[164:167], v[28:31]
	v_mfma_f32_16x16x32_bf16 v[20:23], v[132:135], v[172:175], v[20:23]
	v_mfma_f32_16x16x32_bf16 v[12:15], v[140:143], v[172:175], v[12:15]
	v_mfma_f32_16x16x32_bf16 v[64:67], v[136:139], v[152:155], v[64:67]
	v_mfma_f32_16x16x32_bf16 v[60:63], v[144:147], v[152:155], v[60:63]
	v_mfma_f32_16x16x32_bf16 v[52:55], v[136:139], v[160:163], v[52:55]
	v_mfma_f32_16x16x32_bf16 v[44:47], v[144:147], v[160:163], v[44:47]
	v_mfma_f32_16x16x32_bf16 v[36:39], v[136:139], v[168:171], v[36:39]
	v_mfma_f32_16x16x32_bf16 v[28:31], v[144:147], v[168:171], v[28:31]
	v_mfma_f32_16x16x32_bf16 v[20:23], v[136:139], v[176:179], v[20:23]
	v_mfma_f32_16x16x32_bf16 v[12:15], v[144:147], v[176:179], v[12:15]
	v_mfma_f32_16x16x32_bf16 v[56:59], v[180:183], v[148:151], v[56:59]
	v_mfma_f32_16x16x32_bf16 v[48:51], v[188:191], v[148:151], v[48:51]
	v_mfma_f32_16x16x32_bf16 v[40:43], v[180:183], v[156:159], v[40:43]
	v_mfma_f32_16x16x32_bf16 v[32:35], v[188:191], v[156:159], v[32:35]
	v_mfma_f32_16x16x32_bf16 v[24:27], v[180:183], v[164:167], v[24:27]
	v_mfma_f32_16x16x32_bf16 v[16:19], v[188:191], v[164:167], v[16:19]
	v_mfma_f32_16x16x32_bf16 v[8:11], v[180:183], v[172:175], v[8:11]
	v_mfma_f32_16x16x32_bf16 v[4:7], v[188:191], v[172:175], v[4:7]
	v_mfma_f32_16x16x32_bf16 v[56:59], v[184:187], v[152:155], v[56:59]
	v_mfma_f32_16x16x32_bf16 v[48:51], v[202:205], v[152:155], v[48:51]
	v_mfma_f32_16x16x32_bf16 v[40:43], v[184:187], v[160:163], v[40:43]
	v_mfma_f32_16x16x32_bf16 v[32:35], v[202:205], v[160:163], v[32:35]
	v_mfma_f32_16x16x32_bf16 v[24:27], v[184:187], v[168:171], v[24:27]
	v_mfma_f32_16x16x32_bf16 v[16:19], v[202:205], v[168:171], v[16:19]
	v_mfma_f32_16x16x32_bf16 v[8:11], v[184:187], v[176:179], v[8:11]
	v_mfma_f32_16x16x32_bf16 v[4:7], v[202:205], v[176:179], v[4:7]
	s_barrier
	s_cbranch_scc0 .LBB0_1396
	s_setprio 0
	v_mov_b32_e32 v133, v0
	s_lshl_b32 s1, s46, 8
	s_add_i32 s1, s1, s38
	v_and_or_b32 v132, v133, 15, s1
	s_lshl_b32 s1, s45, 8
	v_lshrrev_b32_e32 v133, 1, v133
	v_and_or_b32 v133, v133, 24, s1
	v_or_b32_e32 v134, s39, v133
	v_ashrrev_i32_e32 v135, 31, v134
	v_lshlrev_b64 v[202:203], 1, v[134:135]
	v_ashrrev_i32_e32 v133, 31, v132
	v_lshl_add_u64 v[134:135], s[88:89], 0, v[202:203]
	v_lshlrev_b64 v[216:217], 12, v[132:133]
	v_lshl_add_u64 v[136:137], v[134:135], 0, v[216:217]
	global_load_dwordx4 v[226:229], v[136:137], off
	global_load_dwordx4 v[188:191], v[136:137], off offset:256
	v_or_b32_e32 v136, 16, v132
	v_ashrrev_i32_e32 v137, 31, v136
	v_lshlrev_b64 v[222:223], 12, v[136:137]
	v_lshl_add_u64 v[136:137], v[134:135], 0, v[222:223]
	global_load_dwordx4 v[184:187], v[136:137], off
	global_load_dwordx4 v[180:183], v[136:137], off offset:256
	v_or_b32_e32 v136, 32, v132
	v_ashrrev_i32_e32 v137, 31, v136
	v_lshlrev_b64 v[220:221], 12, v[136:137]
	v_lshl_add_u64 v[136:137], v[134:135], 0, v[220:221]
	global_load_dwordx4 v[176:179], v[136:137], off
	global_load_dwordx4 v[168:171], v[136:137], off offset:256
	v_or_b32_e32 v132, 48, v132
	v_ashrrev_i32_e32 v133, 31, v132
	v_lshlrev_b64 v[212:213], 12, v[132:133]
	v_lshl_add_u64 v[132:133], v[134:135], 0, v[212:213]
	global_load_dwordx4 v[172:175], v[132:133], off
	global_load_dwordx4 v[164:167], v[132:133], off offset:256
	s_mov_b64 s[6:7], 0x80000
	v_lshl_add_u64 v[210:211], v[216:217], 0, s[6:7]
	v_lshl_add_u64 v[132:133], v[134:135], 0, v[210:211]
	global_load_dwordx4 v[160:163], v[132:133], off
	global_load_dwordx4 v[156:159], v[132:133], off offset:256
	s_mov_b64 s[6:7], 0x90000
	v_lshl_add_u64 v[208:209], v[216:217], 0, s[6:7]
	v_lshl_add_u64 v[132:133], v[134:135], 0, v[208:209]
	global_load_dwordx4 v[152:155], v[132:133], off
	global_load_dwordx4 v[148:151], v[132:133], off offset:256
	s_mov_b64 s[6:7], 0xa0000
	v_lshl_add_u64 v[206:207], v[216:217], 0, s[6:7]
	v_lshl_add_u64 v[132:133], v[134:135], 0, v[206:207]
	global_load_dwordx4 v[144:147], v[132:133], off
	global_load_dwordx4 v[140:143], v[132:133], off offset:256
	s_mov_b64 s[6:7], 0xb0000
	v_lshl_add_u64 v[204:205], v[216:217], 0, s[6:7]
	v_lshl_add_u64 v[132:133], v[134:135], 0, v[204:205]
	global_load_dwordx4 v[136:139], v[132:133], off
	s_nop 0
	global_load_dwordx4 v[132:135], v[132:133], off offset:256
	s_and_b64 vcc, exec, s[40:41]
	s_mov_b32 s45, s0
	s_mov_b32 s46, s14
	s_mov_b64 s[20:21], s[18:19]
	s_mov_b64 s[6:7], s[4:5]
	s_waitcnt vmcnt(15)
; __device__ __forceinline__ unsigned cvt_pk_bf16(float lo, float hi) { const f32x2 v = {lo, hi}; const bf16v2_ r = __builtin_convertvector(v, bf16v2_); return __builtin_bit_cast(unsigned, r); }
; __device__ __forceinline__ float bflo(unsigned w) { return __uint_as_float(w << 16); }
; __device__ __forceinline__ float bfhi(unsigned w) { return __uint_as_float(w & 0xffff0000u); }
;     __device__ __forceinline__ void operator()(const f32x4 (&acc)[2][2][4][2], const Unit& u, int wr, int wc, int, int) const {
;     ...
;         for (int ai = 0; ai < 2; ++ai)
; #pragma unroll
;             for (int m = 0; m < 4; ++m)
; #pragma unroll
;                 for (int bj = 0; bj < 2; ++bj) { const u32x4 c = cin[ai][m][bj]; const f32x4 v0 = acc[ai][bj][m][0], v1 = acc[ai][bj][m][1];
;                     u32x4 w; w.x = cvt_pk_bf16(bflo(c.x) + v0[0], bfhi(c.x) + v0[1]); w.y = cvt_pk_bf16(bflo(c.y) + v0[2], bfhi(c.y) + v0[3]);
;                     w.z = cvt_pk_bf16(bflo(c.z) + v1[0], bfhi(c.z) + v1[1]); w.w = cvt_pk_bf16(bflo(c.w) + v1[2], bfhi(c.w) + v1[3]);
;                     *(u32x4*)(C + (size_t)(row0 + ai * HALF + m * 16) * ldc + col0 + bj * HALF) = w; }
	v_lshlrev_b32_e32 v218, 16, v226
	v_and_b32_e32 v219, 0xffff0000, v226
	v_pk_add_f32 v[128:129], v[128:129], v[218:219]
	v_lshlrev_b32_e32 v218, 16, v227
	v_and_b32_e32 v219, 0xffff0000, v227
	v_pk_add_f32 v[130:131], v[130:131], v[218:219]
	v_cvt_pk_bf16_f32 v128, v128, v129
	v_cvt_pk_bf16_f32 v129, v130, v131
	v_lshlrev_b32_e32 v130, 16, v228
	v_and_b32_e32 v131, 0xffff0000, v228
	v_pk_add_f32 v[124:125], v[124:125], v[130:131]
	s_nop 0
	v_cvt_pk_bf16_f32 v130, v124, v125
	v_lshlrev_b32_e32 v124, 16, v229
	v_and_b32_e32 v125, 0xffff0000, v229
	v_pk_add_f32 v[124:125], v[126:127], v[124:125]
	s_waitcnt vmcnt(14)
	v_lshlrev_b32_e32 v126, 16, v188
	v_and_b32_e32 v127, 0xffff0000, v188
	v_pk_add_f32 v[120:121], v[120:121], v[126:127]
	v_lshlrev_b32_e32 v126, 16, v189
	v_and_b32_e32 v127, 0xffff0000, v189
	v_pk_add_f32 v[122:123], v[122:123], v[126:127]
	v_cvt_pk_bf16_f32 v120, v120, v121
	v_cvt_pk_bf16_f32 v121, v122, v123
	v_lshlrev_b32_e32 v122, 16, v190
	v_and_b32_e32 v123, 0xffff0000, v190
	v_pk_add_f32 v[116:117], v[116:117], v[122:123]
	v_cvt_pk_bf16_f32 v131, v124, v125
	v_cvt_pk_bf16_f32 v122, v116, v117
	v_lshlrev_b32_e32 v116, 16, v191
	v_and_b32_e32 v117, 0xffff0000, v191
	v_pk_add_f32 v[116:117], v[118:119], v[116:117]
	v_lshl_add_u64 v[124:125], s[88:89], 0, v[216:217]
	v_cvt_pk_bf16_f32 v123, v116, v117
	s_waitcnt vmcnt(13)
	v_lshlrev_b32_e32 v116, 16, v184
	v_and_b32_e32 v117, 0xffff0000, v184
	v_pk_add_f32 v[112:113], v[112:113], v[116:117]
	v_lshlrev_b32_e32 v116, 16, v185
	v_and_b32_e32 v117, 0xffff0000, v185
	v_pk_add_f32 v[114:115], v[114:115], v[116:117]
	v_cvt_pk_bf16_f32 v112, v112, v113
	v_cvt_pk_bf16_f32 v113, v114, v115
	v_lshlrev_b32_e32 v114, 16, v186
	v_and_b32_e32 v115, 0xffff0000, v186
	v_pk_add_f32 v[108:109], v[108:109], v[114:115]
	v_lshl_add_u64 v[124:125], v[124:125], 0, v[202:203]
	v_cvt_pk_bf16_f32 v114, v108, v109
	v_lshlrev_b32_e32 v108, 16, v187
	v_and_b32_e32 v109, 0xffff0000, v187
	v_pk_add_f32 v[108:109], v[110:111], v[108:109]
	s_waitcnt vmcnt(12)
	v_lshlrev_b32_e32 v110, 16, v180
	v_and_b32_e32 v111, 0xffff0000, v180
	v_pk_add_f32 v[104:105], v[104:105], v[110:111]
	v_lshlrev_b32_e32 v110, 16, v181
	v_and_b32_e32 v111, 0xffff0000, v181
	v_pk_add_f32 v[106:107], v[106:107], v[110:111]
	v_cvt_pk_bf16_f32 v104, v104, v105
	v_cvt_pk_bf16_f32 v105, v106, v107
	v_lshlrev_b32_e32 v106, 16, v182
	v_and_b32_e32 v107, 0xffff0000, v182
	v_pk_add_f32 v[96:97], v[96:97], v[106:107]
	v_cvt_pk_bf16_f32 v115, v108, v109
	v_cvt_pk_bf16_f32 v106, v96, v97
	v_lshlrev_b32_e32 v96, 16, v183
	v_and_b32_e32 v97, 0xffff0000, v183
	v_pk_add_f32 v[96:97], v[98:99], v[96:97]
	s_waitcnt vmcnt(11)
	v_lshlrev_b32_e32 v98, 16, v177
	v_cvt_pk_bf16_f32 v107, v96, v97
	v_lshlrev_b32_e32 v96, 16, v176
	v_and_b32_e32 v97, 0xffff0000, v176
	v_and_b32_e32 v99, 0xffff0000, v177
	v_pk_add_f32 v[96:97], v[100:101], v[96:97]
	v_pk_add_f32 v[98:99], v[102:103], v[98:99]
	v_cvt_pk_bf16_f32 v96, v96, v97
	v_cvt_pk_bf16_f32 v97, v98, v99
	v_lshlrev_b32_e32 v98, 16, v178
	v_and_b32_e32 v99, 0xffff0000, v178
	v_pk_add_f32 v[92:93], v[92:93], v[98:99]
	v_lshl_add_u64 v[108:109], s[88:89], 0, v[222:223]
	v_cvt_pk_bf16_f32 v98, v92, v93
	v_lshlrev_b32_e32 v92, 16, v179
	v_and_b32_e32 v93, 0xffff0000, v179
	v_pk_add_f32 v[92:93], v[94:95], v[92:93]
	s_waitcnt vmcnt(10)
	v_lshlrev_b32_e32 v94, 16, v168
	v_and_b32_e32 v95, 0xffff0000, v168
	v_pk_add_f32 v[88:89], v[88:89], v[94:95]
	v_lshlrev_b32_e32 v94, 16, v169
	v_and_b32_e32 v95, 0xffff0000, v169
	v_pk_add_f32 v[90:91], v[90:91], v[94:95]
	v_cvt_pk_bf16_f32 v88, v88, v89
	v_cvt_pk_bf16_f32 v89, v90, v91
	v_lshlrev_b32_e32 v90, 16, v170
	v_and_b32_e32 v91, 0xffff0000, v170
	v_pk_add_f32 v[80:81], v[80:81], v[90:91]
	v_cvt_pk_bf16_f32 v99, v92, v93
	v_cvt_pk_bf16_f32 v90, v80, v81
	v_lshlrev_b32_e32 v80, 16, v171
	v_and_b32_e32 v81, 0xffff0000, v171
	v_pk_add_f32 v[80:81], v[82:83], v[80:81]
	s_waitcnt vmcnt(9)
	v_lshlrev_b32_e32 v82, 16, v173
	v_cvt_pk_bf16_f32 v91, v80, v81
	v_lshlrev_b32_e32 v80, 16, v172
	v_and_b32_e32 v81, 0xffff0000, v172
	v_and_b32_e32 v83, 0xffff0000, v173
	v_pk_add_f32 v[80:81], v[84:85], v[80:81]
	v_pk_add_f32 v[82:83], v[86:87], v[82:83]
	v_cvt_pk_bf16_f32 v80, v80, v81
	v_cvt_pk_bf16_f32 v81, v82, v83
	v_lshlrev_b32_e32 v82, 16, v174
	v_and_b32_e32 v83, 0xffff0000, v174
	v_pk_add_f32 v[76:77], v[76:77], v[82:83]
	v_lshl_add_u64 v[92:93], s[88:89], 0, v[220:221]
	v_cvt_pk_bf16_f32 v82, v76, v77
	v_lshlrev_b32_e32 v76, 16, v175
	v_and_b32_e32 v77, 0xffff0000, v175
	v_pk_add_f32 v[76:77], v[78:79], v[76:77]
	s_waitcnt vmcnt(8)
	v_lshlrev_b32_e32 v78, 16, v164
	v_and_b32_e32 v79, 0xffff0000, v164
	v_pk_add_f32 v[72:73], v[72:73], v[78:79]
	v_lshlrev_b32_e32 v78, 16, v165
	v_and_b32_e32 v79, 0xffff0000, v165
	v_pk_add_f32 v[74:75], v[74:75], v[78:79]
	v_cvt_pk_bf16_f32 v72, v72, v73
	v_cvt_pk_bf16_f32 v73, v74, v75
	v_lshlrev_b32_e32 v74, 16, v166
	v_and_b32_e32 v75, 0xffff0000, v166
	v_pk_add_f32 v[68:69], v[68:69], v[74:75]
	v_cvt_pk_bf16_f32 v83, v76, v77
	v_cvt_pk_bf16_f32 v74, v68, v69
	v_lshlrev_b32_e32 v68, 16, v167
	v_and_b32_e32 v69, 0xffff0000, v167
	v_pk_add_f32 v[68:69], v[70:71], v[68:69]
	v_lshl_add_u64 v[76:77], s[88:89], 0, v[212:213]
	v_cvt_pk_bf16_f32 v75, v68, v69
	s_waitcnt vmcnt(7)
	v_lshlrev_b32_e32 v68, 16, v160
	v_and_b32_e32 v69, 0xffff0000, v160
	v_pk_add_f32 v[64:65], v[64:65], v[68:69]
	v_lshlrev_b32_e32 v68, 16, v161
	v_and_b32_e32 v69, 0xffff0000, v161
	v_pk_add_f32 v[66:67], v[66:67], v[68:69]
	v_cvt_pk_bf16_f32 v64, v64, v65
	v_cvt_pk_bf16_f32 v65, v66, v67
	v_lshlrev_b32_e32 v66, 16, v162
	v_and_b32_e32 v67, 0xffff0000, v162
	v_pk_add_f32 v[60:61], v[60:61], v[66:67]
	v_lshl_add_u64 v[108:109], v[108:109], 0, v[202:203]
	v_cvt_pk_bf16_f32 v66, v60, v61
	v_lshlrev_b32_e32 v60, 16, v163
	v_and_b32_e32 v61, 0xffff0000, v163
	v_pk_add_f32 v[60:61], v[62:63], v[60:61]
	s_waitcnt vmcnt(6)
; __device__ __forceinline__ unsigned cvt_pk_bf16(float lo, float hi) { const f32x2 v = {lo, hi}; const bf16v2_ r = __builtin_convertvector(v, bf16v2_); return __builtin_bit_cast(unsigned, r); }
; __device__ __forceinline__ float bflo(unsigned w) { return __uint_as_float(w << 16); }
; __device__ __forceinline__ float bfhi(unsigned w) { return __uint_as_float(w & 0xffff0000u); }
;     __device__ __forceinline__ void operator()(const f32x4 (&acc)[2][2][4][2], const Unit& u, int wr, int wc, int, int) const {
;     ...
;         for (int ai = 0; ai < 2; ++ai)
; #pragma unroll
;             for (int m = 0; m < 4; ++m)
; #pragma unroll
;                 for (int bj = 0; bj < 2; ++bj) { const u32x4 c = cin[ai][m][bj]; const f32x4 v0 = acc[ai][bj][m][0], v1 = acc[ai][bj][m][1];
;                     u32x4 w; w.x = cvt_pk_bf16(bflo(c.x) + v0[0], bfhi(c.x) + v0[1]); w.y = cvt_pk_bf16(bflo(c.y) + v0[2], bfhi(c.y) + v0[3]);
;                     w.z = cvt_pk_bf16(bflo(c.z) + v1[0], bfhi(c.z) + v1[1]); w.w = cvt_pk_bf16(bflo(c.w) + v1[2], bfhi(c.w) + v1[3]);
;                     *(u32x4*)(C + (size_t)(row0 + ai * HALF + m * 16) * ldc + col0 + bj * HALF) = w; }
	v_lshlrev_b32_e32 v62, 16, v156
	v_and_b32_e32 v63, 0xffff0000, v156
	v_pk_add_f32 v[56:57], v[56:57], v[62:63]
	v_lshlrev_b32_e32 v62, 16, v157
	v_and_b32_e32 v63, 0xffff0000, v157
	v_pk_add_f32 v[58:59], v[58:59], v[62:63]
	v_cvt_pk_bf16_f32 v56, v56, v57
	v_cvt_pk_bf16_f32 v57, v58, v59
	v_lshlrev_b32_e32 v58, 16, v158
	v_and_b32_e32 v59, 0xffff0000, v158
	v_pk_add_f32 v[48:49], v[48:49], v[58:59]
	v_cvt_pk_bf16_f32 v67, v60, v61
	v_cvt_pk_bf16_f32 v58, v48, v49
	v_lshlrev_b32_e32 v48, 16, v159
	v_and_b32_e32 v49, 0xffff0000, v159
	v_pk_add_f32 v[48:49], v[50:51], v[48:49]
	s_waitcnt vmcnt(5)
	v_lshlrev_b32_e32 v50, 16, v153
	v_cvt_pk_bf16_f32 v59, v48, v49
	v_lshlrev_b32_e32 v48, 16, v152
	v_and_b32_e32 v49, 0xffff0000, v152
	v_and_b32_e32 v51, 0xffff0000, v153
	v_pk_add_f32 v[48:49], v[52:53], v[48:49]
	v_pk_add_f32 v[50:51], v[54:55], v[50:51]
	v_cvt_pk_bf16_f32 v48, v48, v49
	v_cvt_pk_bf16_f32 v49, v50, v51
	v_lshlrev_b32_e32 v50, 16, v154
	v_and_b32_e32 v51, 0xffff0000, v154
	v_pk_add_f32 v[44:45], v[44:45], v[50:51]
	v_lshl_add_u64 v[60:61], s[88:89], 0, v[210:211]
	v_cvt_pk_bf16_f32 v50, v44, v45
	v_lshlrev_b32_e32 v44, 16, v155
	v_and_b32_e32 v45, 0xffff0000, v155
	v_pk_add_f32 v[44:45], v[46:47], v[44:45]
	s_waitcnt vmcnt(4)
	v_lshlrev_b32_e32 v46, 16, v148
	v_and_b32_e32 v47, 0xffff0000, v148
	v_pk_add_f32 v[40:41], v[40:41], v[46:47]
	v_lshlrev_b32_e32 v46, 16, v149
	v_and_b32_e32 v47, 0xffff0000, v149
	v_pk_add_f32 v[42:43], v[42:43], v[46:47]
	v_cvt_pk_bf16_f32 v40, v40, v41
	v_cvt_pk_bf16_f32 v41, v42, v43
	v_lshlrev_b32_e32 v42, 16, v150
	v_and_b32_e32 v43, 0xffff0000, v150
	v_pk_add_f32 v[32:33], v[32:33], v[42:43]
	v_cvt_pk_bf16_f32 v51, v44, v45
	v_cvt_pk_bf16_f32 v42, v32, v33
	v_lshlrev_b32_e32 v32, 16, v151
	v_and_b32_e32 v33, 0xffff0000, v151
	v_pk_add_f32 v[32:33], v[34:35], v[32:33]
	s_waitcnt vmcnt(3)
	v_lshlrev_b32_e32 v34, 16, v145
	v_cvt_pk_bf16_f32 v43, v32, v33
	v_lshlrev_b32_e32 v32, 16, v144
	v_and_b32_e32 v33, 0xffff0000, v144
	v_and_b32_e32 v35, 0xffff0000, v145
	v_pk_add_f32 v[32:33], v[36:37], v[32:33]
	v_pk_add_f32 v[34:35], v[38:39], v[34:35]
	v_cvt_pk_bf16_f32 v32, v32, v33
	v_cvt_pk_bf16_f32 v33, v34, v35
	v_lshlrev_b32_e32 v34, 16, v146
	v_and_b32_e32 v35, 0xffff0000, v146
	v_pk_add_f32 v[28:29], v[28:29], v[34:35]
	v_lshl_add_u64 v[44:45], s[88:89], 0, v[208:209]
	v_cvt_pk_bf16_f32 v34, v28, v29
	v_lshlrev_b32_e32 v28, 16, v147
	v_and_b32_e32 v29, 0xffff0000, v147
	v_pk_add_f32 v[28:29], v[30:31], v[28:29]
	s_waitcnt vmcnt(2)
	v_lshlrev_b32_e32 v30, 16, v140
	v_and_b32_e32 v31, 0xffff0000, v140
	v_pk_add_f32 v[24:25], v[24:25], v[30:31]
	v_lshlrev_b32_e32 v30, 16, v141
	v_and_b32_e32 v31, 0xffff0000, v141
	v_pk_add_f32 v[26:27], v[26:27], v[30:31]
	v_cvt_pk_bf16_f32 v24, v24, v25
	v_cvt_pk_bf16_f32 v25, v26, v27
	v_lshlrev_b32_e32 v26, 16, v142
	v_and_b32_e32 v27, 0xffff0000, v142
	v_pk_add_f32 v[16:17], v[16:17], v[26:27]
	v_cvt_pk_bf16_f32 v35, v28, v29
	v_cvt_pk_bf16_f32 v26, v16, v17
	v_lshlrev_b32_e32 v16, 16, v143
	v_and_b32_e32 v17, 0xffff0000, v143
	v_pk_add_f32 v[16:17], v[18:19], v[16:17]
	s_waitcnt vmcnt(1)
	v_lshlrev_b32_e32 v18, 16, v137
	v_cvt_pk_bf16_f32 v27, v16, v17
	v_lshlrev_b32_e32 v16, 16, v136
	v_and_b32_e32 v17, 0xffff0000, v136
	v_and_b32_e32 v19, 0xffff0000, v137
	v_pk_add_f32 v[16:17], v[20:21], v[16:17]
	v_pk_add_f32 v[18:19], v[22:23], v[18:19]
	v_cvt_pk_bf16_f32 v16, v16, v17
	v_cvt_pk_bf16_f32 v17, v18, v19
	v_lshlrev_b32_e32 v18, 16, v138
	v_and_b32_e32 v19, 0xffff0000, v138
	v_pk_add_f32 v[12:13], v[12:13], v[18:19]
	v_lshl_add_u64 v[28:29], s[88:89], 0, v[206:207]
	v_cvt_pk_bf16_f32 v18, v12, v13
	v_lshlrev_b32_e32 v12, 16, v139
	v_and_b32_e32 v13, 0xffff0000, v139
	v_pk_add_f32 v[12:13], v[14:15], v[12:13]
	s_waitcnt vmcnt(0)
; __device__ __forceinline__ unsigned cvt_pk_bf16(float lo, float hi) { const f32x2 v = {lo, hi}; const bf16v2_ r = __builtin_convertvector(v, bf16v2_); return __builtin_bit_cast(unsigned, r); }
; __device__ __forceinline__ float bflo(unsigned w) { return __uint_as_float(w << 16); }
; __device__ __forceinline__ float bfhi(unsigned w) { return __uint_as_float(w & 0xffff0000u); }
; __device__ __forceinline__ float wave_sum(float v) { v = row16_sum(v); v += shx(v, 16); v += shx(v, 32); return v; }
;     __device__ __forceinline__ void operator()(const f32x4 (&acc)[2][2][4][2], const Unit& u, int wr, int wc, int, int) const {
;     ...
;         for (int ai = 0; ai < 2; ++ai)
; #pragma unroll
;             for (int m = 0; m < 4; ++m)
; #pragma unroll
;                 for (int bj = 0; bj < 2; ++bj) { const u32x4 c = cin[ai][m][bj]; const f32x4 v0 = acc[ai][bj][m][0], v1 = acc[ai][bj][m][1];
;                     u32x4 w; w.x = cvt_pk_bf16(bflo(c.x) + v0[0], bfhi(c.x) + v0[1]); w.y = cvt_pk_bf16(bflo(c.y) + v0[2], bfhi(c.y) + v0[3]);
;                     w.z = cvt_pk_bf16(bflo(c.z) + v1[0], bfhi(c.z) + v1[1]); w.w = cvt_pk_bf16(bflo(c.w) + v1[2], bfhi(c.w) + v1[3]);
;                     *(u32x4*)(C + (size_t)(row0 + ai * HALF + m * 16) * ldc + col0 + bj * HALF) = w; }
; __device__ __forceinline__ void rowstat_phase(const Frame& F, const bf16_t* __restrict__ res, float* __restrict__ rstd_out) {
;     ...
;         for (int r = 0; r < 4; ++r) { ss[r] = 0.f;
; #pragma unroll
;             for (int i = 0; i < 4; ++i) { const u32x4 x = v[r][i];
;                 ss[r] += bflo(x.x) * bflo(x.x) + bfhi(x.x) * bfhi(x.x) + bflo(x.y) * bflo(x.y) + bfhi(x.y) * bfhi(x.y) + bflo(x.z) * bflo(x.z) + bfhi(x.z) * bfhi(x.z) + bflo(x.w) * bflo(x.w) + bfhi(x.w) * bfhi(x.w); }
;             ss[r] = wave_sum(ss[r]); }
	v_lshlrev_b32_e32 v14, 16, v132
	v_and_b32_e32 v15, 0xffff0000, v132
	v_pk_add_f32 v[8:9], v[8:9], v[14:15]
	v_lshlrev_b32_e32 v14, 16, v133
	v_and_b32_e32 v15, 0xffff0000, v133
	v_pk_add_f32 v[10:11], v[10:11], v[14:15]
	v_cvt_pk_bf16_f32 v8, v8, v9
	v_cvt_pk_bf16_f32 v9, v10, v11
	v_lshlrev_b32_e32 v10, 16, v134
	v_and_b32_e32 v11, 0xffff0000, v134
	v_pk_add_f32 v[4:5], v[4:5], v[10:11]
	v_cvt_pk_bf16_f32 v19, v12, v13
	v_cvt_pk_bf16_f32 v10, v4, v5
	v_lshlrev_b32_e32 v4, 16, v135
	v_and_b32_e32 v5, 0xffff0000, v135
	v_lshl_add_u64 v[12:13], s[88:89], 0, v[204:205]
	v_pk_add_f32 v[4:5], v[6:7], v[4:5]
	v_lshl_add_u64 v[92:93], v[92:93], 0, v[202:203]
	v_lshl_add_u64 v[76:77], v[76:77], 0, v[202:203]
	v_lshl_add_u64 v[60:61], v[60:61], 0, v[202:203]
	v_lshl_add_u64 v[44:45], v[44:45], 0, v[202:203]
	v_lshl_add_u64 v[28:29], v[28:29], 0, v[202:203]
	v_lshl_add_u64 v[12:13], v[12:13], 0, v[202:203]
	v_cvt_pk_bf16_f32 v11, v4, v5
	global_store_dwordx4 v[124:125], v[128:131], off
	global_store_dwordx4 v[124:125], v[120:123], off offset:256
	global_store_dwordx4 v[108:109], v[112:115], off
	global_store_dwordx4 v[108:109], v[104:107], off offset:256
	global_store_dwordx4 v[92:93], v[96:99], off
	global_store_dwordx4 v[92:93], v[88:91], off offset:256
	global_store_dwordx4 v[76:77], v[80:83], off
	global_store_dwordx4 v[76:77], v[72:75], off offset:256
	global_store_dwordx4 v[60:61], v[64:67], off
	global_store_dwordx4 v[60:61], v[56:59], off offset:256
	global_store_dwordx4 v[44:45], v[48:51], off
	global_store_dwordx4 v[44:45], v[40:43], off offset:256
	global_store_dwordx4 v[28:29], v[32:35], off
	global_store_dwordx4 v[28:29], v[24:27], off offset:256
	global_store_dwordx4 v[12:13], v[16:19], off
	global_store_dwordx4 v[12:13], v[8:11], off offset:256
	v_subrev_u32_e32 v226, s88, v124
	v_bfe_u32 v227, v226, 4, 8
	v_lshrrev_b32_e32 v226, 12, v226
	v_and_b32_e32 v228, 15, v227
	v_lshrrev_b32_e32 v227, 5, v227
	v_lshl_or_b32 v227, v227, 4, v228
	v_lshlrev_b32_e32 v227, 10, v227
	v_and_b32_e32 v228, 15, v226
	v_and_b32_e32 v229, 0xc0, v226
	v_lshl_or_b32 v228, v228, 2, v229
	v_lshl_add_u32 v227, v228, 2, v227
	v_lshrrev_b32_e32 v226, 8, v226
	v_lshl_add_u32 v226, v226, 17, v227
	v_add_u32_e32 v226, 0x1e000000, v226
	v_mov_b32_e32 v188, 0
	v_dot2c_f32_bf16_e32 v188, v128, v128
	v_dot2c_f32_bf16_e32 v188, v129, v129
	v_dot2c_f32_bf16_e32 v188, v130, v130
	v_dot2c_f32_bf16_e32 v188, v131, v131
	v_dot2c_f32_bf16_e32 v188, v120, v120
	v_dot2c_f32_bf16_e32 v188, v121, v121
	v_dot2c_f32_bf16_e32 v188, v122, v122
	v_dot2c_f32_bf16_e32 v188, v123, v123
	v_mov_b32_e32 v189, 0
	v_dot2c_f32_bf16_e32 v189, v112, v112
	v_dot2c_f32_bf16_e32 v189, v113, v113
	v_dot2c_f32_bf16_e32 v189, v114, v114
	v_dot2c_f32_bf16_e32 v189, v115, v115
	v_dot2c_f32_bf16_e32 v189, v104, v104
	v_dot2c_f32_bf16_e32 v189, v105, v105
	v_dot2c_f32_bf16_e32 v189, v106, v106
	v_dot2c_f32_bf16_e32 v189, v107, v107
	v_mov_b32_e32 v190, 0
	v_dot2c_f32_bf16_e32 v190, v96, v96
	v_dot2c_f32_bf16_e32 v190, v97, v97
	v_dot2c_f32_bf16_e32 v190, v98, v98
	v_dot2c_f32_bf16_e32 v190, v99, v99
	v_dot2c_f32_bf16_e32 v190, v88, v88
	v_dot2c_f32_bf16_e32 v190, v89, v89
	v_dot2c_f32_bf16_e32 v190, v90, v90
	v_dot2c_f32_bf16_e32 v190, v91, v91
	v_mov_b32_e32 v191, 0
	v_dot2c_f32_bf16_e32 v191, v80, v80
	v_dot2c_f32_bf16_e32 v191, v81, v81
	v_dot2c_f32_bf16_e32 v191, v82, v82
	v_dot2c_f32_bf16_e32 v191, v83, v83
	v_dot2c_f32_bf16_e32 v191, v72, v72
	v_dot2c_f32_bf16_e32 v191, v73, v73
	v_dot2c_f32_bf16_e32 v191, v74, v74
	v_dot2c_f32_bf16_e32 v191, v75, v75
	s_nop 2
	global_store_dwordx4 v226, v[188:191], s[88:89]
	s_nop 1
	v_mov_b32_e32 v188, 0
	v_dot2c_f32_bf16_e32 v188, v64, v64
	v_dot2c_f32_bf16_e32 v188, v65, v65
	v_dot2c_f32_bf16_e32 v188, v66, v66
	v_dot2c_f32_bf16_e32 v188, v67, v67
	v_dot2c_f32_bf16_e32 v188, v56, v56
	v_dot2c_f32_bf16_e32 v188, v57, v57
	v_dot2c_f32_bf16_e32 v188, v58, v58
	v_dot2c_f32_bf16_e32 v188, v59, v59
	v_mov_b32_e32 v189, 0
	v_dot2c_f32_bf16_e32 v189, v48, v48
	v_dot2c_f32_bf16_e32 v189, v49, v49
	v_dot2c_f32_bf16_e32 v189, v50, v50
	v_dot2c_f32_bf16_e32 v189, v51, v51
	v_dot2c_f32_bf16_e32 v189, v40, v40
	v_dot2c_f32_bf16_e32 v189, v41, v41
	v_dot2c_f32_bf16_e32 v189, v42, v42
	v_dot2c_f32_bf16_e32 v189, v43, v43
	v_mov_b32_e32 v190, 0
	v_dot2c_f32_bf16_e32 v190, v32, v32
	v_dot2c_f32_bf16_e32 v190, v33, v33
	v_dot2c_f32_bf16_e32 v190, v34, v34
	v_dot2c_f32_bf16_e32 v190, v35, v35
	v_dot2c_f32_bf16_e32 v190, v24, v24
	v_dot2c_f32_bf16_e32 v190, v25, v25
	v_dot2c_f32_bf16_e32 v190, v26, v26
	v_dot2c_f32_bf16_e32 v190, v27, v27
	v_mov_b32_e32 v191, 0
	v_dot2c_f32_bf16_e32 v191, v16, v16
	v_dot2c_f32_bf16_e32 v191, v17, v17
	v_dot2c_f32_bf16_e32 v191, v18, v18
	v_dot2c_f32_bf16_e32 v191, v19, v19
	v_dot2c_f32_bf16_e32 v191, v8, v8
	v_dot2c_f32_bf16_e32 v191, v9, v9
	v_dot2c_f32_bf16_e32 v191, v10, v10
	v_dot2c_f32_bf16_e32 v191, v11, v11
	s_nop 2
	global_store_dwordx4 v226, v[188:191], s[88:89] offset:512
	s_nop 1
	s_cbranch_vccz .LBB0_1389
	s_waitcnt vmcnt(0)
	s_cmpk_gt_u32 s2, 0xff
	s_cbranch_scc1 .LBB0_1400
	s_barrier

; #define PG8_STAGE(bufoff, gbase, voff) do { _Pragma("unroll") for (int _i = 0; _i < 2; ++_i) \
;         __builtin_amdgcn_global_load_lds((const unsigned*)((const char*)(gbase) + (voff)[_i]), (LAS unsigned*)(lds + (bufoff) + ldsw + _i * 8192), 16, 0, 0); } while (0)
; #define PG8_LDA(dst, b, h) do { _Pragma("unroll") for (int m = 0; m < 4; ++m) _Pragma("unroll") for (int k = 0; k < 2; ++k) dst[m][k] = *(const LAS bf16x8*)(lds + PG8_SA(b, h) + aoff + m * 2048 + k * 1024); } while (0)
; #define PG8_LDB(dst, b, h) do { _Pragma("unroll") for (int n = 0; n < 2; ++n) _Pragma("unroll") for (int k = 0; k < 2; ++k) dst[n][k] = *(const LAS bf16x8*)(lds + PG8_SB(b, h) + boff + n * 2048 + k * 1024); } while (0)
; #define PG8_WAIT_V(n) asm volatile("s_waitcnt vmcnt(" #n ")" ::: "memory")
; #define PG8_WAIT_L(n) asm volatile("s_waitcnt lgkmcnt(" #n ")" ::: "memory")
; #define PG8_BAR __builtin_amdgcn_s_barrier()
; #define PG8_SCHED __builtin_amdgcn_sched_barrier(0)
; template <class Epi, class Sched>
; __device__ __forceinline__ void gemm_phase(LAS unsigned char* lds, const Gemm g, const Sched& S, const Epi& E) {
;     ...
;             PG8_LDB(B0, 0, 0); PG8_SCHED; PG8_LDA(At, 0, 0); PG8_STAGE(PG8_SA(1, 1), a1 + hstepA, voffA);
;             PG8_WAIT_L(8); PG8_BAR; PG8_WAIT_L(0); PG8_MMA(0, 0, At, B0); PG8_BAR; PG8_SCHED;
;             PG8_LDB(B1, 0, 1); PG8_STAGE(PG8_SB(0, 0), b2, voffB);
;             PG8_BAR; PG8_WAIT_L(0); PG8_MMA(0, 1, At, B1); PG8_BAR;
;             PG8_LDA(At, 0, 1); PG8_STAGE(PG8_SA(0, 0), a2, voffA);
;             PG8_BAR; PG8_WAIT_L(0); PG8_MMA(1, 0, At, B0); PG8_BAR; PG8_SCHED;
;             PG8_STAGE(PG8_SB(0, 1), b2 + hstepB, voffB);
;             PG8_WAIT_V(6); PG8_BAR; PG8_MMA(1, 1, At, B1); PG8_BAR;
;             PG8_LDB(B0, 1, 0); PG8_SCHED; PG8_LDA(At, 1, 0); PG8_STAGE(PG8_SA(0, 1), a2 + hstepA, voffA);
;             PG8_WAIT_L(8); PG8_BAR; PG8_WAIT_L(0); PG8_MMA(0, 0, At, B0); PG8_BAR; PG8_SCHED;
;             PG8_LDB(B1, 1, 1); PG8_STAGE(PG8_SB(1, 0), b3, voffB);
;             PG8_BAR; PG8_WAIT_L(0); PG8_MMA(0, 1, At, B1); PG8_BAR;
;             PG8_LDA(At, 1, 1); PG8_STAGE(PG8_SA(1, 0), a3, voffA);
;             PG8_BAR; PG8_WAIT_L(0); PG8_MMA(1, 0, At, B0); PG8_BAR; PG8_SCHED;
;             PG8_STAGE(PG8_SB(1, 1), b3 + hstepB, voffB);
;             PG8_WAIT_V(6); PG8_BAR; PG8_MMA(1, 1, At, B1); PG8_BAR;
.LBB0_1666:
	s_setprio 0
	s_add_u32 s14, s6, 0x100
	s_addc_u32 s15, s7, 0
	s_add_i32 s45, 0, 0x10000
	v_add_u32_e32 v144, s45, v1
	ds_read_b128 v[132:135], v144
	ds_read_b128 v[136:139], v144 offset:1024
	ds_read_b128 v[140:143], v144 offset:2048
	ds_read_b128 v[144:147], v144 offset:3072
	s_cmpk_eq_i32 s44, 0x54
	s_cselect_b32 s21, s1, s15
	s_cselect_b32 s20, s0, s14
	s_cselect_b32 s19, s5, s43
	s_cselect_b32 s18, s4, s42
	ds_read_b128 v[148:151], v224
	ds_read_b128 v[152:155], v224 offset:1024
	ds_read_b128 v[156:159], v224 offset:2048
	ds_read_b128 v[160:163], v224 offset:3072
	ds_read_b128 v[164:167], v224 offset:4096
	ds_read_b128 v[168:171], v224 offset:5120
	ds_read_b128 v[172:175], v224 offset:6144
	ds_read_b128 v[176:179], v224 offset:7168
	s_add_i32 s51, 0, 0x14000
	v_add_u32_e32 v202, s51, v1
	ds_read_b128 v[180:183], v202
	ds_read_b128 v[184:187], v202 offset:1024
	ds_read_b128 v[188:191], v202 offset:2048
	ds_read_b128 v[202:205], v202 offset:3072
	s_add_i32 m0, s29, 0xc000
	s_nop 0
	global_load_lds_dwordx4 v198, s[6:7]
	s_add_i32 m0, s29, 0xe000
	s_nop 0
	global_load_lds_dwordx4 v200, s[6:7]
	s_waitcnt lgkmcnt(0)
	s_setprio 1
	s_barrier
	v_mfma_f32_16x16x32_bf16 v[128:131], v[132:135], v[148:151], v[128:131]
	v_mfma_f32_16x16x32_bf16 v[124:127], v[140:143], v[148:151], v[124:127]
	v_mfma_f32_16x16x32_bf16 v[112:115], v[132:135], v[156:159], v[112:115]
	v_mfma_f32_16x16x32_bf16 v[108:111], v[140:143], v[156:159], v[108:111]
	v_mfma_f32_16x16x32_bf16 v[100:103], v[132:135], v[164:167], v[100:103]
	v_mfma_f32_16x16x32_bf16 v[92:95], v[140:143], v[164:167], v[92:95]
	v_mfma_f32_16x16x32_bf16 v[84:87], v[132:135], v[172:175], v[84:87]
	v_mfma_f32_16x16x32_bf16 v[76:79], v[140:143], v[172:175], v[76:79]
	v_mfma_f32_16x16x32_bf16 v[128:131], v[136:139], v[152:155], v[128:131]
	v_mfma_f32_16x16x32_bf16 v[124:127], v[144:147], v[152:155], v[124:127]
	v_mfma_f32_16x16x32_bf16 v[112:115], v[136:139], v[160:163], v[112:115]
	v_mfma_f32_16x16x32_bf16 v[108:111], v[144:147], v[160:163], v[108:111]
	v_mfma_f32_16x16x32_bf16 v[100:103], v[136:139], v[168:171], v[100:103]
	v_mfma_f32_16x16x32_bf16 v[92:95], v[144:147], v[168:171], v[92:95]
	v_mfma_f32_16x16x32_bf16 v[84:87], v[136:139], v[176:179], v[84:87]
	v_mfma_f32_16x16x32_bf16 v[76:79], v[144:147], v[176:179], v[76:79]
	v_mfma_f32_16x16x32_bf16 v[120:123], v[180:183], v[148:151], v[120:123]
	v_mfma_f32_16x16x32_bf16 v[116:119], v[188:191], v[148:151], v[116:119]
	v_mfma_f32_16x16x32_bf16 v[104:107], v[180:183], v[156:159], v[104:107]
	v_mfma_f32_16x16x32_bf16 v[96:99], v[188:191], v[156:159], v[96:99]
	v_mfma_f32_16x16x32_bf16 v[88:91], v[180:183], v[164:167], v[88:91]
	v_mfma_f32_16x16x32_bf16 v[80:83], v[188:191], v[164:167], v[80:83]
	v_mfma_f32_16x16x32_bf16 v[72:75], v[180:183], v[172:175], v[72:75]
	v_mfma_f32_16x16x32_bf16 v[68:71], v[188:191], v[172:175], v[68:71]
	v_mfma_f32_16x16x32_bf16 v[120:123], v[184:187], v[152:155], v[120:123]
	v_mfma_f32_16x16x32_bf16 v[116:119], v[202:205], v[152:155], v[116:119]
	v_mfma_f32_16x16x32_bf16 v[104:107], v[184:187], v[160:163], v[104:107]
	v_mfma_f32_16x16x32_bf16 v[96:99], v[202:205], v[160:163], v[96:99]
	v_mfma_f32_16x16x32_bf16 v[88:91], v[184:187], v[168:171], v[88:91]
	v_mfma_f32_16x16x32_bf16 v[80:83], v[202:205], v[168:171], v[80:83]
	v_mfma_f32_16x16x32_bf16 v[72:75], v[184:187], v[176:179], v[72:75]
	v_mfma_f32_16x16x32_bf16 v[68:71], v[202:205], v[176:179], v[68:71]
	s_barrier
	s_setprio 0
	ds_read_b128 v[148:151], v224 offset:16384
	ds_read_b128 v[152:155], v224 offset:17408
	ds_read_b128 v[156:159], v224 offset:18432
	ds_read_b128 v[160:163], v224 offset:19456
	ds_read_b128 v[164:167], v224 offset:20480
	ds_read_b128 v[168:171], v224 offset:21504
	ds_read_b128 v[172:175], v224 offset:22528
	ds_read_b128 v[176:179], v224 offset:23552
	s_add_i32 s6, s45, s28
	v_lshl_add_u64 v[206:207], s[18:19], 0, v[2:3]
	s_mov_b32 m0, s6
	s_nop 0
	global_load_lds_dwordx4 v[206:207], off
	v_lshl_add_u64 v[208:209], s[18:19], 0, v[192:193]
	s_add_i32 m0, s6, 0x2000
	s_nop 0
	global_load_lds_dwordx4 v[208:209], off
	s_mov_b32 m0, s29
	v_lshl_add_u64 v[210:211], s[20:21], 0, v[196:197]
	global_load_lds_dwordx4 v[210:211], off
	v_lshl_add_u64 v[212:213], s[20:21], 0, v[194:195]
	s_mov_b32 m0, s30
	s_nop 0
	global_load_lds_dwordx4 v[212:213], off
	s_add_u32 s6, s18, 0x160000
	s_addc_u32 s7, s19, 0
	s_add_i32 s45, s51, s28
	s_mov_b32 m0, s45
	s_nop 0
	global_load_lds_dwordx4 v2, s[6:7]
	s_add_i32 m0, s45, 0x2000
	s_nop 0
	global_load_lds_dwordx4 v192, s[6:7]
	s_waitcnt lgkmcnt(0)
	s_waitcnt vmcnt(6)
	s_setprio 1
	s_barrier
; #define PG8_STAGE(bufoff, gbase, voff) do { _Pragma("unroll") for (int _i = 0; _i < 2; ++_i) \
;         __builtin_amdgcn_global_load_lds((const unsigned*)((const char*)(gbase) + (voff)[_i]), (LAS unsigned*)(lds + (bufoff) + ldsw + _i * 8192), 16, 0, 0); } while (0)
; #define PG8_LDA(dst, b, h) do { _Pragma("unroll") for (int m = 0; m < 4; ++m) _Pragma("unroll") for (int k = 0; k < 2; ++k) dst[m][k] = *(const LAS bf16x8*)(lds + PG8_SA(b, h) + aoff + m * 2048 + k * 1024); } while (0)
; #define PG8_LDB(dst, b, h) do { _Pragma("unroll") for (int n = 0; n < 2; ++n) _Pragma("unroll") for (int k = 0; k < 2; ++k) dst[n][k] = *(const LAS bf16x8*)(lds + PG8_SB(b, h) + boff + n * 2048 + k * 1024); } while (0)
; #define PG8_MMA(ai, bj, At, Bt) do { __builtin_amdgcn_s_setprio(1); _Pragma("unroll") for (int m = 0; m < 4; ++m) _Pragma("unroll") for (int n = 0; n < 2; ++n) _Pragma("unroll") for (int k = 0; k < 2; ++k) \
;         acc[ai][bj][m][n] = __builtin_amdgcn_mfma_f32_16x16x32_bf16(Bt[n][k], At[m][k], acc[ai][bj][m][n], 0, 0, 0); __builtin_amdgcn_s_setprio(0); } while (0)
; #define PG8_WAIT_V(n) asm volatile("s_waitcnt vmcnt(" #n ")" ::: "memory")
; #define PG8_WAIT_L(n) asm volatile("s_waitcnt lgkmcnt(" #n ")" ::: "memory")
; template <class Epi, class Sched>
; __device__ __forceinline__ void gemm_phase(LAS unsigned char* lds, const Gemm g, const Sched& S, const Epi& E) {
;     ...
;             PG8_WAIT_L(8); PG8_BAR; PG8_WAIT_L(0); PG8_MMA(0, 0, At, B0); PG8_BAR; PG8_SCHED;
;             PG8_LDB(B1, 0, 1); PG8_STAGE(PG8_SB(0, 0), b2, voffB);
;             PG8_BAR; PG8_WAIT_L(0); PG8_MMA(0, 1, At, B1); PG8_BAR;
;             PG8_LDA(At, 0, 1); PG8_STAGE(PG8_SA(0, 0), a2, voffA);
;             PG8_BAR; PG8_WAIT_L(0); PG8_MMA(1, 0, At, B0); PG8_BAR; PG8_SCHED;
;             PG8_STAGE(PG8_SB(0, 1), b2 + hstepB, voffB);
;             PG8_WAIT_V(6); PG8_BAR; PG8_MMA(1, 1, At, B1); PG8_BAR;
;             PG8_LDB(B0, 1, 0); PG8_SCHED; PG8_LDA(At, 1, 0); PG8_STAGE(PG8_SA(0, 1), a2 + hstepA, voffA);
;             PG8_WAIT_L(8); PG8_BAR; PG8_WAIT_L(0); PG8_MMA(0, 0, At, B0); PG8_BAR; PG8_SCHED;
;             PG8_LDB(B1, 1, 1); PG8_STAGE(PG8_SB(1, 0), b3, voffB);
;             PG8_BAR; PG8_WAIT_L(0); PG8_MMA(0, 1, At, B1); PG8_BAR;
;             PG8_LDA(At, 1, 1); PG8_STAGE(PG8_SA(1, 0), a3, voffA);
;             PG8_BAR; PG8_WAIT_L(0); PG8_MMA(1, 0, At, B0); PG8_BAR; PG8_SCHED;
	v_mfma_f32_16x16x32_bf16 v[64:67], v[132:135], v[148:151], v[64:67]
	v_mfma_f32_16x16x32_bf16 v[60:63], v[140:143], v[148:151], v[60:63]
	v_mfma_f32_16x16x32_bf16 v[52:55], v[132:135], v[156:159], v[52:55]
	v_mfma_f32_16x16x32_bf16 v[44:47], v[140:143], v[156:159], v[44:47]
	v_mfma_f32_16x16x32_bf16 v[36:39], v[132:135], v[164:167], v[36:39]
	v_mfma_f32_16x16x32_bf16 v[28:31], v[140:143], v[164:167], v[28:31]
	v_mfma_f32_16x16x32_bf16 v[20:23], v[132:135], v[172:175], v[20:23]
	v_mfma_f32_16x16x32_bf16 v[12:15], v[140:143], v[172:175], v[12:15]
	v_mfma_f32_16x16x32_bf16 v[64:67], v[136:139], v[152:155], v[64:67]
	v_mfma_f32_16x16x32_bf16 v[60:63], v[144:147], v[152:155], v[60:63]
	v_mfma_f32_16x16x32_bf16 v[52:55], v[136:139], v[160:163], v[52:55]
	v_mfma_f32_16x16x32_bf16 v[44:47], v[144:147], v[160:163], v[44:47]
	v_mfma_f32_16x16x32_bf16 v[36:39], v[136:139], v[168:171], v[36:39]
	v_mfma_f32_16x16x32_bf16 v[28:31], v[144:147], v[168:171], v[28:31]
	v_mfma_f32_16x16x32_bf16 v[20:23], v[136:139], v[176:179], v[20:23]
	v_mfma_f32_16x16x32_bf16 v[12:15], v[144:147], v[176:179], v[12:15]
	v_mfma_f32_16x16x32_bf16 v[56:59], v[180:183], v[148:151], v[56:59]
	v_mfma_f32_16x16x32_bf16 v[48:51], v[188:191], v[148:151], v[48:51]
	v_mfma_f32_16x16x32_bf16 v[40:43], v[180:183], v[156:159], v[40:43]
	v_mfma_f32_16x16x32_bf16 v[32:35], v[188:191], v[156:159], v[32:35]
	v_mfma_f32_16x16x32_bf16 v[24:27], v[180:183], v[164:167], v[24:27]
	v_mfma_f32_16x16x32_bf16 v[16:19], v[188:191], v[164:167], v[16:19]
	v_mfma_f32_16x16x32_bf16 v[8:11], v[180:183], v[172:175], v[8:11]
	v_mfma_f32_16x16x32_bf16 v[4:7], v[188:191], v[172:175], v[4:7]
	v_mfma_f32_16x16x32_bf16 v[56:59], v[184:187], v[152:155], v[56:59]
	v_mfma_f32_16x16x32_bf16 v[48:51], v[202:205], v[152:155], v[48:51]
	v_mfma_f32_16x16x32_bf16 v[40:43], v[184:187], v[160:163], v[40:43]
	v_mfma_f32_16x16x32_bf16 v[32:35], v[202:205], v[160:163], v[32:35]
	v_mfma_f32_16x16x32_bf16 v[24:27], v[184:187], v[168:171], v[24:27]
	v_mfma_f32_16x16x32_bf16 v[16:19], v[202:205], v[168:171], v[16:19]
	v_mfma_f32_16x16x32_bf16 v[8:11], v[184:187], v[176:179], v[8:11]
	v_mfma_f32_16x16x32_bf16 v[4:7], v[202:205], v[176:179], v[4:7]
	s_barrier
	s_setprio 0
	s_add_i32 s45, 0, 0x18000
	v_add_u32_e32 v144, s45, v1
	ds_read_b128 v[132:135], v144
	ds_read_b128 v[136:139], v144 offset:1024
	ds_read_b128 v[140:143], v144 offset:2048
	ds_read_b128 v[144:147], v144 offset:3072
	s_add_u32 s6, s20, 0x160000
	s_addc_u32 s7, s21, 0
	ds_read_b128 v[148:151], v224 offset:32768
	ds_read_b128 v[152:155], v224 offset:33792
	ds_read_b128 v[156:159], v224 offset:34816
	ds_read_b128 v[160:163], v224 offset:35840
	ds_read_b128 v[164:167], v224 offset:36864
	ds_read_b128 v[168:171], v224 offset:37888
	ds_read_b128 v[172:175], v224 offset:38912
	ds_read_b128 v[176:179], v224 offset:39936
	s_mov_b32 m0, s31
	s_nop 0
	global_load_lds_dwordx4 v196, s[6:7]
	s_mov_b32 m0, s35
	s_nop 0
	global_load_lds_dwordx4 v194, s[6:7]
	s_add_i32 s20, 0, 0x1c000
	v_add_u32_e32 v202, s20, v1
	ds_read_b128 v[180:183], v202
	ds_read_b128 v[184:187], v202 offset:1024
	ds_read_b128 v[188:191], v202 offset:2048
	ds_read_b128 v[202:205], v202 offset:3072
	s_waitcnt lgkmcnt(0)
	s_setprio 1
	s_barrier
	v_mfma_f32_16x16x32_bf16 v[128:131], v[132:135], v[148:151], v[128:131]
	v_mfma_f32_16x16x32_bf16 v[124:127], v[140:143], v[148:151], v[124:127]
	v_mfma_f32_16x16x32_bf16 v[112:115], v[132:135], v[156:159], v[112:115]
	v_mfma_f32_16x16x32_bf16 v[108:111], v[140:143], v[156:159], v[108:111]
	v_mfma_f32_16x16x32_bf16 v[100:103], v[132:135], v[164:167], v[100:103]
	v_mfma_f32_16x16x32_bf16 v[92:95], v[140:143], v[164:167], v[92:95]
	v_mfma_f32_16x16x32_bf16 v[84:87], v[132:135], v[172:175], v[84:87]
	v_mfma_f32_16x16x32_bf16 v[76:79], v[140:143], v[172:175], v[76:79]
	v_mfma_f32_16x16x32_bf16 v[128:131], v[136:139], v[152:155], v[128:131]
	v_mfma_f32_16x16x32_bf16 v[124:127], v[144:147], v[152:155], v[124:127]
	v_mfma_f32_16x16x32_bf16 v[112:115], v[136:139], v[160:163], v[112:115]
	v_mfma_f32_16x16x32_bf16 v[108:111], v[144:147], v[160:163], v[108:111]
	v_mfma_f32_16x16x32_bf16 v[100:103], v[136:139], v[168:171], v[100:103]
	v_mfma_f32_16x16x32_bf16 v[92:95], v[144:147], v[168:171], v[92:95]
	v_mfma_f32_16x16x32_bf16 v[84:87], v[136:139], v[176:179], v[84:87]
	v_mfma_f32_16x16x32_bf16 v[76:79], v[144:147], v[176:179], v[76:79]
	v_mfma_f32_16x16x32_bf16 v[120:123], v[180:183], v[148:151], v[120:123]
	v_mfma_f32_16x16x32_bf16 v[116:119], v[188:191], v[148:151], v[116:119]
	v_mfma_f32_16x16x32_bf16 v[104:107], v[180:183], v[156:159], v[104:107]
	v_mfma_f32_16x16x32_bf16 v[96:99], v[188:191], v[156:159], v[96:99]
	v_mfma_f32_16x16x32_bf16 v[88:91], v[180:183], v[164:167], v[88:91]
	v_mfma_f32_16x16x32_bf16 v[80:83], v[188:191], v[164:167], v[80:83]
	v_mfma_f32_16x16x32_bf16 v[72:75], v[180:183], v[172:175], v[72:75]
	v_mfma_f32_16x16x32_bf16 v[68:71], v[188:191], v[172:175], v[68:71]
	v_mfma_f32_16x16x32_bf16 v[120:123], v[184:187], v[152:155], v[120:123]
	v_mfma_f32_16x16x32_bf16 v[116:119], v[202:205], v[152:155], v[116:119]
	v_mfma_f32_16x16x32_bf16 v[104:107], v[184:187], v[160:163], v[104:107]
	v_mfma_f32_16x16x32_bf16 v[96:99], v[202:205], v[160:163], v[96:99]
	v_mfma_f32_16x16x32_bf16 v[88:91], v[184:187], v[168:171], v[88:91]
	v_mfma_f32_16x16x32_bf16 v[80:83], v[202:205], v[168:171], v[80:83]
	v_mfma_f32_16x16x32_bf16 v[72:75], v[184:187], v[176:179], v[72:75]
	v_mfma_f32_16x16x32_bf16 v[68:71], v[202:205], v[176:179], v[68:71]
	s_barrier
; __device__ __forceinline__ int opaque_tid() { int t = threadIdx.x; asm volatile("" : "+v"(t)); return t; }
; #define PG8_STAGE(bufoff, gbase, voff) do { _Pragma("unroll") for (int _i = 0; _i < 2; ++_i) \
;         __builtin_amdgcn_global_load_lds((const unsigned*)((const char*)(gbase) + (voff)[_i]), (LAS unsigned*)(lds + (bufoff) + ldsw + _i * 8192), 16, 0, 0); } while (0)
; #define PG8_LDA(dst, b, h) do { _Pragma("unroll") for (int m = 0; m < 4; ++m) _Pragma("unroll") for (int k = 0; k < 2; ++k) dst[m][k] = *(const LAS bf16x8*)(lds + PG8_SA(b, h) + aoff + m * 2048 + k * 1024); } while (0)
; #define PG8_LDB(dst, b, h) do { _Pragma("unroll") for (int n = 0; n < 2; ++n) _Pragma("unroll") for (int k = 0; k < 2; ++k) dst[n][k] = *(const LAS bf16x8*)(lds + PG8_SB(b, h) + boff + n * 2048 + k * 1024); } while (0)
; #define PG8_WAIT_V(n) asm volatile("s_waitcnt vmcnt(" #n ")" ::: "memory")
; #define PG8_BAR __builtin_amdgcn_s_barrier()
;     __device__ __forceinline__ void operator()(const f32x4 (&acc)[2][2][4][2], const Unit& u, int wr, int wc, int, int) const {
;         const int ol_ = opaque_tid() & 63, fr = ol_ & 15, fq = ol_ >> 4;
;         const int row0 = u.pm * BM + wr * 64 + fr, col0 = u.pn * BM + wc * 32 + 8 * fq;
;         u32x4 cin[2][4][2];
; #pragma unroll
;         for (int ai = 0; ai < 2; ++ai)
; #pragma unroll
;             for (int m = 0; m < 4; ++m)
; #pragma unroll
;                 for (int bj = 0; bj < 2; ++bj) cin[ai][m][bj] = *(const u32x4*)(C + (size_t)(row0 + ai * HALF + m * 16) * ldc + col0 + bj * HALF);
; template <class Epi, class Sched>
; __device__ __forceinline__ void gemm_phase(LAS unsigned char* lds, const Gemm g, const Sched& S, const Epi& E) {
;     ...
;             PG8_WAIT_V(6); PG8_BAR; PG8_MMA(1, 1, At, B1); PG8_BAR;
;             PG8_LDB(B0, 1, 0); PG8_SCHED; PG8_LDA(At, 1, 0); PG8_STAGE(PG8_SA(0, 1), a2 + hstepA, voffA);
;             PG8_WAIT_L(8); PG8_BAR; PG8_WAIT_L(0); PG8_MMA(0, 0, At, B0); PG8_BAR; PG8_SCHED;
;             PG8_LDB(B1, 1, 1); PG8_STAGE(PG8_SB(1, 0), b3, voffB);
;             PG8_BAR; PG8_WAIT_L(0); PG8_MMA(0, 1, At, B1); PG8_BAR;
;             PG8_LDA(At, 1, 1); PG8_STAGE(PG8_SA(1, 0), a3, voffA);
;             PG8_BAR; PG8_WAIT_L(0); PG8_MMA(1, 0, At, B0); PG8_BAR; PG8_SCHED;
;             PG8_STAGE(PG8_SB(1, 1), b3 + hstepB, voffB);
;             PG8_WAIT_V(6); PG8_BAR; PG8_MMA(1, 1, At, B1); PG8_BAR;
	s_setprio 0
	ds_read_b128 v[148:151], v224 offset:49152
	ds_read_b128 v[152:155], v224 offset:50176
	ds_read_b128 v[156:159], v224 offset:51200
	ds_read_b128 v[160:163], v224 offset:52224
	ds_read_b128 v[164:167], v224 offset:53248
	ds_read_b128 v[168:171], v224 offset:54272
	ds_read_b128 v[172:175], v224 offset:55296
	ds_read_b128 v[176:179], v224 offset:56320
	s_add_i32 s6, s45, s28
	v_lshl_add_u64 v[206:207], v[206:207], 0, s[8:9]
	s_mov_b32 m0, s6
	s_nop 0
	global_load_lds_dwordx4 v[206:207], off
	v_lshl_add_u64 v[206:207], v[208:209], 0, s[8:9]
	s_add_i32 m0, s6, 0x2000
	s_nop 0
	global_load_lds_dwordx4 v[206:207], off
	s_mov_b32 m0, s38
	v_lshl_add_u64 v[206:207], v[210:211], 0, s[8:9]
	global_load_lds_dwordx4 v[206:207], off
	v_lshl_add_u64 v[206:207], v[212:213], 0, s[8:9]
	s_mov_b32 m0, s39
	s_nop 0
	global_load_lds_dwordx4 v[206:207], off
	s_add_u32 s6, s18, 0x160080
	s_addc_u32 s7, s19, 0
	s_add_i32 s18, s20, s28
	s_mov_b32 m0, s18
	s_nop 0
	global_load_lds_dwordx4 v2, s[6:7]
	s_add_i32 m0, s18, 0x2000
	s_nop 0
	global_load_lds_dwordx4 v192, s[6:7]
	s_add_i32 s44, s44, 2
	s_add_u32 s42, s42, 0x100
	s_addc_u32 s43, s43, 0
	s_cmpk_gt_u32 s44, 0x55
	s_mov_b64 s[6:7], s[14:15]
	s_waitcnt lgkmcnt(0)
	s_waitcnt vmcnt(6)
	s_setprio 1
	s_barrier
	v_mfma_f32_16x16x32_bf16 v[64:67], v[132:135], v[148:151], v[64:67]
	v_mfma_f32_16x16x32_bf16 v[60:63], v[140:143], v[148:151], v[60:63]
	v_mfma_f32_16x16x32_bf16 v[52:55], v[132:135], v[156:159], v[52:55]
	v_mfma_f32_16x16x32_bf16 v[44:47], v[140:143], v[156:159], v[44:47]
	v_mfma_f32_16x16x32_bf16 v[36:39], v[132:135], v[164:167], v[36:39]
	v_mfma_f32_16x16x32_bf16 v[28:31], v[140:143], v[164:167], v[28:31]
	v_mfma_f32_16x16x32_bf16 v[20:23], v[132:135], v[172:175], v[20:23]
	v_mfma_f32_16x16x32_bf16 v[12:15], v[140:143], v[172:175], v[12:15]
	v_mfma_f32_16x16x32_bf16 v[64:67], v[136:139], v[152:155], v[64:67]
	v_mfma_f32_16x16x32_bf16 v[60:63], v[144:147], v[152:155], v[60:63]
	v_mfma_f32_16x16x32_bf16 v[52:55], v[136:139], v[160:163], v[52:55]
	v_mfma_f32_16x16x32_bf16 v[44:47], v[144:147], v[160:163], v[44:47]
	v_mfma_f32_16x16x32_bf16 v[36:39], v[136:139], v[168:171], v[36:39]
	v_mfma_f32_16x16x32_bf16 v[28:31], v[144:147], v[168:171], v[28:31]
	v_mfma_f32_16x16x32_bf16 v[20:23], v[136:139], v[176:179], v[20:23]
	v_mfma_f32_16x16x32_bf16 v[12:15], v[144:147], v[176:179], v[12:15]
	v_mfma_f32_16x16x32_bf16 v[56:59], v[180:183], v[148:151], v[56:59]
	v_mfma_f32_16x16x32_bf16 v[48:51], v[188:191], v[148:151], v[48:51]
	v_mfma_f32_16x16x32_bf16 v[40:43], v[180:183], v[156:159], v[40:43]
	v_mfma_f32_16x16x32_bf16 v[32:35], v[188:191], v[156:159], v[32:35]
	v_mfma_f32_16x16x32_bf16 v[24:27], v[180:183], v[164:167], v[24:27]
	v_mfma_f32_16x16x32_bf16 v[16:19], v[188:191], v[164:167], v[16:19]
	v_mfma_f32_16x16x32_bf16 v[8:11], v[180:183], v[172:175], v[8:11]
	v_mfma_f32_16x16x32_bf16 v[4:7], v[188:191], v[172:175], v[4:7]
	v_mfma_f32_16x16x32_bf16 v[56:59], v[184:187], v[152:155], v[56:59]
	v_mfma_f32_16x16x32_bf16 v[48:51], v[202:205], v[152:155], v[48:51]
	v_mfma_f32_16x16x32_bf16 v[40:43], v[184:187], v[160:163], v[40:43]
	v_mfma_f32_16x16x32_bf16 v[32:35], v[202:205], v[160:163], v[32:35]
	v_mfma_f32_16x16x32_bf16 v[24:27], v[184:187], v[168:171], v[24:27]
	v_mfma_f32_16x16x32_bf16 v[16:19], v[202:205], v[168:171], v[16:19]
	v_mfma_f32_16x16x32_bf16 v[8:11], v[184:187], v[176:179], v[8:11]
	v_mfma_f32_16x16x32_bf16 v[4:7], v[202:205], v[176:179], v[4:7]
	s_barrier
	s_cbranch_scc0 .LBB0_1666
	s_setprio 0
	v_mov_b32_e32 v133, v0
	s_lshl_b32 s6, s50, 8
	s_add_i32 s6, s6, s36
	v_and_or_b32 v132, v133, 15, s6
	s_lshl_b32 s6, s49, 8
	v_lshrrev_b32_e32 v133, 1, v133
	v_and_or_b32 v133, v133, 24, s6
	v_or_b32_e32 v134, s37, v133
	v_ashrrev_i32_e32 v135, 31, v134
	v_lshlrev_b64 v[202:203], 1, v[134:135]
	v_ashrrev_i32_e32 v133, 31, v132
	v_lshl_add_u64 v[134:135], s[88:89], 0, v[202:203]
	v_lshlrev_b64 v[226:227], 12, v[132:133]
	v_lshl_add_u64 v[136:137], v[134:135], 0, v[226:227]
	global_load_dwordx4 v[216:219], v[136:137], off
	global_load_dwordx4 v[188:191], v[136:137], off offset:256
	v_or_b32_e32 v136, 16, v132
	v_ashrrev_i32_e32 v137, 31, v136
	v_lshlrev_b64 v[222:223], 12, v[136:137]
	v_lshl_add_u64 v[136:137], v[134:135], 0, v[222:223]
	global_load_dwordx4 v[184:187], v[136:137], off
	global_load_dwordx4 v[180:183], v[136:137], off offset:256
	v_or_b32_e32 v136, 32, v132
	v_ashrrev_i32_e32 v137, 31, v136
	v_lshlrev_b64 v[220:221], 12, v[136:137]
	v_lshl_add_u64 v[136:137], v[134:135], 0, v[220:221]
	global_load_dwordx4 v[176:179], v[136:137], off
	global_load_dwordx4 v[168:171], v[136:137], off offset:256
	v_or_b32_e32 v132, 48, v132
	v_ashrrev_i32_e32 v133, 31, v132
	v_lshlrev_b64 v[212:213], 12, v[132:133]
	v_lshl_add_u64 v[132:133], v[134:135], 0, v[212:213]
	global_load_dwordx4 v[172:175], v[132:133], off
	global_load_dwordx4 v[164:167], v[132:133], off offset:256
	s_mov_b64 s[6:7], 0x80000
	v_lshl_add_u64 v[210:211], v[226:227], 0, s[6:7]
	v_lshl_add_u64 v[132:133], v[134:135], 0, v[210:211]
	global_load_dwordx4 v[160:163], v[132:133], off
	global_load_dwordx4 v[156:159], v[132:133], off offset:256
	s_mov_b64 s[6:7], 0x90000
	v_lshl_add_u64 v[208:209], v[226:227], 0, s[6:7]
	v_lshl_add_u64 v[132:133], v[134:135], 0, v[208:209]
	global_load_dwordx4 v[152:155], v[132:133], off
	global_load_dwordx4 v[148:151], v[132:133], off offset:256
	s_mov_b64 s[6:7], 0xa0000
	v_lshl_add_u64 v[206:207], v[226:227], 0, s[6:7]
	v_lshl_add_u64 v[132:133], v[134:135], 0, v[206:207]
	global_load_dwordx4 v[144:147], v[132:133], off
	global_load_dwordx4 v[140:143], v[132:133], off offset:256
	s_mov_b64 s[6:7], 0xb0000
	v_lshl_add_u64 v[204:205], v[226:227], 0, s[6:7]
	v_lshl_add_u64 v[132:133], v[134:135], 0, v[204:205]
	global_load_dwordx4 v[136:139], v[132:133], off
	s_nop 0
	global_load_dwordx4 v[132:135], v[132:133], off offset:256
	s_and_b64 vcc, exec, s[40:41]
	s_mov_b32 s49, s47
	s_mov_b32 s50, s48
	s_mov_b64 s[14:15], s[4:5]
	s_mov_b64 s[6:7], s[0:1]
	s_waitcnt vmcnt(15)
; __device__ __forceinline__ unsigned cvt_pk_bf16(float lo, float hi) { const f32x2 v = {lo, hi}; const bf16v2_ r = __builtin_convertvector(v, bf16v2_); return __builtin_bit_cast(unsigned, r); }
; __device__ __forceinline__ float bflo(unsigned w) { return __uint_as_float(w << 16); }
; __device__ __forceinline__ float bfhi(unsigned w) { return __uint_as_float(w & 0xffff0000u); }
;     __device__ __forceinline__ void operator()(const f32x4 (&acc)[2][2][4][2], const Unit& u, int wr, int wc, int, int) const {
;     ...
;         for (int ai = 0; ai < 2; ++ai)
; #pragma unroll
;             for (int m = 0; m < 4; ++m)
; #pragma unroll
;                 for (int bj = 0; bj < 2; ++bj) { const u32x4 c = cin[ai][m][bj]; const f32x4 v0 = acc[ai][bj][m][0], v1 = acc[ai][bj][m][1];
;                     u32x4 w; w.x = cvt_pk_bf16(bflo(c.x) + v0[0], bfhi(c.x) + v0[1]); w.y = cvt_pk_bf16(bflo(c.y) + v0[2], bfhi(c.y) + v0[3]);
;                     w.z = cvt_pk_bf16(bflo(c.z) + v1[0], bfhi(c.z) + v1[1]); w.w = cvt_pk_bf16(bflo(c.w) + v1[2], bfhi(c.w) + v1[3]);
;                     *(u32x4*)(C + (size_t)(row0 + ai * HALF + m * 16) * ldc + col0 + bj * HALF) = w; }
	v_lshlrev_b32_e32 v228, 16, v216
	v_and_b32_e32 v229, 0xffff0000, v216
	v_lshlrev_b32_e32 v216, 16, v217
	v_and_b32_e32 v217, 0xffff0000, v217
	v_pk_add_f32 v[128:129], v[128:129], v[228:229]
	v_pk_add_f32 v[130:131], v[130:131], v[216:217]
	v_cvt_pk_bf16_f32 v128, v128, v129
	v_cvt_pk_bf16_f32 v129, v130, v131
	v_lshlrev_b32_e32 v130, 16, v218
	v_and_b32_e32 v131, 0xffff0000, v218
	v_pk_add_f32 v[124:125], v[124:125], v[130:131]
	s_nop 0
	v_cvt_pk_bf16_f32 v130, v124, v125
	v_lshlrev_b32_e32 v124, 16, v219
	v_and_b32_e32 v125, 0xffff0000, v219
	v_pk_add_f32 v[124:125], v[126:127], v[124:125]
	s_waitcnt vmcnt(14)
	v_lshlrev_b32_e32 v126, 16, v188
	v_and_b32_e32 v127, 0xffff0000, v188
	v_pk_add_f32 v[120:121], v[120:121], v[126:127]
	v_lshlrev_b32_e32 v126, 16, v189
	v_and_b32_e32 v127, 0xffff0000, v189
	v_pk_add_f32 v[122:123], v[122:123], v[126:127]
	v_cvt_pk_bf16_f32 v120, v120, v121
	v_cvt_pk_bf16_f32 v121, v122, v123
	v_lshlrev_b32_e32 v122, 16, v190
	v_and_b32_e32 v123, 0xffff0000, v190
	v_pk_add_f32 v[116:117], v[116:117], v[122:123]
	v_cvt_pk_bf16_f32 v131, v124, v125
	v_cvt_pk_bf16_f32 v122, v116, v117
	v_lshlrev_b32_e32 v116, 16, v191
	v_and_b32_e32 v117, 0xffff0000, v191
	v_pk_add_f32 v[116:117], v[118:119], v[116:117]
	v_lshl_add_u64 v[124:125], s[88:89], 0, v[226:227]
	v_cvt_pk_bf16_f32 v123, v116, v117
	s_waitcnt vmcnt(13)
	v_lshlrev_b32_e32 v116, 16, v184
	v_and_b32_e32 v117, 0xffff0000, v184
	v_pk_add_f32 v[112:113], v[112:113], v[116:117]
	v_lshlrev_b32_e32 v116, 16, v185
	v_and_b32_e32 v117, 0xffff0000, v185
	v_pk_add_f32 v[114:115], v[114:115], v[116:117]
	v_cvt_pk_bf16_f32 v112, v112, v113
	v_cvt_pk_bf16_f32 v113, v114, v115
	v_lshlrev_b32_e32 v114, 16, v186
	v_and_b32_e32 v115, 0xffff0000, v186
	v_pk_add_f32 v[108:109], v[108:109], v[114:115]
	v_lshl_add_u64 v[124:125], v[124:125], 0, v[202:203]
	v_cvt_pk_bf16_f32 v114, v108, v109
	v_lshlrev_b32_e32 v108, 16, v187
	v_and_b32_e32 v109, 0xffff0000, v187
	v_pk_add_f32 v[108:109], v[110:111], v[108:109]
	s_waitcnt vmcnt(12)
	v_lshlrev_b32_e32 v110, 16, v180
	v_and_b32_e32 v111, 0xffff0000, v180
	v_pk_add_f32 v[104:105], v[104:105], v[110:111]
	v_lshlrev_b32_e32 v110, 16, v181
	v_and_b32_e32 v111, 0xffff0000, v181
	v_pk_add_f32 v[106:107], v[106:107], v[110:111]
	v_cvt_pk_bf16_f32 v104, v104, v105
	v_cvt_pk_bf16_f32 v105, v106, v107
	v_lshlrev_b32_e32 v106, 16, v182
	v_and_b32_e32 v107, 0xffff0000, v182
	v_pk_add_f32 v[96:97], v[96:97], v[106:107]
	v_cvt_pk_bf16_f32 v115, v108, v109
	v_cvt_pk_bf16_f32 v106, v96, v97
	v_lshlrev_b32_e32 v96, 16, v183
	v_and_b32_e32 v97, 0xffff0000, v183
	v_pk_add_f32 v[96:97], v[98:99], v[96:97]
	s_waitcnt vmcnt(11)
	v_lshlrev_b32_e32 v98, 16, v177
	v_cvt_pk_bf16_f32 v107, v96, v97
	v_lshlrev_b32_e32 v96, 16, v176
	v_and_b32_e32 v97, 0xffff0000, v176
	v_and_b32_e32 v99, 0xffff0000, v177
	v_pk_add_f32 v[96:97], v[100:101], v[96:97]
	v_pk_add_f32 v[98:99], v[102:103], v[98:99]
	v_cvt_pk_bf16_f32 v96, v96, v97
	v_cvt_pk_bf16_f32 v97, v98, v99
	v_lshlrev_b32_e32 v98, 16, v178
	v_and_b32_e32 v99, 0xffff0000, v178
	v_pk_add_f32 v[92:93], v[92:93], v[98:99]
	v_lshl_add_u64 v[108:109], s[88:89], 0, v[222:223]
	v_cvt_pk_bf16_f32 v98, v92, v93
	v_lshlrev_b32_e32 v92, 16, v179
	v_and_b32_e32 v93, 0xffff0000, v179
	v_pk_add_f32 v[92:93], v[94:95], v[92:93]
	s_waitcnt vmcnt(10)
	v_lshlrev_b32_e32 v94, 16, v168
	v_and_b32_e32 v95, 0xffff0000, v168
	v_pk_add_f32 v[88:89], v[88:89], v[94:95]
	v_lshlrev_b32_e32 v94, 16, v169
	v_and_b32_e32 v95, 0xffff0000, v169
	v_pk_add_f32 v[90:91], v[90:91], v[94:95]
	v_cvt_pk_bf16_f32 v88, v88, v89
	v_cvt_pk_bf16_f32 v89, v90, v91
	v_lshlrev_b32_e32 v90, 16, v170
	v_and_b32_e32 v91, 0xffff0000, v170
	v_pk_add_f32 v[80:81], v[80:81], v[90:91]
	v_cvt_pk_bf16_f32 v99, v92, v93
	v_cvt_pk_bf16_f32 v90, v80, v81
	v_lshlrev_b32_e32 v80, 16, v171
	v_and_b32_e32 v81, 0xffff0000, v171
	v_pk_add_f32 v[80:81], v[82:83], v[80:81]
	s_waitcnt vmcnt(9)
	v_lshlrev_b32_e32 v82, 16, v173
	v_cvt_pk_bf16_f32 v91, v80, v81
	v_lshlrev_b32_e32 v80, 16, v172
	v_and_b32_e32 v81, 0xffff0000, v172
	v_and_b32_e32 v83, 0xffff0000, v173
	v_pk_add_f32 v[80:81], v[84:85], v[80:81]
	v_pk_add_f32 v[82:83], v[86:87], v[82:83]
	v_cvt_pk_bf16_f32 v80, v80, v81
	v_cvt_pk_bf16_f32 v81, v82, v83
	v_lshlrev_b32_e32 v82, 16, v174
	v_and_b32_e32 v83, 0xffff0000, v174
	v_pk_add_f32 v[76:77], v[76:77], v[82:83]
	v_lshl_add_u64 v[92:93], s[88:89], 0, v[220:221]
	v_cvt_pk_bf16_f32 v82, v76, v77
	v_lshlrev_b32_e32 v76, 16, v175
	v_and_b32_e32 v77, 0xffff0000, v175
	v_pk_add_f32 v[76:77], v[78:79], v[76:77]
	s_waitcnt vmcnt(8)
	v_lshlrev_b32_e32 v78, 16, v164
	v_and_b32_e32 v79, 0xffff0000, v164
	v_pk_add_f32 v[72:73], v[72:73], v[78:79]
	v_lshlrev_b32_e32 v78, 16, v165
	v_and_b32_e32 v79, 0xffff0000, v165
	v_pk_add_f32 v[74:75], v[74:75], v[78:79]
	v_cvt_pk_bf16_f32 v72, v72, v73
	v_cvt_pk_bf16_f32 v73, v74, v75
	v_lshlrev_b32_e32 v74, 16, v166
	v_and_b32_e32 v75, 0xffff0000, v166
	v_pk_add_f32 v[68:69], v[68:69], v[74:75]
	v_cvt_pk_bf16_f32 v83, v76, v77
	v_cvt_pk_bf16_f32 v74, v68, v69
	v_lshlrev_b32_e32 v68, 16, v167
	v_and_b32_e32 v69, 0xffff0000, v167
	v_pk_add_f32 v[68:69], v[70:71], v[68:69]
	v_lshl_add_u64 v[76:77], s[88:89], 0, v[212:213]
	v_cvt_pk_bf16_f32 v75, v68, v69
	s_waitcnt vmcnt(7)
	v_lshlrev_b32_e32 v68, 16, v160
	v_and_b32_e32 v69, 0xffff0000, v160
	v_pk_add_f32 v[64:65], v[64:65], v[68:69]
	v_lshlrev_b32_e32 v68, 16, v161
	v_and_b32_e32 v69, 0xffff0000, v161
	v_pk_add_f32 v[66:67], v[66:67], v[68:69]
	v_cvt_pk_bf16_f32 v64, v64, v65
	v_cvt_pk_bf16_f32 v65, v66, v67
	v_lshlrev_b32_e32 v66, 16, v162
	v_and_b32_e32 v67, 0xffff0000, v162
	v_pk_add_f32 v[60:61], v[60:61], v[66:67]
	v_lshl_add_u64 v[108:109], v[108:109], 0, v[202:203]
	v_cvt_pk_bf16_f32 v66, v60, v61
	v_lshlrev_b32_e32 v60, 16, v163
	v_and_b32_e32 v61, 0xffff0000, v163
	v_pk_add_f32 v[60:61], v[62:63], v[60:61]
	s_waitcnt vmcnt(6)
; __device__ __forceinline__ unsigned cvt_pk_bf16(float lo, float hi) { const f32x2 v = {lo, hi}; const bf16v2_ r = __builtin_convertvector(v, bf16v2_); return __builtin_bit_cast(unsigned, r); }
; __device__ __forceinline__ float bflo(unsigned w) { return __uint_as_float(w << 16); }
; __device__ __forceinline__ float bfhi(unsigned w) { return __uint_as_float(w & 0xffff0000u); }
;     __device__ __forceinline__ void operator()(const f32x4 (&acc)[2][2][4][2], const Unit& u, int wr, int wc, int, int) const {
;     ...
;         for (int ai = 0; ai < 2; ++ai)
; #pragma unroll
;             for (int m = 0; m < 4; ++m)
; #pragma unroll
;                 for (int bj = 0; bj < 2; ++bj) { const u32x4 c = cin[ai][m][bj]; const f32x4 v0 = acc[ai][bj][m][0], v1 = acc[ai][bj][m][1];
;                     u32x4 w; w.x = cvt_pk_bf16(bflo(c.x) + v0[0], bfhi(c.x) + v0[1]); w.y = cvt_pk_bf16(bflo(c.y) + v0[2], bfhi(c.y) + v0[3]);
;                     w.z = cvt_pk_bf16(bflo(c.z) + v1[0], bfhi(c.z) + v1[1]); w.w = cvt_pk_bf16(bflo(c.w) + v1[2], bfhi(c.w) + v1[3]);
;                     *(u32x4*)(C + (size_t)(row0 + ai * HALF + m * 16) * ldc + col0 + bj * HALF) = w; }
	v_lshlrev_b32_e32 v62, 16, v156
	v_and_b32_e32 v63, 0xffff0000, v156
	v_pk_add_f32 v[56:57], v[56:57], v[62:63]
	v_lshlrev_b32_e32 v62, 16, v157
	v_and_b32_e32 v63, 0xffff0000, v157
	v_pk_add_f32 v[58:59], v[58:59], v[62:63]
	v_cvt_pk_bf16_f32 v56, v56, v57
	v_cvt_pk_bf16_f32 v57, v58, v59
	v_lshlrev_b32_e32 v58, 16, v158
	v_and_b32_e32 v59, 0xffff0000, v158
	v_pk_add_f32 v[48:49], v[48:49], v[58:59]
	v_cvt_pk_bf16_f32 v67, v60, v61
	v_cvt_pk_bf16_f32 v58, v48, v49
	v_lshlrev_b32_e32 v48, 16, v159
	v_and_b32_e32 v49, 0xffff0000, v159
	v_pk_add_f32 v[48:49], v[50:51], v[48:49]
	s_waitcnt vmcnt(5)
	v_lshlrev_b32_e32 v50, 16, v153
	v_cvt_pk_bf16_f32 v59, v48, v49
	v_lshlrev_b32_e32 v48, 16, v152
	v_and_b32_e32 v49, 0xffff0000, v152
	v_and_b32_e32 v51, 0xffff0000, v153
	v_pk_add_f32 v[48:49], v[52:53], v[48:49]
	v_pk_add_f32 v[50:51], v[54:55], v[50:51]
	v_cvt_pk_bf16_f32 v48, v48, v49
	v_cvt_pk_bf16_f32 v49, v50, v51
	v_lshlrev_b32_e32 v50, 16, v154
	v_and_b32_e32 v51, 0xffff0000, v154
	v_pk_add_f32 v[44:45], v[44:45], v[50:51]
	v_lshl_add_u64 v[60:61], s[88:89], 0, v[210:211]
	v_cvt_pk_bf16_f32 v50, v44, v45
	v_lshlrev_b32_e32 v44, 16, v155
	v_and_b32_e32 v45, 0xffff0000, v155
	v_pk_add_f32 v[44:45], v[46:47], v[44:45]
	s_waitcnt vmcnt(4)
	v_lshlrev_b32_e32 v46, 16, v148
	v_and_b32_e32 v47, 0xffff0000, v148
	v_pk_add_f32 v[40:41], v[40:41], v[46:47]
	v_lshlrev_b32_e32 v46, 16, v149
	v_and_b32_e32 v47, 0xffff0000, v149
	v_pk_add_f32 v[42:43], v[42:43], v[46:47]
	v_cvt_pk_bf16_f32 v40, v40, v41
	v_cvt_pk_bf16_f32 v41, v42, v43
	v_lshlrev_b32_e32 v42, 16, v150
	v_and_b32_e32 v43, 0xffff0000, v150
	v_pk_add_f32 v[32:33], v[32:33], v[42:43]
	v_cvt_pk_bf16_f32 v51, v44, v45
	v_cvt_pk_bf16_f32 v42, v32, v33
	v_lshlrev_b32_e32 v32, 16, v151
	v_and_b32_e32 v33, 0xffff0000, v151
	v_pk_add_f32 v[32:33], v[34:35], v[32:33]
	s_waitcnt vmcnt(3)
	v_lshlrev_b32_e32 v34, 16, v145
	v_cvt_pk_bf16_f32 v43, v32, v33
	v_lshlrev_b32_e32 v32, 16, v144
	v_and_b32_e32 v33, 0xffff0000, v144
	v_and_b32_e32 v35, 0xffff0000, v145
	v_pk_add_f32 v[32:33], v[36:37], v[32:33]
	v_pk_add_f32 v[34:35], v[38:39], v[34:35]
	v_cvt_pk_bf16_f32 v32, v32, v33
	v_cvt_pk_bf16_f32 v33, v34, v35
	v_lshlrev_b32_e32 v34, 16, v146
	v_and_b32_e32 v35, 0xffff0000, v146
	v_pk_add_f32 v[28:29], v[28:29], v[34:35]
	v_lshl_add_u64 v[44:45], s[88:89], 0, v[208:209]
	v_cvt_pk_bf16_f32 v34, v28, v29
	v_lshlrev_b32_e32 v28, 16, v147
	v_and_b32_e32 v29, 0xffff0000, v147
	v_pk_add_f32 v[28:29], v[30:31], v[28:29]
	s_waitcnt vmcnt(2)
	v_lshlrev_b32_e32 v30, 16, v140
	v_and_b32_e32 v31, 0xffff0000, v140
	v_pk_add_f32 v[24:25], v[24:25], v[30:31]
	v_lshlrev_b32_e32 v30, 16, v141
	v_and_b32_e32 v31, 0xffff0000, v141
	v_pk_add_f32 v[26:27], v[26:27], v[30:31]
	v_cvt_pk_bf16_f32 v24, v24, v25
	v_cvt_pk_bf16_f32 v25, v26, v27
	v_lshlrev_b32_e32 v26, 16, v142
	v_and_b32_e32 v27, 0xffff0000, v142
	v_pk_add_f32 v[16:17], v[16:17], v[26:27]
	v_cvt_pk_bf16_f32 v35, v28, v29
	v_cvt_pk_bf16_f32 v26, v16, v17
	v_lshlrev_b32_e32 v16, 16, v143
	v_and_b32_e32 v17, 0xffff0000, v143
	v_pk_add_f32 v[16:17], v[18:19], v[16:17]
	s_waitcnt vmcnt(1)
	v_lshlrev_b32_e32 v18, 16, v137
	v_cvt_pk_bf16_f32 v27, v16, v17
	v_lshlrev_b32_e32 v16, 16, v136
	v_and_b32_e32 v17, 0xffff0000, v136
	v_and_b32_e32 v19, 0xffff0000, v137
	v_pk_add_f32 v[16:17], v[20:21], v[16:17]
	v_pk_add_f32 v[18:19], v[22:23], v[18:19]
	v_cvt_pk_bf16_f32 v16, v16, v17
	v_cvt_pk_bf16_f32 v17, v18, v19
	v_lshlrev_b32_e32 v18, 16, v138
	v_and_b32_e32 v19, 0xffff0000, v138
	v_pk_add_f32 v[12:13], v[12:13], v[18:19]
	v_lshl_add_u64 v[28:29], s[88:89], 0, v[206:207]
	v_cvt_pk_bf16_f32 v18, v12, v13
	v_lshlrev_b32_e32 v12, 16, v139
	v_and_b32_e32 v13, 0xffff0000, v139
	v_pk_add_f32 v[12:13], v[14:15], v[12:13]
	s_waitcnt vmcnt(0)
; __device__ __forceinline__ unsigned cvt_pk_bf16(float lo, float hi) { const f32x2 v = {lo, hi}; const bf16v2_ r = __builtin_convertvector(v, bf16v2_); return __builtin_bit_cast(unsigned, r); }
; __device__ __forceinline__ float bflo(unsigned w) { return __uint_as_float(w << 16); }
; __device__ __forceinline__ float bfhi(unsigned w) { return __uint_as_float(w & 0xffff0000u); }
; __device__ __forceinline__ float wave_sum(float v) { v = row16_sum(v); v += shx(v, 16); v += shx(v, 32); return v; }
;     __device__ __forceinline__ void operator()(const f32x4 (&acc)[2][2][4][2], const Unit& u, int wr, int wc, int, int) const {
;     ...
;         for (int ai = 0; ai < 2; ++ai)
; #pragma unroll
;             for (int m = 0; m < 4; ++m)
; #pragma unroll
;                 for (int bj = 0; bj < 2; ++bj) { const u32x4 c = cin[ai][m][bj]; const f32x4 v0 = acc[ai][bj][m][0], v1 = acc[ai][bj][m][1];
;                     u32x4 w; w.x = cvt_pk_bf16(bflo(c.x) + v0[0], bfhi(c.x) + v0[1]); w.y = cvt_pk_bf16(bflo(c.y) + v0[2], bfhi(c.y) + v0[3]);
;                     w.z = cvt_pk_bf16(bflo(c.z) + v1[0], bfhi(c.z) + v1[1]); w.w = cvt_pk_bf16(bflo(c.w) + v1[2], bfhi(c.w) + v1[3]);
;                     *(u32x4*)(C + (size_t)(row0 + ai * HALF + m * 16) * ldc + col0 + bj * HALF) = w; }
; __device__ __forceinline__ void rowstat_phase(const Frame& F, const bf16_t* __restrict__ res, float* __restrict__ rstd_out) {
;     ...
;         for (int r = 0; r < 4; ++r) { ss[r] = 0.f;
; #pragma unroll
;             for (int i = 0; i < 4; ++i) { const u32x4 x = v[r][i];
;                 ss[r] += bflo(x.x) * bflo(x.x) + bfhi(x.x) * bfhi(x.x) + bflo(x.y) * bflo(x.y) + bfhi(x.y) * bfhi(x.y) + bflo(x.z) * bflo(x.z) + bfhi(x.z) * bfhi(x.z) + bflo(x.w) * bflo(x.w) + bfhi(x.w) * bfhi(x.w); }
;             ss[r] = wave_sum(ss[r]); }
	v_lshlrev_b32_e32 v14, 16, v132
	v_and_b32_e32 v15, 0xffff0000, v132
	v_pk_add_f32 v[8:9], v[8:9], v[14:15]
	v_lshlrev_b32_e32 v14, 16, v133
	v_and_b32_e32 v15, 0xffff0000, v133
	v_pk_add_f32 v[10:11], v[10:11], v[14:15]
	v_cvt_pk_bf16_f32 v8, v8, v9
	v_cvt_pk_bf16_f32 v9, v10, v11
	v_lshlrev_b32_e32 v10, 16, v134
	v_and_b32_e32 v11, 0xffff0000, v134
	v_pk_add_f32 v[4:5], v[4:5], v[10:11]
	v_cvt_pk_bf16_f32 v19, v12, v13
	v_cvt_pk_bf16_f32 v10, v4, v5
	v_lshlrev_b32_e32 v4, 16, v135
	v_and_b32_e32 v5, 0xffff0000, v135
	v_lshl_add_u64 v[12:13], s[88:89], 0, v[204:205]
	v_pk_add_f32 v[4:5], v[6:7], v[4:5]
	v_lshl_add_u64 v[92:93], v[92:93], 0, v[202:203]
	v_lshl_add_u64 v[76:77], v[76:77], 0, v[202:203]
	v_lshl_add_u64 v[60:61], v[60:61], 0, v[202:203]
	v_lshl_add_u64 v[44:45], v[44:45], 0, v[202:203]
	v_lshl_add_u64 v[28:29], v[28:29], 0, v[202:203]
	v_lshl_add_u64 v[12:13], v[12:13], 0, v[202:203]
	v_cvt_pk_bf16_f32 v11, v4, v5
	global_store_dwordx4 v[124:125], v[128:131], off
	global_store_dwordx4 v[124:125], v[120:123], off offset:256
	global_store_dwordx4 v[108:109], v[112:115], off
	global_store_dwordx4 v[108:109], v[104:107], off offset:256
	global_store_dwordx4 v[92:93], v[96:99], off
	global_store_dwordx4 v[92:93], v[88:91], off offset:256
	global_store_dwordx4 v[76:77], v[80:83], off
	global_store_dwordx4 v[76:77], v[72:75], off offset:256
	global_store_dwordx4 v[60:61], v[64:67], off
	global_store_dwordx4 v[60:61], v[56:59], off offset:256
	global_store_dwordx4 v[44:45], v[48:51], off
	global_store_dwordx4 v[44:45], v[40:43], off offset:256
	global_store_dwordx4 v[28:29], v[32:35], off
	global_store_dwordx4 v[28:29], v[24:27], off offset:256
	global_store_dwordx4 v[12:13], v[16:19], off
	global_store_dwordx4 v[12:13], v[8:11], off offset:256
	v_subrev_u32_e32 v216, s88, v124
	v_bfe_u32 v217, v216, 4, 8
	v_lshrrev_b32_e32 v216, 12, v216
	v_and_b32_e32 v218, 15, v217
	v_lshrrev_b32_e32 v217, 5, v217
	v_lshl_or_b32 v217, v217, 4, v218
	v_lshlrev_b32_e32 v217, 10, v217
	v_and_b32_e32 v218, 15, v216
	v_and_b32_e32 v219, 0xc0, v216
	v_lshl_or_b32 v218, v218, 2, v219
	v_lshl_add_u32 v217, v218, 2, v217
	v_lshrrev_b32_e32 v216, 8, v216
	v_lshl_add_u32 v216, v216, 17, v217
	v_add_u32_e32 v216, 0x1e000000, v216
	v_mov_b32_e32 v188, 0
	v_dot2c_f32_bf16_e32 v188, v128, v128
	v_dot2c_f32_bf16_e32 v188, v129, v129
	v_dot2c_f32_bf16_e32 v188, v130, v130
	v_dot2c_f32_bf16_e32 v188, v131, v131
	v_dot2c_f32_bf16_e32 v188, v120, v120
	v_dot2c_f32_bf16_e32 v188, v121, v121
	v_dot2c_f32_bf16_e32 v188, v122, v122
	v_dot2c_f32_bf16_e32 v188, v123, v123
	v_mov_b32_e32 v189, 0
	v_dot2c_f32_bf16_e32 v189, v112, v112
	v_dot2c_f32_bf16_e32 v189, v113, v113
	v_dot2c_f32_bf16_e32 v189, v114, v114
	v_dot2c_f32_bf16_e32 v189, v115, v115
	v_dot2c_f32_bf16_e32 v189, v104, v104
	v_dot2c_f32_bf16_e32 v189, v105, v105
	v_dot2c_f32_bf16_e32 v189, v106, v106
	v_dot2c_f32_bf16_e32 v189, v107, v107
	v_mov_b32_e32 v190, 0
	v_dot2c_f32_bf16_e32 v190, v96, v96
	v_dot2c_f32_bf16_e32 v190, v97, v97
	v_dot2c_f32_bf16_e32 v190, v98, v98
	v_dot2c_f32_bf16_e32 v190, v99, v99
	v_dot2c_f32_bf16_e32 v190, v88, v88
	v_dot2c_f32_bf16_e32 v190, v89, v89
	v_dot2c_f32_bf16_e32 v190, v90, v90
	v_dot2c_f32_bf16_e32 v190, v91, v91
	v_mov_b32_e32 v191, 0
	v_dot2c_f32_bf16_e32 v191, v80, v80
	v_dot2c_f32_bf16_e32 v191, v81, v81
	v_dot2c_f32_bf16_e32 v191, v82, v82
	v_dot2c_f32_bf16_e32 v191, v83, v83
	v_dot2c_f32_bf16_e32 v191, v72, v72
	v_dot2c_f32_bf16_e32 v191, v73, v73
	v_dot2c_f32_bf16_e32 v191, v74, v74
	v_dot2c_f32_bf16_e32 v191, v75, v75
	s_nop 2
	global_store_dwordx4 v216, v[188:191], s[88:89]
	s_nop 1
	v_mov_b32_e32 v188, 0
	v_dot2c_f32_bf16_e32 v188, v64, v64
	v_dot2c_f32_bf16_e32 v188, v65, v65
	v_dot2c_f32_bf16_e32 v188, v66, v66
	v_dot2c_f32_bf16_e32 v188, v67, v67
	v_dot2c_f32_bf16_e32 v188, v56, v56
	v_dot2c_f32_bf16_e32 v188, v57, v57
	v_dot2c_f32_bf16_e32 v188, v58, v58
	v_dot2c_f32_bf16_e32 v188, v59, v59
	v_mov_b32_e32 v189, 0
	v_dot2c_f32_bf16_e32 v189, v48, v48
	v_dot2c_f32_bf16_e32 v189, v49, v49
	v_dot2c_f32_bf16_e32 v189, v50, v50
	v_dot2c_f32_bf16_e32 v189, v51, v51
	v_dot2c_f32_bf16_e32 v189, v40, v40
	v_dot2c_f32_bf16_e32 v189, v41, v41
	v_dot2c_f32_bf16_e32 v189, v42, v42
	v_dot2c_f32_bf16_e32 v189, v43, v43
	v_mov_b32_e32 v190, 0
	v_dot2c_f32_bf16_e32 v190, v32, v32
	v_dot2c_f32_bf16_e32 v190, v33, v33
	v_dot2c_f32_bf16_e32 v190, v34, v34
	v_dot2c_f32_bf16_e32 v190, v35, v35
	v_dot2c_f32_bf16_e32 v190, v24, v24
	v_dot2c_f32_bf16_e32 v190, v25, v25
	v_dot2c_f32_bf16_e32 v190, v26, v26
	v_dot2c_f32_bf16_e32 v190, v27, v27
	v_mov_b32_e32 v191, 0
	v_dot2c_f32_bf16_e32 v191, v16, v16
	v_dot2c_f32_bf16_e32 v191, v17, v17
	v_dot2c_f32_bf16_e32 v191, v18, v18
	v_dot2c_f32_bf16_e32 v191, v19, v19
	v_dot2c_f32_bf16_e32 v191, v8, v8
	v_dot2c_f32_bf16_e32 v191, v9, v9
	v_dot2c_f32_bf16_e32 v191, v10, v10
	v_dot2c_f32_bf16_e32 v191, v11, v11
	s_nop 2
	global_store_dwordx4 v216, v[188:191], s[88:89] offset:512
	s_nop 1
	s_cbranch_vccz .LBB0_1655
	s_waitcnt vmcnt(0)
	s_cmpk_gt_u32 s2, 0xff
	s_cbranch_scc1 .LBB0_1670
	s_barrier
